# write-through (sc0 sc1) on the 16-byte GEMM epilogue stores so the barrier L2 write-back is cheap
# baseline (speedup 1.0000x reference)
.LBB0_431:
	v_lshl_or_b32 v164, s62, 8, v199
	v_mov_b64_e32 v[122:123], s[28:29]
	v_mov_b32_e32 v193, v192
	v_ashrrev_i32_e32 v165, 31, v164
	v_mad_i64_i32 v[122:123], s[2:3], v188, s63, v[122:123]
	v_cvt_pk_bf16_f32 v126, v126, v127
	v_cvt_pk_bf16_f32 v127, v128, v129
	v_cvt_pk_bf16_f32 v128, v194, v195
	v_cvt_pk_bf16_f32 v129, v124, v125
	v_mov_b32_e32 v124, v192
	v_mov_b32_e32 v125, v192
	v_lshl_add_u64 v[122:123], v[164:165], 1, v[122:123]
	v_pk_mul_f32 v[120:121], v[120:121], v[124:125]
	v_pk_mul_f32 v[118:119], v[118:119], v[192:193]
	v_pk_mul_f32 v[116:117], v[116:117], v[124:125]
	s_and_b64 vcc, exec, s[42:43]
	v_pk_mul_f32 v[114:115], v[114:115], v[192:193]
	global_store_dwordx4 v[122:123], v[126:129], off sc0 sc1
	s_cbranch_vccnz .LBB0_510
	v_mul_f32_e32 v118, 0xbfb8aa3b, v118
	v_mul_f32_e32 v114, 0xbfb8aa3b, v114
	v_mul_f32_e32 v119, 0xbfb8aa3b, v119
	v_mul_f32_e32 v115, 0xbfb8aa3b, v115
	v_mul_f32_e32 v120, 0xbfb8aa3b, v120
	v_mul_f32_e32 v116, 0xbfb8aa3b, v116
	v_mul_f32_e32 v121, 0xbfb8aa3b, v121
	v_mul_f32_e32 v117, 0xbfb8aa3b, v117
	v_exp_f32_e32 v118, v118
	v_exp_f32_e32 v114, v114
	v_exp_f32_e32 v119, v119
	v_exp_f32_e32 v115, v115
	v_exp_f32_e32 v120, v120
	v_exp_f32_e32 v116, v116
	v_exp_f32_e32 v121, v121
	v_exp_f32_e32 v117, v117
	v_add_f32_e32 v118, 1.0, v118
	v_add_f32_e32 v114, 1.0, v114
	v_add_f32_e32 v119, 1.0, v119
	v_add_f32_e32 v115, 1.0, v115
	v_add_f32_e32 v120, 1.0, v120
	v_add_f32_e32 v116, 1.0, v116
	v_add_f32_e32 v121, 1.0, v121
	v_add_f32_e32 v117, 1.0, v117
	v_rcp_f32_e32 v118, v118
	v_rcp_f32_e32 v114, v114
	v_rcp_f32_e32 v119, v119
	v_rcp_f32_e32 v115, v115
	v_rcp_f32_e32 v120, v120
	v_rcp_f32_e32 v116, v116
	v_rcp_f32_e32 v121, v121
	v_rcp_f32_e32 v117, v117
	s_and_b64 vcc, exec, s[44:45]
	s_cbranch_vccz .LBB0_511

.LBB0_435:
	v_cvt_pk_bf16_f32 v118, v118, v119
	v_cvt_pk_bf16_f32 v119, v120, v121
	v_cvt_pk_bf16_f32 v120, v114, v115
	s_nop 0
	v_cvt_pk_bf16_f32 v121, v116, v117
	global_store_dwordx4 v[122:123], v[118:121], off offset:256 sc0 sc1
	v_mov_b32_e32 v122, 0
	s_and_b64 vcc, exec, s[40:41]
	v_mov_b32_e32 v123, 0
	v_mov_b32_e32 v124, 0
	v_mov_b32_e32 v125, 0
	v_mov_b32_e32 v126, 0
	v_mov_b32_e32 v127, 0
	v_mov_b32_e32 v128, 0
	v_mov_b32_e32 v129, 0
	v_mov_b32_e32 v114, 0
	v_mov_b32_e32 v115, 0
	v_mov_b32_e32 v116, 0
	v_mov_b32_e32 v117, 0
	v_mov_b32_e32 v118, 0
	v_mov_b32_e32 v119, 0
	v_mov_b32_e32 v120, 0
	v_mov_b32_e32 v121, 0
	s_cbranch_vccnz .LBB0_437
	v_lshlrev_b32_e32 v114, 5, v186
	s_mov_b32 s2, 0x1fbe0
	v_and_or_b32 v114, v114, s2, v198
	v_lshlrev_b32_e32 v118, 2, v114
	global_load_dwordx4 v[122:125], v118, s[84:85]
	global_load_dwordx4 v[126:129], v118, s[84:85] offset:16
	global_load_dwordx4 v[114:117], v118, s[84:85] offset:32
	s_nop 0
	global_load_dwordx4 v[118:121], v118, s[84:85] offset:48

.LBB0_441:
	v_mov_b64_e32 v[106:107], s[28:29]
	v_mov_b32_e32 v131, v130
	v_mad_i64_i32 v[106:107], s[2:3], v186, s63, v[106:107]
	s_waitcnt vmcnt(3)
	v_cvt_pk_bf16_f32 v134, v110, v111
	v_cvt_pk_bf16_f32 v135, v132, v133
	v_cvt_pk_bf16_f32 v136, v108, v109
	v_mov_b32_e32 v108, v130
	v_mov_b32_e32 v109, v130
	v_lshl_add_u64 v[106:107], v[164:165], 1, v[106:107]
	v_pk_mul_f32 v[104:105], v[104:105], v[108:109]
	v_pk_mul_f32 v[102:103], v[102:103], v[130:131]
	v_pk_mul_f32 v[100:101], v[100:101], v[108:109]
	s_and_b64 vcc, exec, s[42:43]
	v_pk_mul_f32 v[98:99], v[98:99], v[130:131]
	v_cvt_pk_bf16_f32 v137, v112, v113
	global_store_dwordx4 v[106:107], v[134:137], off sc0 sc1
	s_cbranch_vccnz .LBB0_514
	v_mul_f32_e32 v102, 0xbfb8aa3b, v102
	v_mul_f32_e32 v98, 0xbfb8aa3b, v98
	v_mul_f32_e32 v103, 0xbfb8aa3b, v103
	v_mul_f32_e32 v99, 0xbfb8aa3b, v99
	v_mul_f32_e32 v104, 0xbfb8aa3b, v104
	v_mul_f32_e32 v100, 0xbfb8aa3b, v100
	v_mul_f32_e32 v105, 0xbfb8aa3b, v105
	v_mul_f32_e32 v101, 0xbfb8aa3b, v101
	v_exp_f32_e32 v102, v102
	v_exp_f32_e32 v98, v98
	v_exp_f32_e32 v103, v103
	v_exp_f32_e32 v99, v99
	v_exp_f32_e32 v104, v104
	v_exp_f32_e32 v100, v100
	v_exp_f32_e32 v105, v105
	v_exp_f32_e32 v101, v101
	v_add_f32_e32 v102, 1.0, v102
	v_add_f32_e32 v98, 1.0, v98
	v_add_f32_e32 v103, 1.0, v103
	v_add_f32_e32 v99, 1.0, v99
	v_add_f32_e32 v104, 1.0, v104
	v_add_f32_e32 v100, 1.0, v100
	v_add_f32_e32 v105, 1.0, v105
	v_add_f32_e32 v101, 1.0, v101
	v_rcp_f32_e32 v102, v102
	v_rcp_f32_e32 v98, v98
	v_rcp_f32_e32 v103, v103
	v_rcp_f32_e32 v99, v99
	v_rcp_f32_e32 v104, v104
	v_rcp_f32_e32 v100, v100
	v_rcp_f32_e32 v105, v105
	v_rcp_f32_e32 v101, v101
	s_and_b64 vcc, exec, s[44:45]
	s_cbranch_vccz .LBB0_515

.LBB0_445:
	v_cvt_pk_bf16_f32 v102, v102, v103
	v_cvt_pk_bf16_f32 v103, v104, v105
	v_cvt_pk_bf16_f32 v104, v98, v99
	s_nop 0
	v_cvt_pk_bf16_f32 v105, v100, v101
	global_store_dwordx4 v[106:107], v[102:105], off offset:256 sc0 sc1
	v_mov_b32_e32 v106, 0
	s_and_b64 vcc, exec, s[40:41]
	v_mov_b32_e32 v107, 0
	v_mov_b32_e32 v108, 0
	v_mov_b32_e32 v109, 0
	v_mov_b32_e32 v110, 0
	v_mov_b32_e32 v111, 0
	v_mov_b32_e32 v112, 0
	v_mov_b32_e32 v113, 0
	v_mov_b32_e32 v98, 0
	v_mov_b32_e32 v99, 0
	v_mov_b32_e32 v100, 0
	v_mov_b32_e32 v101, 0
	v_mov_b32_e32 v102, 0
	v_mov_b32_e32 v103, 0
	v_mov_b32_e32 v104, 0
	v_mov_b32_e32 v105, 0
	s_cbranch_vccnz .LBB0_447
	v_lshlrev_b32_e32 v98, 5, v180
	s_mov_b32 s2, 0x1fde0
	v_and_or_b32 v98, v98, s2, v198
	v_lshlrev_b32_e32 v102, 2, v98
	global_load_dwordx4 v[106:109], v102, s[84:85]
	global_load_dwordx4 v[110:113], v102, s[84:85] offset:16
	global_load_dwordx4 v[98:101], v102, s[84:85] offset:32
	s_nop 0
	global_load_dwordx4 v[102:105], v102, s[84:85] offset:48

.LBB0_451:
	v_mov_b64_e32 v[90:91], s[28:29]
	v_mov_b32_e32 v117, v116
	v_mad_i64_i32 v[90:91], s[2:3], v180, s63, v[90:91]
	v_cvt_pk_bf16_f32 v94, v94, v95
	v_cvt_pk_bf16_f32 v95, v96, v97
	v_cvt_pk_bf16_f32 v96, v92, v93
	v_mov_b32_e32 v92, v116
	v_mov_b32_e32 v93, v116
	v_lshl_add_u64 v[90:91], v[164:165], 1, v[90:91]
	v_pk_mul_f32 v[88:89], v[88:89], v[92:93]
	v_pk_mul_f32 v[86:87], v[86:87], v[116:117]
	v_pk_mul_f32 v[84:85], v[84:85], v[92:93]
	s_and_b64 vcc, exec, s[42:43]
	v_pk_mul_f32 v[82:83], v[82:83], v[116:117]
	v_cvt_pk_bf16_f32 v97, v118, v119
	global_store_dwordx4 v[90:91], v[94:97], off sc0 sc1
	s_cbranch_vccnz .LBB0_518
	v_mul_f32_e32 v86, 0xbfb8aa3b, v86
	v_mul_f32_e32 v82, 0xbfb8aa3b, v82
	v_mul_f32_e32 v87, 0xbfb8aa3b, v87
	v_mul_f32_e32 v83, 0xbfb8aa3b, v83
	v_mul_f32_e32 v88, 0xbfb8aa3b, v88
	v_mul_f32_e32 v84, 0xbfb8aa3b, v84
	v_mul_f32_e32 v89, 0xbfb8aa3b, v89
	v_mul_f32_e32 v85, 0xbfb8aa3b, v85
	v_exp_f32_e32 v86, v86
	v_exp_f32_e32 v82, v82
	v_exp_f32_e32 v87, v87
	v_exp_f32_e32 v83, v83
	v_exp_f32_e32 v88, v88
	v_exp_f32_e32 v84, v84
	v_exp_f32_e32 v89, v89
	v_exp_f32_e32 v85, v85
	v_add_f32_e32 v86, 1.0, v86
	v_add_f32_e32 v82, 1.0, v82
	v_add_f32_e32 v87, 1.0, v87
	v_add_f32_e32 v83, 1.0, v83
	v_add_f32_e32 v88, 1.0, v88
	v_add_f32_e32 v84, 1.0, v84
	v_add_f32_e32 v89, 1.0, v89
	v_add_f32_e32 v85, 1.0, v85
	v_rcp_f32_e32 v86, v86
	v_rcp_f32_e32 v82, v82
	v_rcp_f32_e32 v87, v87
	v_rcp_f32_e32 v83, v83
	v_rcp_f32_e32 v88, v88
	v_rcp_f32_e32 v84, v84
	v_rcp_f32_e32 v89, v89
	v_rcp_f32_e32 v85, v85
	s_and_b64 vcc, exec, s[44:45]
	s_cbranch_vccz .LBB0_519

.LBB0_455:
	v_cvt_pk_bf16_f32 v86, v86, v87
	v_cvt_pk_bf16_f32 v87, v88, v89
	v_cvt_pk_bf16_f32 v88, v82, v83
	s_nop 0
	v_cvt_pk_bf16_f32 v89, v84, v85
	global_store_dwordx4 v[90:91], v[86:89], off offset:256 sc0 sc1
	v_mov_b32_e32 v90, 0
	s_and_b64 vcc, exec, s[40:41]
	v_mov_b32_e32 v91, 0
	v_mov_b32_e32 v92, 0
	v_mov_b32_e32 v93, 0
	v_mov_b32_e32 v94, 0
	v_mov_b32_e32 v95, 0
	v_mov_b32_e32 v96, 0
	v_mov_b32_e32 v97, 0
	v_mov_b32_e32 v82, 0
	v_mov_b32_e32 v83, 0
	v_mov_b32_e32 v84, 0
	v_mov_b32_e32 v85, 0
	v_mov_b32_e32 v86, 0
	v_mov_b32_e32 v87, 0
	v_mov_b32_e32 v88, 0
	v_mov_b32_e32 v89, 0
	s_cbranch_vccnz .LBB0_457
	v_lshlrev_b32_e32 v82, 5, v178
	s_mov_b32 s2, 0x1ffe0
	v_and_or_b32 v82, v82, s2, v198
	v_lshlrev_b32_e32 v86, 2, v82
	global_load_dwordx4 v[90:93], v86, s[84:85]
	global_load_dwordx4 v[94:97], v86, s[84:85] offset:16
	global_load_dwordx4 v[82:85], v86, s[84:85] offset:32
	s_nop 0
	global_load_dwordx4 v[86:89], v86, s[84:85] offset:48

.LBB0_461:
	v_mov_b64_e32 v[74:75], s[28:29]
	v_mov_b32_e32 v99, v98
	v_mad_i64_i32 v[74:75], s[2:3], v178, s63, v[74:75]
	s_waitcnt vmcnt(2)
	v_cvt_pk_bf16_f32 v102, v78, v79
	v_cvt_pk_bf16_f32 v103, v100, v101
	v_cvt_pk_bf16_f32 v104, v76, v77
	v_mov_b32_e32 v76, v98
	v_mov_b32_e32 v77, v98
	v_lshl_add_u64 v[74:75], v[164:165], 1, v[74:75]
	v_pk_mul_f32 v[72:73], v[72:73], v[76:77]
	v_pk_mul_f32 v[70:71], v[70:71], v[98:99]
	v_pk_mul_f32 v[68:69], v[68:69], v[76:77]
	s_and_b64 vcc, exec, s[42:43]
	v_pk_mul_f32 v[66:67], v[66:67], v[98:99]
	v_cvt_pk_bf16_f32 v105, v80, v81
	global_store_dwordx4 v[74:75], v[102:105], off sc0 sc1
	s_cbranch_vccnz .LBB0_522
	v_mul_f32_e32 v70, 0xbfb8aa3b, v70
	v_mul_f32_e32 v66, 0xbfb8aa3b, v66
	v_mul_f32_e32 v71, 0xbfb8aa3b, v71
	v_mul_f32_e32 v67, 0xbfb8aa3b, v67
	v_mul_f32_e32 v72, 0xbfb8aa3b, v72
	v_mul_f32_e32 v68, 0xbfb8aa3b, v68
	v_mul_f32_e32 v73, 0xbfb8aa3b, v73
	v_mul_f32_e32 v69, 0xbfb8aa3b, v69
	v_exp_f32_e32 v70, v70
	v_exp_f32_e32 v66, v66
	v_exp_f32_e32 v71, v71
	v_exp_f32_e32 v67, v67
	v_exp_f32_e32 v72, v72
	v_exp_f32_e32 v68, v68
	v_exp_f32_e32 v73, v73
	v_exp_f32_e32 v69, v69
	v_add_f32_e32 v70, 1.0, v70
	v_add_f32_e32 v66, 1.0, v66
	v_add_f32_e32 v71, 1.0, v71
	v_add_f32_e32 v67, 1.0, v67
	v_add_f32_e32 v72, 1.0, v72
	v_add_f32_e32 v68, 1.0, v68
	v_add_f32_e32 v73, 1.0, v73
	v_add_f32_e32 v69, 1.0, v69
	v_rcp_f32_e32 v70, v70
	v_rcp_f32_e32 v66, v66
	v_rcp_f32_e32 v71, v71
	v_rcp_f32_e32 v67, v67
	v_rcp_f32_e32 v72, v72
	v_rcp_f32_e32 v68, v68
	v_rcp_f32_e32 v73, v73
	v_rcp_f32_e32 v69, v69
	s_and_b64 vcc, exec, s[44:45]
	s_cbranch_vccz .LBB0_523

.LBB0_465:
	v_cvt_pk_bf16_f32 v70, v70, v71
	v_cvt_pk_bf16_f32 v71, v72, v73
	v_cvt_pk_bf16_f32 v72, v66, v67
	s_nop 0
	v_cvt_pk_bf16_f32 v73, v68, v69
	global_store_dwordx4 v[74:75], v[70:73], off offset:256 sc0 sc1
	v_mov_b32_e32 v74, 0
	s_and_b64 vcc, exec, s[40:41]
	v_mov_b32_e32 v75, 0
	v_mov_b32_e32 v76, 0
	v_mov_b32_e32 v77, 0
	v_mov_b32_e32 v78, 0
	v_mov_b32_e32 v79, 0
	v_mov_b32_e32 v80, 0
	v_mov_b32_e32 v81, 0
	v_mov_b32_e32 v66, 0
	v_mov_b32_e32 v67, 0
	v_mov_b32_e32 v68, 0
	v_mov_b32_e32 v69, 0
	v_mov_b32_e32 v70, 0
	v_mov_b32_e32 v71, 0
	v_mov_b32_e32 v72, 0
	v_mov_b32_e32 v73, 0
	s_cbranch_vccnz .LBB0_467
	v_lshlrev_b32_e32 v66, 5, v172
	s_mov_b32 s2, 0x1f9e0
	v_and_or_b32 v66, v66, s2, v198
	v_lshlrev_b32_e32 v70, 2, v66
	global_load_dwordx4 v[74:77], v70, s[84:85]
	global_load_dwordx4 v[78:81], v70, s[84:85] offset:16
	global_load_dwordx4 v[66:69], v70, s[84:85] offset:32
	s_nop 0
	global_load_dwordx4 v[70:73], v70, s[84:85] offset:48

.LBB0_471:
	v_mov_b64_e32 v[58:59], s[28:29]
	v_mov_b32_e32 v85, v84
	v_mad_i64_i32 v[58:59], s[2:3], v172, s63, v[58:59]
	v_cvt_pk_bf16_f32 v62, v62, v63
	v_cvt_pk_bf16_f32 v63, v64, v65
	v_cvt_pk_bf16_f32 v64, v60, v61
	v_mov_b32_e32 v60, v84
	v_mov_b32_e32 v61, v84
	v_lshl_add_u64 v[58:59], v[164:165], 1, v[58:59]
	v_pk_mul_f32 v[56:57], v[56:57], v[60:61]
	v_pk_mul_f32 v[54:55], v[54:55], v[84:85]
	v_pk_mul_f32 v[52:53], v[52:53], v[60:61]
	s_and_b64 vcc, exec, s[42:43]
	v_pk_mul_f32 v[50:51], v[50:51], v[84:85]
	v_cvt_pk_bf16_f32 v65, v86, v87
	global_store_dwordx4 v[58:59], v[62:65], off sc0 sc1
	s_cbranch_vccnz .LBB0_526
	v_mul_f32_e32 v54, 0xbfb8aa3b, v54
	v_mul_f32_e32 v50, 0xbfb8aa3b, v50
	v_mul_f32_e32 v55, 0xbfb8aa3b, v55
	v_mul_f32_e32 v51, 0xbfb8aa3b, v51
	v_mul_f32_e32 v56, 0xbfb8aa3b, v56
	v_mul_f32_e32 v52, 0xbfb8aa3b, v52
	v_mul_f32_e32 v57, 0xbfb8aa3b, v57
	v_mul_f32_e32 v53, 0xbfb8aa3b, v53
	v_exp_f32_e32 v54, v54
	v_exp_f32_e32 v50, v50
	v_exp_f32_e32 v55, v55
	v_exp_f32_e32 v51, v51
	v_exp_f32_e32 v56, v56
	v_exp_f32_e32 v52, v52
	v_exp_f32_e32 v57, v57
	v_exp_f32_e32 v53, v53
	v_add_f32_e32 v54, 1.0, v54
	v_add_f32_e32 v50, 1.0, v50
	v_add_f32_e32 v55, 1.0, v55
	v_add_f32_e32 v51, 1.0, v51
	v_add_f32_e32 v56, 1.0, v56
	v_add_f32_e32 v52, 1.0, v52
	v_add_f32_e32 v57, 1.0, v57
	v_add_f32_e32 v53, 1.0, v53
	v_rcp_f32_e32 v54, v54
	v_rcp_f32_e32 v50, v50
	v_rcp_f32_e32 v55, v55
	v_rcp_f32_e32 v51, v51
	v_rcp_f32_e32 v56, v56
	v_rcp_f32_e32 v52, v52
	v_rcp_f32_e32 v57, v57
	v_rcp_f32_e32 v53, v53
	s_and_b64 vcc, exec, s[44:45]
	s_cbranch_vccz .LBB0_527

.LBB0_475:
	v_cvt_pk_bf16_f32 v54, v54, v55
	v_cvt_pk_bf16_f32 v55, v56, v57
	v_cvt_pk_bf16_f32 v56, v50, v51
	s_nop 0
	v_cvt_pk_bf16_f32 v57, v52, v53
	global_store_dwordx4 v[58:59], v[54:57], off offset:256 sc0 sc1
	v_mov_b32_e32 v58, 0
	s_and_b64 vcc, exec, s[40:41]
	v_mov_b32_e32 v59, 0
	v_mov_b32_e32 v60, 0
	v_mov_b32_e32 v61, 0
	v_mov_b32_e32 v62, 0
	v_mov_b32_e32 v63, 0
	v_mov_b32_e32 v64, 0
	v_mov_b32_e32 v65, 0
	v_mov_b32_e32 v50, 0
	v_mov_b32_e32 v51, 0
	v_mov_b32_e32 v52, 0
	v_mov_b32_e32 v53, 0
	v_mov_b32_e32 v54, 0
	v_mov_b32_e32 v55, 0
	v_mov_b32_e32 v56, 0
	v_mov_b32_e32 v57, 0
	s_cbranch_vccnz .LBB0_477
	v_lshlrev_b32_e32 v50, 5, v166
	s_mov_b32 s2, 0x1fbe0
	v_and_or_b32 v50, v50, s2, v198
	v_lshlrev_b32_e32 v54, 2, v50
	global_load_dwordx4 v[58:61], v54, s[84:85]
	global_load_dwordx4 v[62:65], v54, s[84:85] offset:16
	global_load_dwordx4 v[50:53], v54, s[84:85] offset:32
	s_nop 0
	global_load_dwordx4 v[54:57], v54, s[84:85] offset:48

.LBB0_481:
	v_mov_b64_e32 v[42:43], s[28:29]
	v_mov_b32_e32 v67, v66
	v_mad_i64_i32 v[42:43], s[2:3], v166, s63, v[42:43]
	s_waitcnt vmcnt(2)
	v_cvt_pk_bf16_f32 v70, v46, v47
	v_cvt_pk_bf16_f32 v71, v68, v69
	v_cvt_pk_bf16_f32 v72, v44, v45
	v_mov_b32_e32 v44, v66
	v_mov_b32_e32 v45, v66
	v_lshl_add_u64 v[42:43], v[164:165], 1, v[42:43]
	v_pk_mul_f32 v[40:41], v[40:41], v[44:45]
	v_pk_mul_f32 v[38:39], v[38:39], v[66:67]
	v_pk_mul_f32 v[36:37], v[36:37], v[44:45]
	s_and_b64 vcc, exec, s[42:43]
	v_pk_mul_f32 v[34:35], v[34:35], v[66:67]
	v_cvt_pk_bf16_f32 v73, v48, v49
	global_store_dwordx4 v[42:43], v[70:73], off sc0 sc1
	s_cbranch_vccnz .LBB0_530
	v_mul_f32_e32 v38, 0xbfb8aa3b, v38
	v_mul_f32_e32 v34, 0xbfb8aa3b, v34
	v_mul_f32_e32 v39, 0xbfb8aa3b, v39
	v_mul_f32_e32 v35, 0xbfb8aa3b, v35
	v_mul_f32_e32 v40, 0xbfb8aa3b, v40
	v_mul_f32_e32 v36, 0xbfb8aa3b, v36
	v_mul_f32_e32 v41, 0xbfb8aa3b, v41
	v_mul_f32_e32 v37, 0xbfb8aa3b, v37
	v_exp_f32_e32 v38, v38
	v_exp_f32_e32 v34, v34
	v_exp_f32_e32 v39, v39
	v_exp_f32_e32 v35, v35
	v_exp_f32_e32 v40, v40
	v_exp_f32_e32 v36, v36
	v_exp_f32_e32 v41, v41
	v_exp_f32_e32 v37, v37
	v_add_f32_e32 v38, 1.0, v38
	v_add_f32_e32 v34, 1.0, v34
	v_add_f32_e32 v39, 1.0, v39
	v_add_f32_e32 v35, 1.0, v35
	v_add_f32_e32 v40, 1.0, v40
	v_add_f32_e32 v36, 1.0, v36
	v_add_f32_e32 v41, 1.0, v41
	v_add_f32_e32 v37, 1.0, v37
	v_rcp_f32_e32 v38, v38
	v_rcp_f32_e32 v34, v34
	v_rcp_f32_e32 v39, v39
	v_rcp_f32_e32 v35, v35
	v_rcp_f32_e32 v40, v40
	v_rcp_f32_e32 v36, v36
	v_rcp_f32_e32 v41, v41
	v_rcp_f32_e32 v37, v37
	s_and_b64 vcc, exec, s[44:45]
	s_cbranch_vccz .LBB0_531

.LBB0_485:
	v_cvt_pk_bf16_f32 v38, v38, v39
	v_cvt_pk_bf16_f32 v39, v40, v41
	v_cvt_pk_bf16_f32 v40, v34, v35
	s_nop 0
	v_cvt_pk_bf16_f32 v41, v36, v37
	global_store_dwordx4 v[42:43], v[38:41], off offset:256 sc0 sc1
	v_mov_b32_e32 v42, 0
	s_and_b64 vcc, exec, s[40:41]
	v_mov_b32_e32 v43, 0
	v_mov_b32_e32 v44, 0
	v_mov_b32_e32 v45, 0
	v_mov_b32_e32 v46, 0
	v_mov_b32_e32 v47, 0
	v_mov_b32_e32 v48, 0
	v_mov_b32_e32 v49, 0
	v_mov_b32_e32 v34, 0
	v_mov_b32_e32 v35, 0
	v_mov_b32_e32 v36, 0
	v_mov_b32_e32 v37, 0
	v_mov_b32_e32 v38, 0
	v_mov_b32_e32 v39, 0
	v_mov_b32_e32 v40, 0
	v_mov_b32_e32 v41, 0
	s_cbranch_vccnz .LBB0_487
	v_lshlrev_b32_e32 v34, 5, v162
	s_mov_b32 s2, 0x1fde0
	v_and_or_b32 v34, v34, s2, v198
	v_lshlrev_b32_e32 v38, 2, v34
	global_load_dwordx4 v[42:45], v38, s[84:85]
	global_load_dwordx4 v[46:49], v38, s[84:85] offset:16
	global_load_dwordx4 v[34:37], v38, s[84:85] offset:32
	s_nop 0
	global_load_dwordx4 v[38:41], v38, s[84:85] offset:48

.LBB0_491:
	v_mov_b64_e32 v[26:27], s[28:29]
	v_mov_b32_e32 v53, v52
	v_mad_i64_i32 v[26:27], s[2:3], v162, s63, v[26:27]
	v_cvt_pk_bf16_f32 v30, v30, v31
	v_cvt_pk_bf16_f32 v31, v32, v33
	v_cvt_pk_bf16_f32 v32, v28, v29
	v_mov_b32_e32 v28, v52
	v_mov_b32_e32 v29, v52
	v_lshl_add_u64 v[26:27], v[164:165], 1, v[26:27]
	v_pk_mul_f32 v[24:25], v[24:25], v[28:29]
	v_pk_mul_f32 v[22:23], v[22:23], v[52:53]
	v_pk_mul_f32 v[20:21], v[20:21], v[28:29]
	s_and_b64 vcc, exec, s[42:43]
	v_pk_mul_f32 v[18:19], v[18:19], v[52:53]
	v_cvt_pk_bf16_f32 v33, v54, v55
	global_store_dwordx4 v[26:27], v[30:33], off sc0 sc1
	s_cbranch_vccnz .LBB0_534
	v_mul_f32_e32 v22, 0xbfb8aa3b, v22
	v_mul_f32_e32 v18, 0xbfb8aa3b, v18
	v_mul_f32_e32 v23, 0xbfb8aa3b, v23
	v_mul_f32_e32 v19, 0xbfb8aa3b, v19
	v_mul_f32_e32 v24, 0xbfb8aa3b, v24
	v_mul_f32_e32 v20, 0xbfb8aa3b, v20
	v_mul_f32_e32 v25, 0xbfb8aa3b, v25
	v_mul_f32_e32 v21, 0xbfb8aa3b, v21
	v_exp_f32_e32 v22, v22
	v_exp_f32_e32 v18, v18
	v_exp_f32_e32 v23, v23
	v_exp_f32_e32 v19, v19
	v_exp_f32_e32 v24, v24
	v_exp_f32_e32 v20, v20
	v_exp_f32_e32 v25, v25
	v_exp_f32_e32 v21, v21
	v_add_f32_e32 v22, 1.0, v22
	v_add_f32_e32 v18, 1.0, v18
	v_add_f32_e32 v23, 1.0, v23
	v_add_f32_e32 v19, 1.0, v19
	v_add_f32_e32 v24, 1.0, v24
	v_add_f32_e32 v20, 1.0, v20
	v_add_f32_e32 v25, 1.0, v25
	v_add_f32_e32 v21, 1.0, v21
	v_rcp_f32_e32 v22, v22
	v_rcp_f32_e32 v18, v18
	v_rcp_f32_e32 v23, v23
	v_rcp_f32_e32 v19, v19
	v_rcp_f32_e32 v24, v24
	v_rcp_f32_e32 v20, v20
	v_rcp_f32_e32 v25, v25
	v_rcp_f32_e32 v21, v21
	s_and_b64 vcc, exec, s[44:45]
	s_cbranch_vccz .LBB0_535

.LBB0_495:
	v_cvt_pk_bf16_f32 v22, v22, v23
	v_cvt_pk_bf16_f32 v23, v24, v25
	v_cvt_pk_bf16_f32 v24, v18, v19
	s_nop 0
	v_cvt_pk_bf16_f32 v25, v20, v21
	global_store_dwordx4 v[26:27], v[22:25], off offset:256 sc0 sc1
	v_mov_b32_e32 v26, 0
	s_and_b64 vcc, exec, s[40:41]
	v_mov_b32_e32 v27, 0
	v_mov_b32_e32 v28, 0
	v_mov_b32_e32 v29, 0
	v_mov_b32_e32 v30, 0
	v_mov_b32_e32 v31, 0
	v_mov_b32_e32 v32, 0
	v_mov_b32_e32 v33, 0
	v_mov_b32_e32 v18, 0
	v_mov_b32_e32 v19, 0
	v_mov_b32_e32 v20, 0
	v_mov_b32_e32 v21, 0
	v_mov_b32_e32 v22, 0
	v_mov_b32_e32 v23, 0
	v_mov_b32_e32 v24, 0
	v_mov_b32_e32 v25, 0
	s_cbranch_vccnz .LBB0_497
	v_lshlrev_b32_e32 v18, 5, v160
	s_mov_b32 s2, 0x1ffe0
	v_and_or_b32 v18, v18, s2, v198
	v_lshlrev_b32_e32 v22, 2, v18
	global_load_dwordx4 v[26:29], v22, s[84:85]
	global_load_dwordx4 v[30:33], v22, s[84:85] offset:16
	global_load_dwordx4 v[18:21], v22, s[84:85] offset:32
	s_nop 0
	global_load_dwordx4 v[22:25], v22, s[84:85] offset:48

.LBB0_501:
	v_mov_b64_e32 v[10:11], s[28:29]
	v_mov_b32_e32 v35, v34
	v_mad_i64_i32 v[10:11], s[2:3], v160, s63, v[10:11]
	s_waitcnt vmcnt(2)
	v_cvt_pk_bf16_f32 v38, v14, v15
	v_cvt_pk_bf16_f32 v39, v36, v37
	v_cvt_pk_bf16_f32 v40, v12, v13
	v_mov_b32_e32 v12, v34
	v_mov_b32_e32 v13, v34
	v_lshl_add_u64 v[10:11], v[164:165], 1, v[10:11]
	v_pk_mul_f32 v[8:9], v[8:9], v[12:13]
	v_pk_mul_f32 v[6:7], v[6:7], v[34:35]
	v_pk_mul_f32 v[4:5], v[4:5], v[12:13]
	s_and_b64 vcc, exec, s[42:43]
	v_pk_mul_f32 v[2:3], v[2:3], v[34:35]
	v_cvt_pk_bf16_f32 v41, v16, v17
	global_store_dwordx4 v[10:11], v[38:41], off sc0 sc1
	s_cbranch_vccnz .LBB0_538
	v_mul_f32_e32 v6, 0xbfb8aa3b, v6
	v_mul_f32_e32 v2, 0xbfb8aa3b, v2
	v_mul_f32_e32 v7, 0xbfb8aa3b, v7
	v_mul_f32_e32 v3, 0xbfb8aa3b, v3
	v_mul_f32_e32 v8, 0xbfb8aa3b, v8
	v_mul_f32_e32 v4, 0xbfb8aa3b, v4
	v_mul_f32_e32 v9, 0xbfb8aa3b, v9
	v_mul_f32_e32 v5, 0xbfb8aa3b, v5
	v_exp_f32_e32 v6, v6
	v_exp_f32_e32 v2, v2
	v_exp_f32_e32 v7, v7
	v_exp_f32_e32 v3, v3
	v_exp_f32_e32 v8, v8
	v_exp_f32_e32 v4, v4
	v_exp_f32_e32 v9, v9
	v_exp_f32_e32 v5, v5
	v_add_f32_e32 v6, 1.0, v6
	v_add_f32_e32 v2, 1.0, v2
	v_add_f32_e32 v7, 1.0, v7
	v_add_f32_e32 v3, 1.0, v3
	v_add_f32_e32 v8, 1.0, v8
	v_add_f32_e32 v4, 1.0, v4
	v_add_f32_e32 v9, 1.0, v9
	v_add_f32_e32 v5, 1.0, v5
	v_rcp_f32_e32 v6, v6
	v_rcp_f32_e32 v2, v2
	v_rcp_f32_e32 v7, v7
	v_rcp_f32_e32 v3, v3
	v_rcp_f32_e32 v8, v8
	v_rcp_f32_e32 v4, v4
	v_rcp_f32_e32 v9, v9
	v_rcp_f32_e32 v5, v5
	s_and_b64 vcc, exec, s[44:45]
	s_cbranch_vccz .LBB0_539

.LBB0_505:
	s_andn2_b64 vcc, exec, s[38:39]
	s_mov_b64 s[2:3], -1
	v_cvt_pk_bf16_f32 v6, v6, v7
	v_cvt_pk_bf16_f32 v7, v8, v9
	v_cvt_pk_bf16_f32 v8, v2, v3
	v_cvt_pk_bf16_f32 v9, v4, v5
	global_store_dwordx4 v[10:11], v[6:9], off offset:256 sc0 sc1
	s_cbranch_vccnz .LBB0_407
	s_andn2_b64 vcc, exec, s[4:5]
	s_cbranch_vccnz .LBB0_406
	s_barrier
	s_branch .LBB0_406

.LBB0_559:
	v_lshl_add_u32 v124, s52, 8, v162
	v_ashrrev_i32_e32 v125, 31, v124
	v_or_b32_e32 v122, s9, v165
	v_lshlrev_b64 v[126:127], 14, v[124:125]
	v_ashrrev_i32_e32 v123, 31, v122
	v_lshl_add_u64 v[126:127], s[34:35], 0, v[126:127]
	v_cvt_pk_bf16_f32 v158, v158, v159
	v_cvt_pk_bf16_f32 v159, v128, v129
	v_cndmask_b32_e64 v128, 0, 1, s[2:3]
	v_lshl_add_u64 v[126:127], v[122:123], 1, v[126:127]
	s_waitcnt lgkmcnt(4)
	v_pk_mul_f32 v[120:121], v[120:121], v[146:147]
	v_pk_mul_f32 v[118:119], v[118:119], v[144:145]
	s_waitcnt lgkmcnt(0)
	v_pk_mul_f32 v[116:117], v[116:117], v[142:143]
	v_cmp_ne_u32_e64 s[40:41], 1, v128
	s_andn2_b64 vcc, exec, s[2:3]
	v_pk_mul_f32 v[114:115], v[114:115], v[140:141]
	v_cvt_pk_bf16_f32 v160, v160, v161
	v_cvt_pk_bf16_f32 v161, v156, v157
	global_store_dwordx4 v[126:127], v[158:161], off sc0 sc1
	s_cbranch_vccnz .LBB0_561
	v_mul_f32_e32 v129, 0x3d372713, v114
	v_mul_f32_e32 v129, v114, v129
	v_fma_f32 v129, v114, v129, v114
	v_mul_f32_e32 v129, 0x3f4c422a, v129
	v_add_f32_e32 v129, v129, v129
	v_mul_f32_e32 v129, 0xbfb8aa3b, v129
	v_exp_f32_e32 v129, v129
	v_mul_f32_e32 v128, 0x3d372713, v118
	v_mul_f32_e32 v128, v118, v128
	v_mov_b32_e32 v157, v119
	v_add_f32_e32 v129, 1.0, v129
	v_rcp_f32_e32 v156, v129
	v_mul_f32_e32 v129, 0x3d372713, v119
	v_mul_f32_e32 v129, v119, v129
	v_fma_f32 v128, v118, v128, v118
	v_fmac_f32_e32 v157, v157, v129
	v_mul_f32_e32 v128, 0x3f4c422a, v128
	v_mul_f32_e32 v129, 0x3f4c422a, v157
	v_add_f32_e32 v128, v128, v128
	v_add_f32_e32 v129, v129, v129
	v_mul_f32_e32 v159, 0x3d372713, v116
	v_mul_f32_e32 v128, 0xbfb8aa3b, v128
	v_mul_f32_e32 v129, 0xbfb8aa3b, v129
	v_mul_f32_e32 v159, v116, v159
	v_exp_f32_e32 v128, v128
	v_exp_f32_e32 v129, v129
	v_fma_f32 v159, v116, v159, v116
	v_mul_f32_e32 v159, 0x3f4c422a, v159
	v_add_f32_e32 v159, v159, v159
	v_mul_f32_e32 v159, 0xbfb8aa3b, v159
	v_add_f32_e32 v128, 1.0, v128
	v_add_f32_e32 v129, 1.0, v129
	v_exp_f32_e32 v159, v159
	v_rcp_f32_e32 v128, v128
	v_rcp_f32_e32 v129, v129
	v_mul_f32_e32 v157, 0x3d372713, v115
	v_mul_f32_e32 v157, v115, v157
	v_mov_b32_e32 v158, v115
	v_fmac_f32_e32 v158, v158, v157
	v_add_f32_e32 v159, 1.0, v159
	v_mul_f32_e32 v157, 0x3f4c422a, v158
	v_mul_f32_e32 v158, 0x3d372713, v120
	v_rcp_f32_e32 v160, v159
	v_mul_f32_e32 v159, 0x3d372713, v121
	v_pk_mul_f32 v[118:119], v[118:119], v[128:129]
	v_mul_f32_e32 v128, 0x3d372713, v117
	v_mul_f32_e32 v158, v120, v158
	v_mul_f32_e32 v159, v121, v159
	v_mul_f32_e32 v128, v117, v128
	v_fma_f32 v158, v120, v158, v120
	v_fma_f32 v159, v121, v159, v121
	v_fma_f32 v128, v117, v128, v117
	v_mul_f32_e32 v158, 0x3f4c422a, v158
	v_mul_f32_e32 v159, 0x3f4c422a, v159
	v_mul_f32_e32 v128, 0x3f4c422a, v128
	v_add_f32_e32 v157, v157, v157
	v_add_f32_e32 v158, v158, v158
	v_add_f32_e32 v159, v159, v159
	v_add_f32_e32 v128, v128, v128
	v_mul_f32_e32 v157, 0xbfb8aa3b, v157
	v_mul_f32_e32 v158, 0xbfb8aa3b, v158
	v_mul_f32_e32 v159, 0xbfb8aa3b, v159
	v_mul_f32_e32 v128, 0xbfb8aa3b, v128
	v_exp_f32_e32 v157, v157
	v_exp_f32_e32 v158, v158
	v_exp_f32_e32 v159, v159
	v_exp_f32_e32 v128, v128
	v_add_f32_e32 v157, 1.0, v157
	v_add_f32_e32 v158, 1.0, v158
	v_add_f32_e32 v159, 1.0, v159
	v_add_f32_e32 v128, 1.0, v128
	v_rcp_f32_e32 v157, v157
	v_rcp_f32_e32 v158, v158
	v_rcp_f32_e32 v159, v159
	v_rcp_f32_e32 v161, v128
	v_pk_mul_f32 v[114:115], v[114:115], v[156:157]
	v_pk_mul_f32 v[120:121], v[120:121], v[158:159]
	v_pk_mul_f32 v[116:117], v[116:117], v[160:161]
.LBB0_561:
	v_cvt_pk_bf16_f32 v118, v118, v119
	v_cvt_pk_bf16_f32 v119, v120, v121
	v_cvt_pk_bf16_f32 v120, v114, v115
	v_pk_mul_f32 v[112:113], v[112:113], v[154:155]
	v_pk_mul_f32 v[110:111], v[110:111], v[152:153]
	v_pk_mul_f32 v[108:109], v[108:109], v[150:151]
	s_and_b64 vcc, exec, s[40:41]
	v_pk_mul_f32 v[114:115], v[106:107], v[148:149]
	v_cvt_pk_bf16_f32 v121, v116, v117
	global_store_dwordx4 v[126:127], v[118:121], off offset:256 sc0 sc1
	s_cbranch_vccnz .LBB0_563
	v_mul_f32_e32 v107, 0x3d372713, v114
	v_mul_f32_e32 v107, v114, v107
	v_fma_f32 v107, v114, v107, v114
	v_mul_f32_e32 v107, 0x3f4c422a, v107
	v_add_f32_e32 v107, v107, v107
	v_mul_f32_e32 v107, 0xbfb8aa3b, v107
	v_exp_f32_e32 v107, v107
	v_mul_f32_e32 v106, 0x3d372713, v110
	v_mul_f32_e32 v106, v110, v106
	v_mov_b32_e32 v117, v111
	v_add_f32_e32 v107, 1.0, v107
	v_rcp_f32_e32 v116, v107
	v_mul_f32_e32 v107, 0x3d372713, v111
	v_mul_f32_e32 v107, v111, v107
	v_fma_f32 v106, v110, v106, v110
	v_fmac_f32_e32 v117, v117, v107
	v_mul_f32_e32 v106, 0x3f4c422a, v106
	v_mul_f32_e32 v107, 0x3f4c422a, v117
	v_add_f32_e32 v106, v106, v106
	v_add_f32_e32 v107, v107, v107
	v_mul_f32_e32 v119, 0x3d372713, v108
	v_mul_f32_e32 v106, 0xbfb8aa3b, v106
	v_mul_f32_e32 v107, 0xbfb8aa3b, v107
	v_mul_f32_e32 v119, v108, v119
	v_exp_f32_e32 v106, v106
	v_exp_f32_e32 v107, v107
	v_fma_f32 v119, v108, v119, v108
	v_mul_f32_e32 v119, 0x3f4c422a, v119
	v_add_f32_e32 v119, v119, v119
	v_mul_f32_e32 v119, 0xbfb8aa3b, v119
	v_add_f32_e32 v106, 1.0, v106
	v_add_f32_e32 v107, 1.0, v107
	v_exp_f32_e32 v119, v119
	v_rcp_f32_e32 v106, v106
	v_rcp_f32_e32 v107, v107
	v_mul_f32_e32 v117, 0x3d372713, v115
	v_mul_f32_e32 v117, v115, v117
	v_mov_b32_e32 v118, v115
	v_fmac_f32_e32 v118, v118, v117
	v_add_f32_e32 v119, 1.0, v119
	v_mul_f32_e32 v117, 0x3f4c422a, v118
	v_mul_f32_e32 v118, 0x3d372713, v112
	v_rcp_f32_e32 v120, v119
	v_mul_f32_e32 v119, 0x3d372713, v113
	v_pk_mul_f32 v[110:111], v[110:111], v[106:107]
	v_mul_f32_e32 v106, 0x3d372713, v109
	v_mul_f32_e32 v118, v112, v118
	v_mul_f32_e32 v119, v113, v119
	v_mul_f32_e32 v106, v109, v106
	v_fma_f32 v118, v112, v118, v112
	v_fma_f32 v119, v113, v119, v113
	v_fma_f32 v106, v109, v106, v109
	v_mul_f32_e32 v118, 0x3f4c422a, v118
	v_mul_f32_e32 v119, 0x3f4c422a, v119
	v_mul_f32_e32 v106, 0x3f4c422a, v106
	v_add_f32_e32 v117, v117, v117
	v_add_f32_e32 v118, v118, v118
	v_add_f32_e32 v119, v119, v119
	v_add_f32_e32 v106, v106, v106
	v_mul_f32_e32 v117, 0xbfb8aa3b, v117
	v_mul_f32_e32 v118, 0xbfb8aa3b, v118
	v_mul_f32_e32 v119, 0xbfb8aa3b, v119
	v_mul_f32_e32 v106, 0xbfb8aa3b, v106
	v_exp_f32_e32 v117, v117
	v_exp_f32_e32 v118, v118
	v_exp_f32_e32 v119, v119
	v_exp_f32_e32 v106, v106
	v_add_f32_e32 v117, 1.0, v117
	v_add_f32_e32 v118, 1.0, v118
	v_add_f32_e32 v119, 1.0, v119
	v_add_f32_e32 v106, 1.0, v106
	v_rcp_f32_e32 v117, v117
	v_rcp_f32_e32 v118, v118
	v_rcp_f32_e32 v119, v119
	v_rcp_f32_e32 v121, v106
	v_pk_mul_f32 v[114:115], v[114:115], v[116:117]
	v_pk_mul_f32 v[112:113], v[112:113], v[118:119]
	v_pk_mul_f32 v[108:109], v[108:109], v[120:121]
.LBB0_563:
	v_or_b32_e32 v106, 16, v124
	v_ashrrev_i32_e32 v107, 31, v106
	v_lshlrev_b64 v[106:107], 14, v[106:107]
	v_lshl_add_u64 v[106:107], s[34:35], 0, v[106:107]
	v_lshl_add_u64 v[106:107], v[122:123], 1, v[106:107]
	v_pk_mul_f32 v[104:105], v[104:105], v[146:147]
	v_pk_mul_f32 v[102:103], v[102:103], v[144:145]
	v_pk_mul_f32 v[100:101], v[100:101], v[142:143]
	s_and_b64 vcc, exec, s[40:41]
	v_pk_mul_f32 v[98:99], v[98:99], v[140:141]
	v_cvt_pk_bf16_f32 v110, v110, v111
	v_cvt_pk_bf16_f32 v111, v112, v113
	v_cvt_pk_bf16_f32 v112, v114, v115
	v_cvt_pk_bf16_f32 v113, v108, v109
	global_store_dwordx4 v[106:107], v[110:113], off sc0 sc1
	s_cbranch_vccnz .LBB0_565
	v_mul_f32_e32 v109, 0x3d372713, v98
	v_mul_f32_e32 v109, v98, v109
	v_fma_f32 v109, v98, v109, v98
	v_mul_f32_e32 v109, 0x3f4c422a, v109
	v_add_f32_e32 v109, v109, v109
	v_mul_f32_e32 v109, 0xbfb8aa3b, v109
	v_exp_f32_e32 v109, v109
	v_mul_f32_e32 v108, 0x3d372713, v102
	v_mul_f32_e32 v108, v102, v108
	v_mov_b32_e32 v111, v103
	v_add_f32_e32 v109, 1.0, v109
	v_rcp_f32_e32 v110, v109
	v_mul_f32_e32 v109, 0x3d372713, v103
	v_mul_f32_e32 v109, v103, v109
	v_fma_f32 v108, v102, v108, v102
	v_fmac_f32_e32 v111, v111, v109
	v_mul_f32_e32 v108, 0x3f4c422a, v108
	v_mul_f32_e32 v109, 0x3f4c422a, v111
	v_add_f32_e32 v108, v108, v108
	v_add_f32_e32 v109, v109, v109
	v_mul_f32_e32 v113, 0x3d372713, v100
	v_mul_f32_e32 v108, 0xbfb8aa3b, v108
	v_mul_f32_e32 v109, 0xbfb8aa3b, v109
	v_mul_f32_e32 v113, v100, v113
	v_exp_f32_e32 v108, v108
	v_exp_f32_e32 v109, v109
	v_fma_f32 v113, v100, v113, v100
	v_mul_f32_e32 v113, 0x3f4c422a, v113
	v_add_f32_e32 v113, v113, v113
	v_mul_f32_e32 v113, 0xbfb8aa3b, v113
	v_add_f32_e32 v108, 1.0, v108
	v_add_f32_e32 v109, 1.0, v109
	v_exp_f32_e32 v113, v113
	v_rcp_f32_e32 v108, v108
	v_rcp_f32_e32 v109, v109
	v_mul_f32_e32 v111, 0x3d372713, v99
	v_mul_f32_e32 v111, v99, v111
	v_mov_b32_e32 v112, v99
	v_fmac_f32_e32 v112, v112, v111
	v_add_f32_e32 v113, 1.0, v113
	v_mul_f32_e32 v111, 0x3f4c422a, v112
	v_mul_f32_e32 v112, 0x3d372713, v104
	v_rcp_f32_e32 v114, v113
	v_mul_f32_e32 v113, 0x3d372713, v105
	v_pk_mul_f32 v[102:103], v[102:103], v[108:109]
	v_mul_f32_e32 v108, 0x3d372713, v101
	v_mul_f32_e32 v112, v104, v112
	v_mul_f32_e32 v113, v105, v113
	v_mul_f32_e32 v108, v101, v108
	v_fma_f32 v112, v104, v112, v104
	v_fma_f32 v113, v105, v113, v105
	v_fma_f32 v108, v101, v108, v101
	v_mul_f32_e32 v112, 0x3f4c422a, v112
	v_mul_f32_e32 v113, 0x3f4c422a, v113
	v_mul_f32_e32 v108, 0x3f4c422a, v108
	v_add_f32_e32 v111, v111, v111
	v_add_f32_e32 v112, v112, v112
	v_add_f32_e32 v113, v113, v113
	v_add_f32_e32 v108, v108, v108
	v_mul_f32_e32 v111, 0xbfb8aa3b, v111
	v_mul_f32_e32 v112, 0xbfb8aa3b, v112
	v_mul_f32_e32 v113, 0xbfb8aa3b, v113
	v_mul_f32_e32 v108, 0xbfb8aa3b, v108
	v_exp_f32_e32 v111, v111
	v_exp_f32_e32 v112, v112
	v_exp_f32_e32 v113, v113
	v_exp_f32_e32 v108, v108
	v_add_f32_e32 v111, 1.0, v111
	v_add_f32_e32 v112, 1.0, v112
	v_add_f32_e32 v113, 1.0, v113
	v_add_f32_e32 v108, 1.0, v108
	v_rcp_f32_e32 v111, v111
	v_rcp_f32_e32 v112, v112
	v_rcp_f32_e32 v113, v113
	v_rcp_f32_e32 v115, v108
	v_pk_mul_f32 v[98:99], v[98:99], v[110:111]
	v_pk_mul_f32 v[104:105], v[104:105], v[112:113]
	v_pk_mul_f32 v[100:101], v[100:101], v[114:115]
.LBB0_565:
	v_cvt_pk_bf16_f32 v102, v102, v103
	v_cvt_pk_bf16_f32 v103, v104, v105
	v_cvt_pk_bf16_f32 v104, v98, v99
	v_pk_mul_f32 v[96:97], v[96:97], v[154:155]
	v_pk_mul_f32 v[94:95], v[94:95], v[152:153]
	v_pk_mul_f32 v[92:93], v[92:93], v[150:151]
	s_and_b64 vcc, exec, s[40:41]
	v_pk_mul_f32 v[98:99], v[90:91], v[148:149]
	v_cvt_pk_bf16_f32 v105, v100, v101
	global_store_dwordx4 v[106:107], v[102:105], off offset:256 sc0 sc1
	s_cbranch_vccnz .LBB0_567
	v_mul_f32_e32 v91, 0x3d372713, v98
	v_mul_f32_e32 v91, v98, v91
	v_fma_f32 v91, v98, v91, v98
	v_mul_f32_e32 v91, 0x3f4c422a, v91
	v_add_f32_e32 v91, v91, v91
	v_mul_f32_e32 v91, 0xbfb8aa3b, v91
	v_exp_f32_e32 v91, v91
	v_mul_f32_e32 v90, 0x3d372713, v94
	v_mul_f32_e32 v90, v94, v90
	v_mov_b32_e32 v101, v95
	v_add_f32_e32 v91, 1.0, v91
	v_rcp_f32_e32 v100, v91
	v_mul_f32_e32 v91, 0x3d372713, v95
	v_mul_f32_e32 v91, v95, v91
	v_fma_f32 v90, v94, v90, v94
	v_fmac_f32_e32 v101, v101, v91
	v_mul_f32_e32 v90, 0x3f4c422a, v90
	v_mul_f32_e32 v91, 0x3f4c422a, v101
	v_add_f32_e32 v90, v90, v90
	v_add_f32_e32 v91, v91, v91
	v_mul_f32_e32 v103, 0x3d372713, v92
	v_mul_f32_e32 v90, 0xbfb8aa3b, v90
	v_mul_f32_e32 v91, 0xbfb8aa3b, v91
	v_mul_f32_e32 v103, v92, v103
	v_exp_f32_e32 v90, v90
	v_exp_f32_e32 v91, v91
	v_fma_f32 v103, v92, v103, v92
	v_mul_f32_e32 v103, 0x3f4c422a, v103
	v_add_f32_e32 v103, v103, v103
	v_mul_f32_e32 v103, 0xbfb8aa3b, v103
	v_add_f32_e32 v90, 1.0, v90
	v_add_f32_e32 v91, 1.0, v91
	v_exp_f32_e32 v103, v103
	v_rcp_f32_e32 v90, v90
	v_rcp_f32_e32 v91, v91
	v_mul_f32_e32 v101, 0x3d372713, v99
	v_mul_f32_e32 v101, v99, v101
	v_mov_b32_e32 v102, v99
	v_fmac_f32_e32 v102, v102, v101
	v_add_f32_e32 v103, 1.0, v103
	v_mul_f32_e32 v101, 0x3f4c422a, v102
	v_mul_f32_e32 v102, 0x3d372713, v96
	v_rcp_f32_e32 v104, v103
	v_mul_f32_e32 v103, 0x3d372713, v97
	v_pk_mul_f32 v[94:95], v[94:95], v[90:91]
	v_mul_f32_e32 v90, 0x3d372713, v93
	v_mul_f32_e32 v102, v96, v102
	v_mul_f32_e32 v103, v97, v103
	v_mul_f32_e32 v90, v93, v90
	v_fma_f32 v102, v96, v102, v96
	v_fma_f32 v103, v97, v103, v97
	v_fma_f32 v90, v93, v90, v93
	v_mul_f32_e32 v102, 0x3f4c422a, v102
	v_mul_f32_e32 v103, 0x3f4c422a, v103
	v_mul_f32_e32 v90, 0x3f4c422a, v90
	v_add_f32_e32 v101, v101, v101
	v_add_f32_e32 v102, v102, v102
	v_add_f32_e32 v103, v103, v103
	v_add_f32_e32 v90, v90, v90
	v_mul_f32_e32 v101, 0xbfb8aa3b, v101
	v_mul_f32_e32 v102, 0xbfb8aa3b, v102
	v_mul_f32_e32 v103, 0xbfb8aa3b, v103
	v_mul_f32_e32 v90, 0xbfb8aa3b, v90
	v_exp_f32_e32 v101, v101
	v_exp_f32_e32 v102, v102
	v_exp_f32_e32 v103, v103
	v_exp_f32_e32 v90, v90
	v_add_f32_e32 v101, 1.0, v101
	v_add_f32_e32 v102, 1.0, v102
	v_add_f32_e32 v103, 1.0, v103
	v_add_f32_e32 v90, 1.0, v90
	v_rcp_f32_e32 v101, v101
	v_rcp_f32_e32 v102, v102
	v_rcp_f32_e32 v103, v103
	v_rcp_f32_e32 v105, v90
	v_pk_mul_f32 v[98:99], v[98:99], v[100:101]
	v_pk_mul_f32 v[96:97], v[96:97], v[102:103]
	v_pk_mul_f32 v[92:93], v[92:93], v[104:105]
.LBB0_567:
	v_or_b32_e32 v90, 32, v124
	v_ashrrev_i32_e32 v91, 31, v90
	v_lshlrev_b64 v[90:91], 14, v[90:91]
	v_lshl_add_u64 v[90:91], s[34:35], 0, v[90:91]
	v_lshl_add_u64 v[90:91], v[122:123], 1, v[90:91]
	v_pk_mul_f32 v[88:89], v[88:89], v[146:147]
	v_pk_mul_f32 v[86:87], v[86:87], v[144:145]
	v_pk_mul_f32 v[84:85], v[84:85], v[142:143]
	s_and_b64 vcc, exec, s[40:41]
	v_pk_mul_f32 v[82:83], v[82:83], v[140:141]
	v_cvt_pk_bf16_f32 v94, v94, v95
	v_cvt_pk_bf16_f32 v95, v96, v97
	v_cvt_pk_bf16_f32 v96, v98, v99
	v_cvt_pk_bf16_f32 v97, v92, v93
	global_store_dwordx4 v[90:91], v[94:97], off sc0 sc1
	s_cbranch_vccnz .LBB0_569
	v_mul_f32_e32 v93, 0x3d372713, v82
	v_mul_f32_e32 v93, v82, v93
	v_fma_f32 v93, v82, v93, v82
	v_mul_f32_e32 v93, 0x3f4c422a, v93
	v_add_f32_e32 v93, v93, v93
	v_mul_f32_e32 v93, 0xbfb8aa3b, v93
	v_exp_f32_e32 v93, v93
	v_mul_f32_e32 v92, 0x3d372713, v86
	v_mul_f32_e32 v92, v86, v92
	v_mov_b32_e32 v95, v87
	v_add_f32_e32 v93, 1.0, v93
	v_rcp_f32_e32 v94, v93
	v_mul_f32_e32 v93, 0x3d372713, v87
	v_mul_f32_e32 v93, v87, v93
	v_fma_f32 v92, v86, v92, v86
	v_fmac_f32_e32 v95, v95, v93
	v_mul_f32_e32 v92, 0x3f4c422a, v92
	v_mul_f32_e32 v93, 0x3f4c422a, v95
	v_add_f32_e32 v92, v92, v92
	v_add_f32_e32 v93, v93, v93
	v_mul_f32_e32 v97, 0x3d372713, v84
	v_mul_f32_e32 v92, 0xbfb8aa3b, v92
	v_mul_f32_e32 v93, 0xbfb8aa3b, v93
	v_mul_f32_e32 v97, v84, v97
	v_exp_f32_e32 v92, v92
	v_exp_f32_e32 v93, v93
	v_fma_f32 v97, v84, v97, v84
	v_mul_f32_e32 v97, 0x3f4c422a, v97
	v_add_f32_e32 v97, v97, v97
	v_mul_f32_e32 v97, 0xbfb8aa3b, v97
	v_add_f32_e32 v92, 1.0, v92
	v_add_f32_e32 v93, 1.0, v93
	v_exp_f32_e32 v97, v97
	v_rcp_f32_e32 v92, v92
	v_rcp_f32_e32 v93, v93
	v_mul_f32_e32 v95, 0x3d372713, v83
	v_mul_f32_e32 v95, v83, v95
	v_mov_b32_e32 v96, v83
	v_fmac_f32_e32 v96, v96, v95
	v_add_f32_e32 v97, 1.0, v97
	v_mul_f32_e32 v95, 0x3f4c422a, v96
	v_mul_f32_e32 v96, 0x3d372713, v88
	v_rcp_f32_e32 v98, v97
	v_mul_f32_e32 v97, 0x3d372713, v89
	v_pk_mul_f32 v[86:87], v[86:87], v[92:93]
	v_mul_f32_e32 v92, 0x3d372713, v85
	v_mul_f32_e32 v96, v88, v96
	v_mul_f32_e32 v97, v89, v97
	v_mul_f32_e32 v92, v85, v92
	v_fma_f32 v96, v88, v96, v88
	v_fma_f32 v97, v89, v97, v89
	v_fma_f32 v92, v85, v92, v85
	v_mul_f32_e32 v96, 0x3f4c422a, v96
	v_mul_f32_e32 v97, 0x3f4c422a, v97
	v_mul_f32_e32 v92, 0x3f4c422a, v92
	v_add_f32_e32 v95, v95, v95
	v_add_f32_e32 v96, v96, v96
	v_add_f32_e32 v97, v97, v97
	v_add_f32_e32 v92, v92, v92
	v_mul_f32_e32 v95, 0xbfb8aa3b, v95
	v_mul_f32_e32 v96, 0xbfb8aa3b, v96
	v_mul_f32_e32 v97, 0xbfb8aa3b, v97
	v_mul_f32_e32 v92, 0xbfb8aa3b, v92
	v_exp_f32_e32 v95, v95
	v_exp_f32_e32 v96, v96
	v_exp_f32_e32 v97, v97
	v_exp_f32_e32 v92, v92
	v_add_f32_e32 v95, 1.0, v95
	v_add_f32_e32 v96, 1.0, v96
	v_add_f32_e32 v97, 1.0, v97
	v_add_f32_e32 v92, 1.0, v92
	v_rcp_f32_e32 v95, v95
	v_rcp_f32_e32 v96, v96
	v_rcp_f32_e32 v97, v97
	v_rcp_f32_e32 v99, v92
	v_pk_mul_f32 v[82:83], v[82:83], v[94:95]
	v_pk_mul_f32 v[88:89], v[88:89], v[96:97]
	v_pk_mul_f32 v[84:85], v[84:85], v[98:99]
.LBB0_569:
	v_cvt_pk_bf16_f32 v86, v86, v87
	v_cvt_pk_bf16_f32 v87, v88, v89
	v_cvt_pk_bf16_f32 v88, v82, v83
	v_pk_mul_f32 v[80:81], v[80:81], v[154:155]
	v_pk_mul_f32 v[78:79], v[78:79], v[152:153]
	v_pk_mul_f32 v[76:77], v[76:77], v[150:151]
	s_and_b64 vcc, exec, s[40:41]
	v_pk_mul_f32 v[82:83], v[74:75], v[148:149]
	v_cvt_pk_bf16_f32 v89, v84, v85
	global_store_dwordx4 v[90:91], v[86:89], off offset:256 sc0 sc1
	s_cbranch_vccnz .LBB0_571
	v_mul_f32_e32 v75, 0x3d372713, v82
	v_mul_f32_e32 v75, v82, v75
	v_fma_f32 v75, v82, v75, v82
	v_mul_f32_e32 v75, 0x3f4c422a, v75
	v_add_f32_e32 v75, v75, v75
	v_mul_f32_e32 v75, 0xbfb8aa3b, v75
	v_exp_f32_e32 v75, v75
	v_mul_f32_e32 v74, 0x3d372713, v78
	v_mul_f32_e32 v74, v78, v74
	v_mov_b32_e32 v85, v79
	v_add_f32_e32 v75, 1.0, v75
	v_rcp_f32_e32 v84, v75
	v_mul_f32_e32 v75, 0x3d372713, v79
	v_mul_f32_e32 v75, v79, v75
	v_fma_f32 v74, v78, v74, v78
	v_fmac_f32_e32 v85, v85, v75
	v_mul_f32_e32 v74, 0x3f4c422a, v74
	v_mul_f32_e32 v75, 0x3f4c422a, v85
	v_add_f32_e32 v74, v74, v74
	v_add_f32_e32 v75, v75, v75
	v_mul_f32_e32 v87, 0x3d372713, v76
	v_mul_f32_e32 v74, 0xbfb8aa3b, v74
	v_mul_f32_e32 v75, 0xbfb8aa3b, v75
	v_mul_f32_e32 v87, v76, v87
	v_exp_f32_e32 v74, v74
	v_exp_f32_e32 v75, v75
	v_fma_f32 v87, v76, v87, v76
	v_mul_f32_e32 v87, 0x3f4c422a, v87
	v_add_f32_e32 v87, v87, v87
	v_mul_f32_e32 v87, 0xbfb8aa3b, v87
	v_add_f32_e32 v74, 1.0, v74
	v_add_f32_e32 v75, 1.0, v75
	v_exp_f32_e32 v87, v87
	v_rcp_f32_e32 v74, v74
	v_rcp_f32_e32 v75, v75
	v_mul_f32_e32 v85, 0x3d372713, v83
	v_mul_f32_e32 v85, v83, v85
	v_mov_b32_e32 v86, v83
	v_fmac_f32_e32 v86, v86, v85
	v_add_f32_e32 v87, 1.0, v87
	v_mul_f32_e32 v85, 0x3f4c422a, v86
	v_mul_f32_e32 v86, 0x3d372713, v80
	v_rcp_f32_e32 v88, v87
	v_mul_f32_e32 v87, 0x3d372713, v81
	v_pk_mul_f32 v[78:79], v[78:79], v[74:75]
	v_mul_f32_e32 v74, 0x3d372713, v77
	v_mul_f32_e32 v86, v80, v86
	v_mul_f32_e32 v87, v81, v87
	v_mul_f32_e32 v74, v77, v74
	v_fma_f32 v86, v80, v86, v80
	v_fma_f32 v87, v81, v87, v81
	v_fma_f32 v74, v77, v74, v77
	v_mul_f32_e32 v86, 0x3f4c422a, v86
	v_mul_f32_e32 v87, 0x3f4c422a, v87
	v_mul_f32_e32 v74, 0x3f4c422a, v74
	v_add_f32_e32 v85, v85, v85
	v_add_f32_e32 v86, v86, v86
	v_add_f32_e32 v87, v87, v87
	v_add_f32_e32 v74, v74, v74
	v_mul_f32_e32 v85, 0xbfb8aa3b, v85
	v_mul_f32_e32 v86, 0xbfb8aa3b, v86
	v_mul_f32_e32 v87, 0xbfb8aa3b, v87
	v_mul_f32_e32 v74, 0xbfb8aa3b, v74
	v_exp_f32_e32 v85, v85
	v_exp_f32_e32 v86, v86
	v_exp_f32_e32 v87, v87
	v_exp_f32_e32 v74, v74
	v_add_f32_e32 v85, 1.0, v85
	v_add_f32_e32 v86, 1.0, v86
	v_add_f32_e32 v87, 1.0, v87
	v_add_f32_e32 v74, 1.0, v74
	v_rcp_f32_e32 v85, v85
	v_rcp_f32_e32 v86, v86
	v_rcp_f32_e32 v87, v87
	v_rcp_f32_e32 v89, v74
	v_pk_mul_f32 v[82:83], v[82:83], v[84:85]
	v_pk_mul_f32 v[80:81], v[80:81], v[86:87]
	v_pk_mul_f32 v[76:77], v[76:77], v[88:89]
.LBB0_571:
	v_or_b32_e32 v74, 48, v124
	v_ashrrev_i32_e32 v75, 31, v74
	v_lshlrev_b64 v[74:75], 14, v[74:75]
	v_lshl_add_u64 v[74:75], s[34:35], 0, v[74:75]
	v_lshl_add_u64 v[74:75], v[122:123], 1, v[74:75]
	v_pk_mul_f32 v[72:73], v[72:73], v[146:147]
	v_pk_mul_f32 v[70:71], v[70:71], v[144:145]
	v_pk_mul_f32 v[68:69], v[68:69], v[142:143]
	s_and_b64 vcc, exec, s[40:41]
	v_pk_mul_f32 v[66:67], v[66:67], v[140:141]
	v_cvt_pk_bf16_f32 v78, v78, v79
	v_cvt_pk_bf16_f32 v79, v80, v81
	v_cvt_pk_bf16_f32 v80, v82, v83
	v_cvt_pk_bf16_f32 v81, v76, v77
	global_store_dwordx4 v[74:75], v[78:81], off sc0 sc1
	s_cbranch_vccnz .LBB0_573
	v_mul_f32_e32 v77, 0x3d372713, v66
	v_mul_f32_e32 v77, v66, v77
	v_fma_f32 v77, v66, v77, v66
	v_mul_f32_e32 v77, 0x3f4c422a, v77
	v_add_f32_e32 v77, v77, v77
	v_mul_f32_e32 v77, 0xbfb8aa3b, v77
	v_exp_f32_e32 v77, v77
	v_mul_f32_e32 v76, 0x3d372713, v70
	v_mul_f32_e32 v76, v70, v76
	v_mov_b32_e32 v79, v71
	v_add_f32_e32 v77, 1.0, v77
	v_rcp_f32_e32 v78, v77
	v_mul_f32_e32 v77, 0x3d372713, v71
	v_mul_f32_e32 v77, v71, v77
	v_fma_f32 v76, v70, v76, v70
	v_fmac_f32_e32 v79, v79, v77
	v_mul_f32_e32 v76, 0x3f4c422a, v76
	v_mul_f32_e32 v77, 0x3f4c422a, v79
	v_add_f32_e32 v76, v76, v76
	v_add_f32_e32 v77, v77, v77
	v_mul_f32_e32 v81, 0x3d372713, v68
	v_mul_f32_e32 v76, 0xbfb8aa3b, v76
	v_mul_f32_e32 v77, 0xbfb8aa3b, v77
	v_mul_f32_e32 v81, v68, v81
	v_exp_f32_e32 v76, v76
	v_exp_f32_e32 v77, v77
	v_fma_f32 v81, v68, v81, v68
	v_mul_f32_e32 v81, 0x3f4c422a, v81
	v_add_f32_e32 v81, v81, v81
	v_mul_f32_e32 v81, 0xbfb8aa3b, v81
	v_add_f32_e32 v76, 1.0, v76
	v_add_f32_e32 v77, 1.0, v77
	v_exp_f32_e32 v81, v81
	v_rcp_f32_e32 v76, v76
	v_rcp_f32_e32 v77, v77
	v_mul_f32_e32 v79, 0x3d372713, v67
	v_mul_f32_e32 v79, v67, v79
	v_mov_b32_e32 v80, v67
	v_fmac_f32_e32 v80, v80, v79
	v_add_f32_e32 v81, 1.0, v81
	v_mul_f32_e32 v79, 0x3f4c422a, v80
	v_mul_f32_e32 v80, 0x3d372713, v72
	v_rcp_f32_e32 v82, v81
	v_mul_f32_e32 v81, 0x3d372713, v73
	v_pk_mul_f32 v[70:71], v[70:71], v[76:77]
	v_mul_f32_e32 v76, 0x3d372713, v69
	v_mul_f32_e32 v80, v72, v80
	v_mul_f32_e32 v81, v73, v81
	v_mul_f32_e32 v76, v69, v76
	v_fma_f32 v80, v72, v80, v72
	v_fma_f32 v81, v73, v81, v73
	v_fma_f32 v76, v69, v76, v69
	v_mul_f32_e32 v80, 0x3f4c422a, v80
	v_mul_f32_e32 v81, 0x3f4c422a, v81
	v_mul_f32_e32 v76, 0x3f4c422a, v76
	v_add_f32_e32 v79, v79, v79
	v_add_f32_e32 v80, v80, v80
	v_add_f32_e32 v81, v81, v81
	v_add_f32_e32 v76, v76, v76
	v_mul_f32_e32 v79, 0xbfb8aa3b, v79
	v_mul_f32_e32 v80, 0xbfb8aa3b, v80
	v_mul_f32_e32 v81, 0xbfb8aa3b, v81
	v_mul_f32_e32 v76, 0xbfb8aa3b, v76
	v_exp_f32_e32 v79, v79
	v_exp_f32_e32 v80, v80
	v_exp_f32_e32 v81, v81
	v_exp_f32_e32 v76, v76
	v_add_f32_e32 v79, 1.0, v79
	v_add_f32_e32 v80, 1.0, v80
	v_add_f32_e32 v81, 1.0, v81
	v_add_f32_e32 v76, 1.0, v76
	v_rcp_f32_e32 v79, v79
	v_rcp_f32_e32 v80, v80
	v_rcp_f32_e32 v81, v81
	v_rcp_f32_e32 v83, v76
	v_pk_mul_f32 v[66:67], v[66:67], v[78:79]
	v_pk_mul_f32 v[72:73], v[72:73], v[80:81]
	v_pk_mul_f32 v[68:69], v[68:69], v[82:83]
.LBB0_573:
	v_cvt_pk_bf16_f32 v70, v70, v71
	v_cvt_pk_bf16_f32 v71, v72, v73
	v_cvt_pk_bf16_f32 v72, v66, v67
	v_pk_mul_f32 v[64:65], v[64:65], v[154:155]
	v_pk_mul_f32 v[62:63], v[62:63], v[152:153]
	v_pk_mul_f32 v[60:61], v[60:61], v[150:151]
	s_and_b64 vcc, exec, s[40:41]
	v_pk_mul_f32 v[66:67], v[58:59], v[148:149]
	v_cvt_pk_bf16_f32 v73, v68, v69
	global_store_dwordx4 v[74:75], v[70:73], off offset:256 sc0 sc1
	s_cbranch_vccnz .LBB0_575
	v_mul_f32_e32 v59, 0x3d372713, v66
	v_mul_f32_e32 v59, v66, v59
	v_fma_f32 v59, v66, v59, v66
	v_mul_f32_e32 v59, 0x3f4c422a, v59
	v_add_f32_e32 v59, v59, v59
	v_mul_f32_e32 v59, 0xbfb8aa3b, v59
	v_exp_f32_e32 v59, v59
	v_mul_f32_e32 v58, 0x3d372713, v62
	v_mul_f32_e32 v58, v62, v58
	v_mov_b32_e32 v69, v63
	v_add_f32_e32 v59, 1.0, v59
	v_rcp_f32_e32 v68, v59
	v_mul_f32_e32 v59, 0x3d372713, v63
	v_mul_f32_e32 v59, v63, v59
	v_fma_f32 v58, v62, v58, v62
	v_fmac_f32_e32 v69, v69, v59
	v_mul_f32_e32 v58, 0x3f4c422a, v58
	v_mul_f32_e32 v59, 0x3f4c422a, v69
	v_add_f32_e32 v58, v58, v58
	v_add_f32_e32 v59, v59, v59
	v_mul_f32_e32 v71, 0x3d372713, v60
	v_mul_f32_e32 v58, 0xbfb8aa3b, v58
	v_mul_f32_e32 v59, 0xbfb8aa3b, v59
	v_mul_f32_e32 v71, v60, v71
	v_exp_f32_e32 v58, v58
	v_exp_f32_e32 v59, v59
	v_fma_f32 v71, v60, v71, v60
	v_mul_f32_e32 v71, 0x3f4c422a, v71
	v_add_f32_e32 v71, v71, v71
	v_mul_f32_e32 v71, 0xbfb8aa3b, v71
	v_add_f32_e32 v58, 1.0, v58
	v_add_f32_e32 v59, 1.0, v59
	v_exp_f32_e32 v71, v71
	v_rcp_f32_e32 v58, v58
	v_rcp_f32_e32 v59, v59
	v_mul_f32_e32 v69, 0x3d372713, v67
	v_mul_f32_e32 v69, v67, v69
	v_mov_b32_e32 v70, v67
	v_fmac_f32_e32 v70, v70, v69
	v_add_f32_e32 v71, 1.0, v71
	v_mul_f32_e32 v69, 0x3f4c422a, v70
	v_mul_f32_e32 v70, 0x3d372713, v64
	v_rcp_f32_e32 v72, v71
	v_mul_f32_e32 v71, 0x3d372713, v65
	v_pk_mul_f32 v[62:63], v[62:63], v[58:59]
	v_mul_f32_e32 v58, 0x3d372713, v61
	v_mul_f32_e32 v70, v64, v70
	v_mul_f32_e32 v71, v65, v71
	v_mul_f32_e32 v58, v61, v58
	v_fma_f32 v70, v64, v70, v64
	v_fma_f32 v71, v65, v71, v65
	v_fma_f32 v58, v61, v58, v61
	v_mul_f32_e32 v70, 0x3f4c422a, v70
	v_mul_f32_e32 v71, 0x3f4c422a, v71
	v_mul_f32_e32 v58, 0x3f4c422a, v58
	v_add_f32_e32 v69, v69, v69
	v_add_f32_e32 v70, v70, v70
	v_add_f32_e32 v71, v71, v71
	v_add_f32_e32 v58, v58, v58
	v_mul_f32_e32 v69, 0xbfb8aa3b, v69
	v_mul_f32_e32 v70, 0xbfb8aa3b, v70
	v_mul_f32_e32 v71, 0xbfb8aa3b, v71
	v_mul_f32_e32 v58, 0xbfb8aa3b, v58
	v_exp_f32_e32 v69, v69
	v_exp_f32_e32 v70, v70
	v_exp_f32_e32 v71, v71
	v_exp_f32_e32 v58, v58
	v_add_f32_e32 v69, 1.0, v69
	v_add_f32_e32 v70, 1.0, v70
	v_add_f32_e32 v71, 1.0, v71
	v_add_f32_e32 v58, 1.0, v58
	v_rcp_f32_e32 v69, v69
	v_rcp_f32_e32 v70, v70
	v_rcp_f32_e32 v71, v71
	v_rcp_f32_e32 v73, v58
	v_pk_mul_f32 v[66:67], v[66:67], v[68:69]
	v_pk_mul_f32 v[64:65], v[64:65], v[70:71]
	v_pk_mul_f32 v[60:61], v[60:61], v[72:73]
.LBB0_575:
	v_lshlrev_b64 v[58:59], 14, v[124:125]
	v_lshl_add_u64 v[58:59], s[34:35], 0, v[58:59]
	v_lshl_add_u64 v[58:59], v[122:123], 1, v[58:59]
	s_mov_b32 s2, 0x200000
	v_cvt_pk_bf16_f32 v62, v62, v63
	v_cvt_pk_bf16_f32 v63, v64, v65
	v_cvt_pk_bf16_f32 v64, v66, v67
	v_cvt_pk_bf16_f32 v65, v60, v61
	v_add_co_u32_e32 v60, vcc, s2, v58
	v_pk_mul_f32 v[56:57], v[56:57], v[146:147]
	s_nop 0
	v_addc_co_u32_e32 v61, vcc, 0, v59, vcc
	v_pk_mul_f32 v[54:55], v[54:55], v[144:145]
	v_pk_mul_f32 v[52:53], v[52:53], v[142:143]
	s_and_b64 vcc, exec, s[40:41]
	v_pk_mul_f32 v[50:51], v[50:51], v[140:141]
	global_store_dwordx4 v[60:61], v[62:65], off sc0 sc1
	s_cbranch_vccnz .LBB0_577
	v_mul_f32_e32 v61, 0x3d372713, v50
	v_mul_f32_e32 v61, v50, v61
	v_fma_f32 v61, v50, v61, v50
	v_mul_f32_e32 v61, 0x3f4c422a, v61
	v_add_f32_e32 v61, v61, v61
	v_mul_f32_e32 v61, 0xbfb8aa3b, v61
	v_exp_f32_e32 v61, v61
	v_mul_f32_e32 v60, 0x3d372713, v54
	v_mul_f32_e32 v60, v54, v60
	v_mov_b32_e32 v63, v55
	v_add_f32_e32 v61, 1.0, v61
	v_rcp_f32_e32 v62, v61
	v_mul_f32_e32 v61, 0x3d372713, v55
	v_mul_f32_e32 v61, v55, v61
	v_fma_f32 v60, v54, v60, v54
	v_fmac_f32_e32 v63, v63, v61
	v_mul_f32_e32 v60, 0x3f4c422a, v60
	v_mul_f32_e32 v61, 0x3f4c422a, v63
	v_add_f32_e32 v60, v60, v60
	v_add_f32_e32 v61, v61, v61
	v_mul_f32_e32 v65, 0x3d372713, v52
	v_mul_f32_e32 v60, 0xbfb8aa3b, v60
	v_mul_f32_e32 v61, 0xbfb8aa3b, v61
	v_mul_f32_e32 v65, v52, v65
	v_exp_f32_e32 v60, v60
	v_exp_f32_e32 v61, v61
	v_fma_f32 v65, v52, v65, v52
	v_mul_f32_e32 v65, 0x3f4c422a, v65
	v_add_f32_e32 v65, v65, v65
	v_mul_f32_e32 v65, 0xbfb8aa3b, v65
	v_add_f32_e32 v60, 1.0, v60
	v_add_f32_e32 v61, 1.0, v61
	v_exp_f32_e32 v65, v65
	v_rcp_f32_e32 v60, v60
	v_rcp_f32_e32 v61, v61
	v_mul_f32_e32 v63, 0x3d372713, v51
	v_mul_f32_e32 v63, v51, v63
	v_mov_b32_e32 v64, v51
	v_fmac_f32_e32 v64, v64, v63
	v_add_f32_e32 v65, 1.0, v65
	v_mul_f32_e32 v63, 0x3f4c422a, v64
	v_mul_f32_e32 v64, 0x3d372713, v56
	v_rcp_f32_e32 v66, v65
	v_mul_f32_e32 v65, 0x3d372713, v57
	v_pk_mul_f32 v[54:55], v[54:55], v[60:61]
	v_mul_f32_e32 v60, 0x3d372713, v53
	v_mul_f32_e32 v64, v56, v64
	v_mul_f32_e32 v65, v57, v65
	v_mul_f32_e32 v60, v53, v60
	v_fma_f32 v64, v56, v64, v56
	v_fma_f32 v65, v57, v65, v57
	v_fma_f32 v60, v53, v60, v53
	v_mul_f32_e32 v64, 0x3f4c422a, v64
	v_mul_f32_e32 v65, 0x3f4c422a, v65
	v_mul_f32_e32 v60, 0x3f4c422a, v60
	v_add_f32_e32 v63, v63, v63
	v_add_f32_e32 v64, v64, v64
	v_add_f32_e32 v65, v65, v65
	v_add_f32_e32 v60, v60, v60
	v_mul_f32_e32 v63, 0xbfb8aa3b, v63
	v_mul_f32_e32 v64, 0xbfb8aa3b, v64
	v_mul_f32_e32 v65, 0xbfb8aa3b, v65
	v_mul_f32_e32 v60, 0xbfb8aa3b, v60
	v_exp_f32_e32 v63, v63
	v_exp_f32_e32 v64, v64
	v_exp_f32_e32 v65, v65
	v_exp_f32_e32 v60, v60
	v_add_f32_e32 v63, 1.0, v63
	v_add_f32_e32 v64, 1.0, v64
	v_add_f32_e32 v65, 1.0, v65
	v_add_f32_e32 v60, 1.0, v60
	v_rcp_f32_e32 v63, v63
	v_rcp_f32_e32 v64, v64
	v_rcp_f32_e32 v65, v65
	v_rcp_f32_e32 v67, v60
	v_pk_mul_f32 v[50:51], v[50:51], v[62:63]
	v_pk_mul_f32 v[56:57], v[56:57], v[64:65]
	v_pk_mul_f32 v[52:53], v[52:53], v[66:67]
.LBB0_577:
	s_mov_b64 s[2:3], 0x200000
	v_lshl_add_u64 v[58:59], v[58:59], 0, s[2:3]
	v_cvt_pk_bf16_f32 v54, v54, v55
	v_cvt_pk_bf16_f32 v55, v56, v57
	v_cvt_pk_bf16_f32 v56, v50, v51
	v_pk_mul_f32 v[48:49], v[48:49], v[154:155]
	v_pk_mul_f32 v[46:47], v[46:47], v[152:153]
	v_pk_mul_f32 v[44:45], v[44:45], v[150:151]
	s_and_b64 vcc, exec, s[40:41]
	v_pk_mul_f32 v[50:51], v[42:43], v[148:149]
	v_cvt_pk_bf16_f32 v57, v52, v53
	global_store_dwordx4 v[58:59], v[54:57], off offset:256 sc0 sc1
	s_cbranch_vccnz .LBB0_579
	v_mul_f32_e32 v43, 0x3d372713, v50
	v_mul_f32_e32 v43, v50, v43
	v_fma_f32 v43, v50, v43, v50
	v_mul_f32_e32 v43, 0x3f4c422a, v43
	v_add_f32_e32 v43, v43, v43
	v_mul_f32_e32 v43, 0xbfb8aa3b, v43
	v_exp_f32_e32 v43, v43
	v_mul_f32_e32 v42, 0x3d372713, v46
	v_mul_f32_e32 v42, v46, v42
	v_mov_b32_e32 v53, v47
	v_add_f32_e32 v43, 1.0, v43
	v_rcp_f32_e32 v52, v43
	v_mul_f32_e32 v43, 0x3d372713, v47
	v_mul_f32_e32 v43, v47, v43
	v_fma_f32 v42, v46, v42, v46
	v_fmac_f32_e32 v53, v53, v43
	v_mul_f32_e32 v42, 0x3f4c422a, v42
	v_mul_f32_e32 v43, 0x3f4c422a, v53
	v_add_f32_e32 v42, v42, v42
	v_add_f32_e32 v43, v43, v43
	v_mul_f32_e32 v55, 0x3d372713, v44
	v_mul_f32_e32 v42, 0xbfb8aa3b, v42
	v_mul_f32_e32 v43, 0xbfb8aa3b, v43
	v_mul_f32_e32 v55, v44, v55
	v_exp_f32_e32 v42, v42
	v_exp_f32_e32 v43, v43
	v_fma_f32 v55, v44, v55, v44
	v_mul_f32_e32 v55, 0x3f4c422a, v55
	v_add_f32_e32 v55, v55, v55
	v_mul_f32_e32 v55, 0xbfb8aa3b, v55
	v_add_f32_e32 v42, 1.0, v42
	v_add_f32_e32 v43, 1.0, v43
	v_exp_f32_e32 v55, v55
	v_rcp_f32_e32 v42, v42
	v_rcp_f32_e32 v43, v43
	v_mul_f32_e32 v53, 0x3d372713, v51
	v_mul_f32_e32 v53, v51, v53
	v_mov_b32_e32 v54, v51
	v_fmac_f32_e32 v54, v54, v53
	v_add_f32_e32 v55, 1.0, v55
	v_mul_f32_e32 v53, 0x3f4c422a, v54
	v_mul_f32_e32 v54, 0x3d372713, v48
	v_rcp_f32_e32 v56, v55
	v_mul_f32_e32 v55, 0x3d372713, v49
	v_pk_mul_f32 v[46:47], v[46:47], v[42:43]
	v_mul_f32_e32 v42, 0x3d372713, v45
	v_mul_f32_e32 v54, v48, v54
	v_mul_f32_e32 v55, v49, v55
	v_mul_f32_e32 v42, v45, v42
	v_fma_f32 v54, v48, v54, v48
	v_fma_f32 v55, v49, v55, v49
	v_fma_f32 v42, v45, v42, v45
	v_mul_f32_e32 v54, 0x3f4c422a, v54
	v_mul_f32_e32 v55, 0x3f4c422a, v55
	v_mul_f32_e32 v42, 0x3f4c422a, v42
	v_add_f32_e32 v53, v53, v53
	v_add_f32_e32 v54, v54, v54
	v_add_f32_e32 v55, v55, v55
	v_add_f32_e32 v42, v42, v42
	v_mul_f32_e32 v53, 0xbfb8aa3b, v53
	v_mul_f32_e32 v54, 0xbfb8aa3b, v54
	v_mul_f32_e32 v55, 0xbfb8aa3b, v55
	v_mul_f32_e32 v42, 0xbfb8aa3b, v42
	v_exp_f32_e32 v53, v53
	v_exp_f32_e32 v54, v54
	v_exp_f32_e32 v55, v55
	v_exp_f32_e32 v42, v42
	v_add_f32_e32 v53, 1.0, v53
	v_add_f32_e32 v54, 1.0, v54
	v_add_f32_e32 v55, 1.0, v55
	v_add_f32_e32 v42, 1.0, v42
	v_rcp_f32_e32 v53, v53
	v_rcp_f32_e32 v54, v54
	v_rcp_f32_e32 v55, v55
	v_rcp_f32_e32 v57, v42
	v_pk_mul_f32 v[50:51], v[50:51], v[52:53]
	v_pk_mul_f32 v[48:49], v[48:49], v[54:55]
	v_pk_mul_f32 v[44:45], v[44:45], v[56:57]
.LBB0_579:
	v_lshlrev_b64 v[42:43], 14, v[124:125]
	v_lshl_add_u64 v[42:43], s[34:35], 0, v[42:43]
	v_lshl_add_u64 v[42:43], v[122:123], 1, v[42:43]
	s_mov_b32 s2, 0x240000
	v_cvt_pk_bf16_f32 v46, v46, v47
	v_cvt_pk_bf16_f32 v47, v48, v49
	v_cvt_pk_bf16_f32 v48, v50, v51
	v_cvt_pk_bf16_f32 v49, v44, v45
	v_add_co_u32_e32 v44, vcc, s2, v42
	v_pk_mul_f32 v[40:41], v[40:41], v[146:147]
	s_nop 0
	v_addc_co_u32_e32 v45, vcc, 0, v43, vcc
	v_pk_mul_f32 v[38:39], v[38:39], v[144:145]
	v_pk_mul_f32 v[36:37], v[36:37], v[142:143]
	s_and_b64 vcc, exec, s[40:41]
	v_pk_mul_f32 v[34:35], v[34:35], v[140:141]
	global_store_dwordx4 v[44:45], v[46:49], off sc0 sc1
	s_cbranch_vccnz .LBB0_581
	v_mul_f32_e32 v45, 0x3d372713, v34
	v_mul_f32_e32 v45, v34, v45
	v_fma_f32 v45, v34, v45, v34
	v_mul_f32_e32 v45, 0x3f4c422a, v45
	v_add_f32_e32 v45, v45, v45
	v_mul_f32_e32 v45, 0xbfb8aa3b, v45
	v_exp_f32_e32 v45, v45
	v_mul_f32_e32 v44, 0x3d372713, v38
	v_mul_f32_e32 v44, v38, v44
	v_mov_b32_e32 v47, v39
	v_add_f32_e32 v45, 1.0, v45
	v_rcp_f32_e32 v46, v45
	v_mul_f32_e32 v45, 0x3d372713, v39
	v_mul_f32_e32 v45, v39, v45
	v_fma_f32 v44, v38, v44, v38
	v_fmac_f32_e32 v47, v47, v45
	v_mul_f32_e32 v44, 0x3f4c422a, v44
	v_mul_f32_e32 v45, 0x3f4c422a, v47
	v_add_f32_e32 v44, v44, v44
	v_add_f32_e32 v45, v45, v45
	v_mul_f32_e32 v49, 0x3d372713, v36
	v_mul_f32_e32 v44, 0xbfb8aa3b, v44
	v_mul_f32_e32 v45, 0xbfb8aa3b, v45
	v_mul_f32_e32 v49, v36, v49
	v_exp_f32_e32 v44, v44
	v_exp_f32_e32 v45, v45
	v_fma_f32 v49, v36, v49, v36
	v_mul_f32_e32 v49, 0x3f4c422a, v49
	v_add_f32_e32 v49, v49, v49
	v_mul_f32_e32 v49, 0xbfb8aa3b, v49
	v_add_f32_e32 v44, 1.0, v44
	v_add_f32_e32 v45, 1.0, v45
	v_exp_f32_e32 v49, v49
	v_rcp_f32_e32 v44, v44
	v_rcp_f32_e32 v45, v45
	v_mul_f32_e32 v47, 0x3d372713, v35
	v_mul_f32_e32 v47, v35, v47
	v_mov_b32_e32 v48, v35
	v_fmac_f32_e32 v48, v48, v47
	v_add_f32_e32 v49, 1.0, v49
	v_mul_f32_e32 v47, 0x3f4c422a, v48
	v_mul_f32_e32 v48, 0x3d372713, v40
	v_rcp_f32_e32 v50, v49
	v_mul_f32_e32 v49, 0x3d372713, v41
	v_pk_mul_f32 v[38:39], v[38:39], v[44:45]
	v_mul_f32_e32 v44, 0x3d372713, v37
	v_mul_f32_e32 v48, v40, v48
	v_mul_f32_e32 v49, v41, v49
	v_mul_f32_e32 v44, v37, v44
	v_fma_f32 v48, v40, v48, v40
	v_fma_f32 v49, v41, v49, v41
	v_fma_f32 v44, v37, v44, v37
	v_mul_f32_e32 v48, 0x3f4c422a, v48
	v_mul_f32_e32 v49, 0x3f4c422a, v49
	v_mul_f32_e32 v44, 0x3f4c422a, v44
	v_add_f32_e32 v47, v47, v47
	v_add_f32_e32 v48, v48, v48
	v_add_f32_e32 v49, v49, v49
	v_add_f32_e32 v44, v44, v44
	v_mul_f32_e32 v47, 0xbfb8aa3b, v47
	v_mul_f32_e32 v48, 0xbfb8aa3b, v48
	v_mul_f32_e32 v49, 0xbfb8aa3b, v49
	v_mul_f32_e32 v44, 0xbfb8aa3b, v44
	v_exp_f32_e32 v47, v47
	v_exp_f32_e32 v48, v48
	v_exp_f32_e32 v49, v49
	v_exp_f32_e32 v44, v44
	v_add_f32_e32 v47, 1.0, v47
	v_add_f32_e32 v48, 1.0, v48
	v_add_f32_e32 v49, 1.0, v49
	v_add_f32_e32 v44, 1.0, v44
	v_rcp_f32_e32 v47, v47
	v_rcp_f32_e32 v48, v48
	v_rcp_f32_e32 v49, v49
	v_rcp_f32_e32 v51, v44
	v_pk_mul_f32 v[34:35], v[34:35], v[46:47]
	v_pk_mul_f32 v[40:41], v[40:41], v[48:49]
	v_pk_mul_f32 v[36:37], v[36:37], v[50:51]
.LBB0_581:
	s_mov_b64 s[2:3], 0x240000
	v_lshl_add_u64 v[42:43], v[42:43], 0, s[2:3]
	v_cvt_pk_bf16_f32 v38, v38, v39
	v_cvt_pk_bf16_f32 v39, v40, v41
	v_cvt_pk_bf16_f32 v40, v34, v35
	v_pk_mul_f32 v[32:33], v[32:33], v[154:155]
	v_pk_mul_f32 v[30:31], v[30:31], v[152:153]
	v_pk_mul_f32 v[28:29], v[28:29], v[150:151]
	s_and_b64 vcc, exec, s[40:41]
	v_pk_mul_f32 v[34:35], v[26:27], v[148:149]
	v_cvt_pk_bf16_f32 v41, v36, v37
	global_store_dwordx4 v[42:43], v[38:41], off offset:256 sc0 sc1
	s_cbranch_vccnz .LBB0_583
	v_mul_f32_e32 v27, 0x3d372713, v34
	v_mul_f32_e32 v27, v34, v27
	v_fma_f32 v27, v34, v27, v34
	v_mul_f32_e32 v27, 0x3f4c422a, v27
	v_add_f32_e32 v27, v27, v27
	v_mul_f32_e32 v27, 0xbfb8aa3b, v27
	v_exp_f32_e32 v27, v27
	v_mul_f32_e32 v26, 0x3d372713, v30
	v_mul_f32_e32 v26, v30, v26
	v_mov_b32_e32 v37, v31
	v_add_f32_e32 v27, 1.0, v27
	v_rcp_f32_e32 v36, v27
	v_mul_f32_e32 v27, 0x3d372713, v31
	v_mul_f32_e32 v27, v31, v27
	v_fma_f32 v26, v30, v26, v30
	v_fmac_f32_e32 v37, v37, v27
	v_mul_f32_e32 v26, 0x3f4c422a, v26
	v_mul_f32_e32 v27, 0x3f4c422a, v37
	v_add_f32_e32 v26, v26, v26
	v_add_f32_e32 v27, v27, v27
	v_mul_f32_e32 v39, 0x3d372713, v28
	v_mul_f32_e32 v26, 0xbfb8aa3b, v26
	v_mul_f32_e32 v27, 0xbfb8aa3b, v27
	v_mul_f32_e32 v39, v28, v39
	v_exp_f32_e32 v26, v26
	v_exp_f32_e32 v27, v27
	v_fma_f32 v39, v28, v39, v28
	v_mul_f32_e32 v39, 0x3f4c422a, v39
	v_add_f32_e32 v39, v39, v39
	v_mul_f32_e32 v39, 0xbfb8aa3b, v39
	v_add_f32_e32 v26, 1.0, v26
	v_add_f32_e32 v27, 1.0, v27
	v_exp_f32_e32 v39, v39
	v_rcp_f32_e32 v26, v26
	v_rcp_f32_e32 v27, v27
	v_mul_f32_e32 v37, 0x3d372713, v35
	v_mul_f32_e32 v37, v35, v37
	v_mov_b32_e32 v38, v35
	v_fmac_f32_e32 v38, v38, v37
	v_add_f32_e32 v39, 1.0, v39
	v_mul_f32_e32 v37, 0x3f4c422a, v38
	v_mul_f32_e32 v38, 0x3d372713, v32
	v_rcp_f32_e32 v40, v39
	v_mul_f32_e32 v39, 0x3d372713, v33
	v_pk_mul_f32 v[30:31], v[30:31], v[26:27]
	v_mul_f32_e32 v26, 0x3d372713, v29
	v_mul_f32_e32 v38, v32, v38
	v_mul_f32_e32 v39, v33, v39
	v_mul_f32_e32 v26, v29, v26
	v_fma_f32 v38, v32, v38, v32
	v_fma_f32 v39, v33, v39, v33
	v_fma_f32 v26, v29, v26, v29
	v_mul_f32_e32 v38, 0x3f4c422a, v38
	v_mul_f32_e32 v39, 0x3f4c422a, v39
	v_mul_f32_e32 v26, 0x3f4c422a, v26
	v_add_f32_e32 v37, v37, v37
	v_add_f32_e32 v38, v38, v38
	v_add_f32_e32 v39, v39, v39
	v_add_f32_e32 v26, v26, v26
	v_mul_f32_e32 v37, 0xbfb8aa3b, v37
	v_mul_f32_e32 v38, 0xbfb8aa3b, v38
	v_mul_f32_e32 v39, 0xbfb8aa3b, v39
	v_mul_f32_e32 v26, 0xbfb8aa3b, v26
	v_exp_f32_e32 v37, v37
	v_exp_f32_e32 v38, v38
	v_exp_f32_e32 v39, v39
	v_exp_f32_e32 v26, v26
	v_add_f32_e32 v37, 1.0, v37
	v_add_f32_e32 v38, 1.0, v38
	v_add_f32_e32 v39, 1.0, v39
	v_add_f32_e32 v26, 1.0, v26
	v_rcp_f32_e32 v37, v37
	v_rcp_f32_e32 v38, v38
	v_rcp_f32_e32 v39, v39
	v_rcp_f32_e32 v41, v26
	v_pk_mul_f32 v[34:35], v[34:35], v[36:37]
	v_pk_mul_f32 v[32:33], v[32:33], v[38:39]
	v_pk_mul_f32 v[28:29], v[28:29], v[40:41]
.LBB0_583:
	v_lshlrev_b64 v[26:27], 14, v[124:125]
	v_lshl_add_u64 v[26:27], s[34:35], 0, v[26:27]
	v_lshl_add_u64 v[26:27], v[122:123], 1, v[26:27]
	s_mov_b32 s2, 0x280000
	v_cvt_pk_bf16_f32 v30, v30, v31
	v_cvt_pk_bf16_f32 v31, v32, v33
	v_cvt_pk_bf16_f32 v32, v34, v35
	v_cvt_pk_bf16_f32 v33, v28, v29
	v_add_co_u32_e32 v28, vcc, s2, v26
	v_pk_mul_f32 v[24:25], v[24:25], v[146:147]
	s_nop 0
	v_addc_co_u32_e32 v29, vcc, 0, v27, vcc
	v_pk_mul_f32 v[22:23], v[22:23], v[144:145]
	v_pk_mul_f32 v[20:21], v[20:21], v[142:143]
	s_and_b64 vcc, exec, s[40:41]
	v_pk_mul_f32 v[18:19], v[18:19], v[140:141]
	global_store_dwordx4 v[28:29], v[30:33], off sc0 sc1
	s_cbranch_vccnz .LBB0_585
	v_mul_f32_e32 v29, 0x3d372713, v18
	v_mul_f32_e32 v29, v18, v29
	v_fma_f32 v29, v18, v29, v18
	v_mul_f32_e32 v29, 0x3f4c422a, v29
	v_add_f32_e32 v29, v29, v29
	v_mul_f32_e32 v29, 0xbfb8aa3b, v29
	v_exp_f32_e32 v29, v29
	v_mul_f32_e32 v28, 0x3d372713, v22
	v_mul_f32_e32 v28, v22, v28
	v_mov_b32_e32 v31, v23
	v_add_f32_e32 v29, 1.0, v29
	v_rcp_f32_e32 v30, v29
	v_mul_f32_e32 v29, 0x3d372713, v23
	v_mul_f32_e32 v29, v23, v29
	v_fma_f32 v28, v22, v28, v22
	v_fmac_f32_e32 v31, v31, v29
	v_mul_f32_e32 v28, 0x3f4c422a, v28
	v_mul_f32_e32 v29, 0x3f4c422a, v31
	v_add_f32_e32 v28, v28, v28
	v_add_f32_e32 v29, v29, v29
	v_mul_f32_e32 v33, 0x3d372713, v20
	v_mul_f32_e32 v28, 0xbfb8aa3b, v28
	v_mul_f32_e32 v29, 0xbfb8aa3b, v29
	v_mul_f32_e32 v33, v20, v33
	v_exp_f32_e32 v28, v28
	v_exp_f32_e32 v29, v29
	v_fma_f32 v33, v20, v33, v20
	v_mul_f32_e32 v33, 0x3f4c422a, v33
	v_add_f32_e32 v33, v33, v33
	v_mul_f32_e32 v33, 0xbfb8aa3b, v33
	v_add_f32_e32 v28, 1.0, v28
	v_add_f32_e32 v29, 1.0, v29
	v_exp_f32_e32 v33, v33
	v_rcp_f32_e32 v28, v28
	v_rcp_f32_e32 v29, v29
	v_mul_f32_e32 v31, 0x3d372713, v19
	v_mul_f32_e32 v31, v19, v31
	v_mov_b32_e32 v32, v19
	v_fmac_f32_e32 v32, v32, v31
	v_add_f32_e32 v33, 1.0, v33
	v_mul_f32_e32 v31, 0x3f4c422a, v32
	v_mul_f32_e32 v32, 0x3d372713, v24
	v_rcp_f32_e32 v34, v33
	v_mul_f32_e32 v33, 0x3d372713, v25
	v_pk_mul_f32 v[22:23], v[22:23], v[28:29]
	v_mul_f32_e32 v28, 0x3d372713, v21
	v_mul_f32_e32 v32, v24, v32
	v_mul_f32_e32 v33, v25, v33
	v_mul_f32_e32 v28, v21, v28
	v_fma_f32 v32, v24, v32, v24
	v_fma_f32 v33, v25, v33, v25
	v_fma_f32 v28, v21, v28, v21
	v_mul_f32_e32 v32, 0x3f4c422a, v32
	v_mul_f32_e32 v33, 0x3f4c422a, v33
	v_mul_f32_e32 v28, 0x3f4c422a, v28
	v_add_f32_e32 v31, v31, v31
	v_add_f32_e32 v32, v32, v32
	v_add_f32_e32 v33, v33, v33
	v_add_f32_e32 v28, v28, v28
	v_mul_f32_e32 v31, 0xbfb8aa3b, v31
	v_mul_f32_e32 v32, 0xbfb8aa3b, v32
	v_mul_f32_e32 v33, 0xbfb8aa3b, v33
	v_mul_f32_e32 v28, 0xbfb8aa3b, v28
	v_exp_f32_e32 v31, v31
	v_exp_f32_e32 v32, v32
	v_exp_f32_e32 v33, v33
	v_exp_f32_e32 v28, v28
	v_add_f32_e32 v31, 1.0, v31
	v_add_f32_e32 v32, 1.0, v32
	v_add_f32_e32 v33, 1.0, v33
	v_add_f32_e32 v28, 1.0, v28
	v_rcp_f32_e32 v31, v31
	v_rcp_f32_e32 v32, v32
	v_rcp_f32_e32 v33, v33
	v_rcp_f32_e32 v35, v28
	v_pk_mul_f32 v[18:19], v[18:19], v[30:31]
	v_pk_mul_f32 v[24:25], v[24:25], v[32:33]
	v_pk_mul_f32 v[20:21], v[20:21], v[34:35]
.LBB0_585:
	s_mov_b64 s[2:3], 0x280000
	v_lshl_add_u64 v[26:27], v[26:27], 0, s[2:3]
	v_cvt_pk_bf16_f32 v22, v22, v23
	v_cvt_pk_bf16_f32 v23, v24, v25
	v_cvt_pk_bf16_f32 v24, v18, v19
	v_pk_mul_f32 v[16:17], v[16:17], v[154:155]
	v_pk_mul_f32 v[14:15], v[14:15], v[152:153]
	v_pk_mul_f32 v[12:13], v[12:13], v[150:151]
	s_and_b64 vcc, exec, s[40:41]
	v_pk_mul_f32 v[18:19], v[10:11], v[148:149]
	v_cvt_pk_bf16_f32 v25, v20, v21
	global_store_dwordx4 v[26:27], v[22:25], off offset:256 sc0 sc1
	s_cbranch_vccnz .LBB0_587
	v_mul_f32_e32 v11, 0x3d372713, v18
	v_mul_f32_e32 v11, v18, v11
	v_fma_f32 v11, v18, v11, v18
	v_mul_f32_e32 v11, 0x3f4c422a, v11
	v_add_f32_e32 v11, v11, v11
	v_mul_f32_e32 v11, 0xbfb8aa3b, v11
	v_exp_f32_e32 v11, v11
	v_mul_f32_e32 v10, 0x3d372713, v14
	v_mul_f32_e32 v10, v14, v10
	v_mov_b32_e32 v21, v15
	v_add_f32_e32 v11, 1.0, v11
	v_rcp_f32_e32 v20, v11
	v_mul_f32_e32 v11, 0x3d372713, v15
	v_mul_f32_e32 v11, v15, v11
	v_fma_f32 v10, v14, v10, v14
	v_fmac_f32_e32 v21, v21, v11
	v_mul_f32_e32 v10, 0x3f4c422a, v10
	v_mul_f32_e32 v11, 0x3f4c422a, v21
	v_add_f32_e32 v10, v10, v10
	v_add_f32_e32 v11, v11, v11
	v_mul_f32_e32 v23, 0x3d372713, v12
	v_mul_f32_e32 v10, 0xbfb8aa3b, v10
	v_mul_f32_e32 v11, 0xbfb8aa3b, v11
	v_mul_f32_e32 v23, v12, v23
	v_exp_f32_e32 v10, v10
	v_exp_f32_e32 v11, v11
	v_fma_f32 v23, v12, v23, v12
	v_mul_f32_e32 v23, 0x3f4c422a, v23
	v_add_f32_e32 v23, v23, v23
	v_mul_f32_e32 v23, 0xbfb8aa3b, v23
	v_add_f32_e32 v10, 1.0, v10
	v_add_f32_e32 v11, 1.0, v11
	v_exp_f32_e32 v23, v23
	v_rcp_f32_e32 v10, v10
	v_rcp_f32_e32 v11, v11
	v_mul_f32_e32 v21, 0x3d372713, v19
	v_mul_f32_e32 v21, v19, v21
	v_mov_b32_e32 v22, v19
	v_fmac_f32_e32 v22, v22, v21
	v_add_f32_e32 v23, 1.0, v23
	v_mul_f32_e32 v21, 0x3f4c422a, v22
	v_mul_f32_e32 v22, 0x3d372713, v16
	v_rcp_f32_e32 v24, v23
	v_mul_f32_e32 v23, 0x3d372713, v17
	v_pk_mul_f32 v[14:15], v[14:15], v[10:11]
	v_mul_f32_e32 v10, 0x3d372713, v13
	v_mul_f32_e32 v22, v16, v22
	v_mul_f32_e32 v23, v17, v23
	v_mul_f32_e32 v10, v13, v10
	v_fma_f32 v22, v16, v22, v16
	v_fma_f32 v23, v17, v23, v17
	v_fma_f32 v10, v13, v10, v13
	v_mul_f32_e32 v22, 0x3f4c422a, v22
	v_mul_f32_e32 v23, 0x3f4c422a, v23
	v_mul_f32_e32 v10, 0x3f4c422a, v10
	v_add_f32_e32 v21, v21, v21
	v_add_f32_e32 v22, v22, v22
	v_add_f32_e32 v23, v23, v23
	v_add_f32_e32 v10, v10, v10
	v_mul_f32_e32 v21, 0xbfb8aa3b, v21
	v_mul_f32_e32 v22, 0xbfb8aa3b, v22
	v_mul_f32_e32 v23, 0xbfb8aa3b, v23
	v_mul_f32_e32 v10, 0xbfb8aa3b, v10
	v_exp_f32_e32 v21, v21
	v_exp_f32_e32 v22, v22
	v_exp_f32_e32 v23, v23
	v_exp_f32_e32 v10, v10
	v_add_f32_e32 v21, 1.0, v21
	v_add_f32_e32 v22, 1.0, v22
	v_add_f32_e32 v23, 1.0, v23
	v_add_f32_e32 v10, 1.0, v10
	v_rcp_f32_e32 v21, v21
	v_rcp_f32_e32 v22, v22
	v_rcp_f32_e32 v23, v23
	v_rcp_f32_e32 v25, v10
	v_pk_mul_f32 v[18:19], v[18:19], v[20:21]
	v_pk_mul_f32 v[16:17], v[16:17], v[22:23]
	v_pk_mul_f32 v[12:13], v[12:13], v[24:25]
.LBB0_587:
	v_lshlrev_b64 v[10:11], 14, v[124:125]
	v_lshl_add_u64 v[10:11], s[34:35], 0, v[10:11]
	v_lshl_add_u64 v[10:11], v[122:123], 1, v[10:11]
	s_mov_b32 s2, 0x2c0000
	v_cvt_pk_bf16_f32 v14, v14, v15
	v_cvt_pk_bf16_f32 v15, v16, v17
	v_cvt_pk_bf16_f32 v16, v18, v19
	v_cvt_pk_bf16_f32 v17, v12, v13
	v_add_co_u32_e32 v12, vcc, s2, v10
	v_pk_mul_f32 v[8:9], v[8:9], v[146:147]
	s_nop 0
	v_addc_co_u32_e32 v13, vcc, 0, v11, vcc
	v_pk_mul_f32 v[6:7], v[6:7], v[144:145]
	v_pk_mul_f32 v[4:5], v[4:5], v[142:143]
	s_and_b64 vcc, exec, s[40:41]
	v_pk_mul_f32 v[2:3], v[2:3], v[140:141]
	global_store_dwordx4 v[12:13], v[14:17], off sc0 sc1
	s_cbranch_vccnz .LBB0_589
	v_mul_f32_e32 v13, 0x3d372713, v2
	v_mul_f32_e32 v13, v2, v13
	v_fma_f32 v13, v2, v13, v2
	v_mul_f32_e32 v13, 0x3f4c422a, v13
	v_add_f32_e32 v13, v13, v13
	v_mul_f32_e32 v13, 0xbfb8aa3b, v13
	v_exp_f32_e32 v13, v13
	v_mul_f32_e32 v12, 0x3d372713, v6
	v_mul_f32_e32 v12, v6, v12
	v_mov_b32_e32 v15, v7
	v_add_f32_e32 v13, 1.0, v13
	v_rcp_f32_e32 v14, v13
	v_mul_f32_e32 v13, 0x3d372713, v7
	v_mul_f32_e32 v13, v7, v13
	v_fma_f32 v12, v6, v12, v6
	v_fmac_f32_e32 v15, v15, v13
	v_mul_f32_e32 v12, 0x3f4c422a, v12
	v_mul_f32_e32 v13, 0x3f4c422a, v15
	v_add_f32_e32 v12, v12, v12
	v_add_f32_e32 v13, v13, v13
	v_mul_f32_e32 v17, 0x3d372713, v4
	v_mul_f32_e32 v12, 0xbfb8aa3b, v12
	v_mul_f32_e32 v13, 0xbfb8aa3b, v13
	v_mul_f32_e32 v17, v4, v17
	v_exp_f32_e32 v12, v12
	v_exp_f32_e32 v13, v13
	v_fma_f32 v17, v4, v17, v4
	v_mul_f32_e32 v17, 0x3f4c422a, v17
	v_add_f32_e32 v17, v17, v17
	v_mul_f32_e32 v17, 0xbfb8aa3b, v17
	v_add_f32_e32 v12, 1.0, v12
	v_add_f32_e32 v13, 1.0, v13
	v_exp_f32_e32 v17, v17
	v_rcp_f32_e32 v12, v12
	v_rcp_f32_e32 v13, v13
	v_mul_f32_e32 v15, 0x3d372713, v3
	v_mul_f32_e32 v15, v3, v15
	v_mov_b32_e32 v16, v3
	v_fmac_f32_e32 v16, v16, v15
	v_add_f32_e32 v17, 1.0, v17
	v_mul_f32_e32 v15, 0x3f4c422a, v16
	v_mul_f32_e32 v16, 0x3d372713, v8
	v_rcp_f32_e32 v18, v17
	v_mul_f32_e32 v17, 0x3d372713, v9
	v_pk_mul_f32 v[6:7], v[6:7], v[12:13]
	v_mul_f32_e32 v12, 0x3d372713, v5
	v_mul_f32_e32 v16, v8, v16
	v_mul_f32_e32 v17, v9, v17
	v_mul_f32_e32 v12, v5, v12
	v_fma_f32 v16, v8, v16, v8
	v_fma_f32 v17, v9, v17, v9
	v_fma_f32 v12, v5, v12, v5
	v_mul_f32_e32 v16, 0x3f4c422a, v16
	v_mul_f32_e32 v17, 0x3f4c422a, v17
	v_mul_f32_e32 v12, 0x3f4c422a, v12
	v_add_f32_e32 v15, v15, v15
	v_add_f32_e32 v16, v16, v16
	v_add_f32_e32 v17, v17, v17
	v_add_f32_e32 v12, v12, v12
	v_mul_f32_e32 v15, 0xbfb8aa3b, v15
	v_mul_f32_e32 v16, 0xbfb8aa3b, v16
	v_mul_f32_e32 v17, 0xbfb8aa3b, v17
	v_mul_f32_e32 v12, 0xbfb8aa3b, v12
	v_exp_f32_e32 v15, v15
	v_exp_f32_e32 v16, v16
	v_exp_f32_e32 v17, v17
	v_exp_f32_e32 v12, v12
	v_add_f32_e32 v15, 1.0, v15
	v_add_f32_e32 v16, 1.0, v16
	v_add_f32_e32 v17, 1.0, v17
	v_add_f32_e32 v12, 1.0, v12
	v_rcp_f32_e32 v15, v15
	v_rcp_f32_e32 v16, v16
	v_rcp_f32_e32 v17, v17
	v_rcp_f32_e32 v19, v12
	v_pk_mul_f32 v[2:3], v[2:3], v[14:15]
	v_pk_mul_f32 v[8:9], v[8:9], v[16:17]
	v_pk_mul_f32 v[4:5], v[4:5], v[18:19]
.LBB0_589:
	s_mov_b64 s[2:3], 0x2c0000
	v_lshl_add_u64 v[10:11], v[10:11], 0, s[2:3]
	s_andn2_b64 vcc, exec, s[38:39]
	s_mov_b64 s[2:3], -1
	v_cvt_pk_bf16_f32 v6, v6, v7
	v_cvt_pk_bf16_f32 v7, v8, v9
	v_cvt_pk_bf16_f32 v8, v2, v3
	v_cvt_pk_bf16_f32 v9, v4, v5
	global_store_dwordx4 v[10:11], v[6:9], off offset:256 sc0 sc1
	s_cbranch_vccnz .LBB0_546
	s_andn2_b64 vcc, exec, s[4:5]
	s_cbranch_vccnz .LBB0_545
	s_barrier
	s_branch .LBB0_545

.LBB0_1422:
	v_add_u32_e32 v43, s17, v26
	s_mov_b32 s0, 0x10000
	v_cmp_gt_i32_e64 s[38:39], s0, v43
	v_ashrrev_i32_e32 v27, 12, v26
	s_movk_i32 s18, 0xfff
	v_cndmask_b32_e64 v47, v26, v43, s[38:39]
	v_ashrrev_i32_e32 v0, 12, v47
	v_bfi_b32 v2, -8, v0, v47
	v_ashrrev_i32_e32 v3, 31, v2
	v_ashrrev_i32_e32 v46, 3, v47
	v_lshlrev_b64 v[2:3], 12, v[2:3]
	v_readlane_b32 s0, v253, 23
	s_waitcnt vmcnt(0)
	v_bfi_b32 v28, -8, v27, v26
	v_and_or_b32 v2, v46, s18, v2
	v_readlane_b32 s1, v253, 24
	v_ashrrev_i32_e32 v29, 31, v28
	v_readlane_b32 s8, v253, 28
	v_lshl_add_u64 v[4:5], v[2:3], 2, s[0:1]
	v_lshlrev_b64 v[34:35], 12, v[28:29]
	v_ashrrev_i32_e32 v48, 3, v26
	global_load_dword v54, v[4:5], off
	v_lshlrev_b64 v[4:5], 5, v[2:3]
	v_readlane_b32 s9, v253, 29
	v_lshlrev_b64 v[2:3], 10, v[2:3]
	v_and_or_b32 v34, v48, s18, v34
	v_lshl_add_u64 v[4:5], s[8:9], 0, v[4:5]
	v_lshl_add_u64 v[2:3], v[44:45], 0, v[2:3]
	v_and_b32_e32 v0, 7, v26
	v_lshl_add_u64 v[26:27], v[34:35], 2, s[0:1]
	global_load_dwordx4 v[18:21], v[4:5], off offset:16
	global_load_dwordx4 v[22:25], v[4:5], off
	global_load_dwordx4 v[14:17], v[2:3], off
	global_load_dwordx4 v[10:13], v[2:3], off offset:256
	global_load_dwordx4 v[6:9], v[2:3], off offset:512
	s_nop 0
	global_load_dwordx4 v[2:5], v[2:3], off offset:768
	v_lshlrev_b32_e32 v0, 8, v0
	global_load_dword v36, v[26:27], off
	v_lshlrev_b64 v[26:27], 5, v[34:35]
	v_lshl_add_u64 v[30:31], s[8:9], 0, v[26:27]
	global_load_dwordx4 v[26:29], v[30:31], off offset:16
	s_nop 0
	global_load_dwordx4 v[30:33], v[30:31], off
	s_waitcnt vmcnt(2)
	v_cmp_eq_u32_e32 vcc, 0, v36
	v_bcnt_u32_b32 v36, v36, 0
	v_cmp_lt_u32_e64 s[40:41], 2, v36
	v_cmp_lt_u32_e64 s[42:43], 1, v36
	s_waitcnt vmcnt(1)
	v_max_f32_e32 v37, v28, v28
	v_cndmask_b32_e64 v26, v239, v26, s[40:41]
	v_max_f32_e32 v36, v26, v26
	s_waitcnt vmcnt(0)
	v_cndmask_b32_e32 v30, v30, v239, vcc
	v_cndmask_b32_e64 v32, v239, v32, s[42:43]
	v_max_f32_e32 v36, v36, v37
	v_max3_f32 v36, v30, v32, v36
	v_sub_f32_e32 v30, v30, v36
	v_exp_f32_e32 v30, v30
	v_sub_f32_e32 v26, v26, v36
	v_exp_f32_e32 v26, v26
	v_mul_f32_e32 v55, v31, v30
	v_fma_f32 v30, v31, v30, 0
	v_sub_f32_e32 v31, v32, v36
	v_exp_f32_e32 v31, v31
	v_cndmask_b32_e64 v30, v30, 0, vcc
	v_mul_f32_e32 v57, v27, v26
	v_cndmask_b32_e64 v26, 0, v57, s[40:41]
	v_mul_f32_e32 v56, v33, v31
	v_cndmask_b32_e64 v31, 0, v56, s[42:43]
	v_add_f32_e32 v30, v31, v30
	v_add_f32_e32 v49, v26, v30
	v_sub_f32_e32 v26, v28, v36
	v_exp_f32_e32 v26, v26
	s_nop 0
	v_mul_f32_e32 v58, v29, v26
	v_fmac_f32_e32 v49, v29, v26
	v_lshlrev_b64 v[26:27], 10, v[34:35]
	v_lshl_add_u64 v[38:39], v[44:45], 0, v[26:27]
	global_load_dwordx4 v[26:29], v[38:39], off
	s_waitcnt vmcnt(0)
	v_and_b32_e32 v30, 0xffff0000, v29
	v_fma_f32 v30, v55, v30, 0
	v_cndmask_b32_e64 v34, v30, 0, vcc
	global_load_dwordx4 v[30:33], v[38:39], off offset:256
	s_waitcnt vmcnt(0)
	v_and_b32_e32 v35, 0xffff0000, v33
	v_mul_f32_e32 v35, v56, v35
	v_cndmask_b32_e64 v35, 0, v35, s[42:43]
	v_add_f32_e32 v40, v35, v34
	global_load_dwordx4 v[34:37], v[38:39], off offset:512
	v_lshlrev_b32_e32 v52, 16, v32
	v_and_b32_e32 v32, 0xffff0000, v32
	v_mul_f32_e32 v32, v56, v32
	v_cndmask_b32_e64 v32, 0, v32, s[42:43]
	v_mul_f32_e32 v52, v56, v52
	v_cndmask_b32_e64 v52, 0, v52, s[42:43]
	s_waitcnt vmcnt(0)
	v_and_b32_e32 v41, 0xffff0000, v37
	v_mul_f32_e32 v41, v57, v41
	v_cndmask_b32_e64 v41, 0, v41, s[40:41]
	v_add_f32_e32 v51, v41, v40
	global_load_dwordx4 v[38:41], v[38:39], off offset:768
	s_waitcnt vmcnt(0)
	v_and_b32_e32 v50, 0xffff0000, v41
	v_fmac_f32_e32 v51, v58, v50
	v_lshlrev_b32_e32 v50, 16, v28
	v_and_b32_e32 v28, 0xffff0000, v28
	v_fma_f32 v28, v55, v28, 0
	v_cndmask_b32_e64 v28, v28, 0, vcc
	v_add_f32_e32 v28, v32, v28
	v_and_b32_e32 v32, 0xffff0000, v36
	v_mul_f32_e32 v32, v57, v32
	v_cndmask_b32_e64 v32, 0, v32, s[40:41]
	v_add_f32_e32 v53, v32, v28
	v_and_b32_e32 v28, 0xffff0000, v40
	v_fma_f32 v50, v55, v50, 0
	v_fmac_f32_e32 v53, v58, v28
	v_lshlrev_b32_e32 v28, 16, v29
	v_lshlrev_b32_e32 v29, 16, v33
	v_cndmask_b32_e64 v50, v50, 0, vcc
	v_fma_f32 v28, v55, v28, 0
	v_mul_f32_e32 v29, v56, v29
	v_add_f32_e32 v50, v52, v50
	v_lshlrev_b32_e32 v52, 16, v36
	v_cndmask_b32_e64 v28, v28, 0, vcc
	v_cndmask_b32_e64 v29, 0, v29, s[42:43]
	v_mul_f32_e32 v52, v57, v52
	v_add_f32_e32 v28, v29, v28
	v_lshlrev_b32_e32 v29, 16, v37
	v_cndmask_b32_e64 v52, 0, v52, s[40:41]
	v_mul_f32_e32 v29, v57, v29
	v_add_f32_e32 v52, v52, v50
	v_lshlrev_b32_e32 v50, 16, v40
	v_cndmask_b32_e64 v29, 0, v29, s[40:41]
	v_fmac_f32_e32 v52, v58, v50
	v_add_f32_e32 v50, v29, v28
	v_lshlrev_b32_e32 v28, 16, v41
	v_fmac_f32_e32 v50, v58, v28
	v_and_b32_e32 v28, 0xffff0000, v27
	v_and_b32_e32 v29, 0xffff0000, v31
	v_fma_f32 v28, v55, v28, 0
	v_mul_f32_e32 v29, v56, v29
	v_cndmask_b32_e64 v28, v28, 0, vcc
	v_cndmask_b32_e64 v29, 0, v29, s[42:43]
	v_add_f32_e32 v28, v29, v28
	v_and_b32_e32 v29, 0xffff0000, v35
	v_mul_f32_e32 v29, v57, v29
	v_cndmask_b32_e64 v29, 0, v29, s[40:41]
	v_add_f32_e32 v29, v29, v28
	v_and_b32_e32 v28, 0xffff0000, v39
	v_fmac_f32_e32 v29, v58, v28
	v_lshlrev_b32_e32 v28, 16, v26
	v_lshlrev_b32_e32 v32, 16, v30
	v_fma_f32 v28, v55, v28, 0
	v_mul_f32_e32 v32, v56, v32
	v_cndmask_b32_e64 v28, v28, 0, vcc
	v_cndmask_b32_e64 v32, 0, v32, s[42:43]
	v_add_f32_e32 v28, v32, v28
	v_lshlrev_b32_e32 v32, 16, v34
	v_mul_f32_e32 v32, v57, v32
	v_cndmask_b32_e64 v32, 0, v32, s[40:41]
	v_add_f32_e32 v32, v32, v28
	v_lshlrev_b32_e32 v28, 16, v38
	v_fmac_f32_e32 v32, v58, v28
	v_and_b32_e32 v26, 0xffff0000, v26
	v_and_b32_e32 v28, 0xffff0000, v30
	v_fma_f32 v26, v55, v26, 0
	v_mul_f32_e32 v28, v56, v28
	v_cndmask_b32_e64 v26, v26, 0, vcc
	v_cndmask_b32_e64 v28, 0, v28, s[42:43]
	v_add_f32_e32 v26, v28, v26
	v_and_b32_e32 v28, 0xffff0000, v34
	v_mul_f32_e32 v28, v57, v28
	v_cndmask_b32_e64 v28, 0, v28, s[40:41]
	v_add_f32_e32 v33, v28, v26
	v_and_b32_e32 v26, 0xffff0000, v38
	v_fmac_f32_e32 v33, v58, v26
	v_lshlrev_b32_e32 v26, 16, v27
	v_lshlrev_b32_e32 v27, 16, v31
	v_fma_f32 v26, v55, v26, 0
	v_mul_f32_e32 v27, v56, v27
	v_cndmask_b32_e64 v26, v26, 0, vcc
	v_cndmask_b32_e64 v27, 0, v27, s[42:43]
	v_add_f32_e32 v26, v27, v26
	v_lshlrev_b32_e32 v27, 16, v35
	v_mul_f32_e32 v27, v57, v27
	v_cndmask_b32_e64 v27, 0, v27, s[40:41]
	v_add_f32_e32 v28, v27, v26
	v_lshlrev_b32_e32 v26, 16, v39
	v_fmac_f32_e32 v28, v58, v26
	v_div_scale_f32 v26, s[0:1], v49, v49, 1.0
	v_rcp_f32_e32 v27, v26
	s_nop 0
	v_fma_f32 v30, -v26, v27, 1.0
	v_fmac_f32_e32 v27, v30, v27
	v_div_scale_f32 v30, vcc, 1.0, v49, 1.0
	v_mul_f32_e32 v31, v30, v27
	v_fma_f32 v34, -v26, v31, v30
	v_fmac_f32_e32 v31, v34, v27
	v_fma_f32 v26, -v26, v31, v30
	v_div_fmas_f32 v26, v26, v27, v31
	v_div_fixup_f32 v26, v26, v49, 1.0
	v_pk_mul_f32 v[30:31], v[26:27], v[32:33] op_sel_hi:[0,1]
	v_ashrrev_i32_e32 v49, 31, v48
	v_pk_mul_f32 v[28:29], v[26:27], v[28:29] op_sel_hi:[0,1]
	v_pk_mul_f32 v[32:33], v[26:27], v[50:51] op_sel_hi:[0,1]
	v_pk_mul_f32 v[34:35], v[26:27], v[52:53] op_sel_hi:[0,1]
	v_cvt_pk_bf16_f32 v26, v30, v31
	v_lshlrev_b64 v[30:31], 12, v[48:49]
	v_lshl_add_u64 v[30:31], s[92:93], 0, v[30:31]
	v_lshl_add_u64 v[30:31], v[30:31], 0, v[0:1]
	v_lshlrev_b32_e32 v0, 1, v42
	v_lshl_add_u64 v[30:31], v[30:31], 0, v[0:1]
	v_add_co_u32_e32 v30, vcc, 0x28d81000, v30
	v_cvt_pk_bf16_f32 v27, v28, v29
	v_cvt_pk_bf16_f32 v28, v34, v35
	v_cvt_pk_bf16_f32 v29, v32, v33
	s_nop 1
	v_addc_co_u32_e32 v31, vcc, 0, v31, vcc
	global_store_dwordx4 v[30:31], v[26:29], off offset:3072 sc0 sc1
	s_and_saveexec_b64 s[8:9], s[38:39]
	s_cbranch_execz .LBB0_1421
	v_bcnt_u32_b32 v26, v54, 0
	v_cmp_lt_u32_e32 vcc, 2, v26
	v_cmp_eq_u32_e64 s[0:1], 0, v54
	v_cmp_lt_u32_e64 s[38:39], 1, v26
	v_cndmask_b32_e32 v18, v239, v18, vcc
	v_max_f32_e32 v26, v18, v18
	v_max_f32_e32 v27, v20, v20
	v_cndmask_b32_e64 v22, v22, v239, s[0:1]
	v_cndmask_b32_e64 v24, v239, v24, s[38:39]
	v_max_f32_e32 v26, v26, v27
	v_max3_f32 v26, v22, v24, v26
	v_sub_f32_e32 v22, v22, v26
	v_sub_f32_e32 v24, v24, v26
	v_exp_f32_e32 v22, v22
	v_exp_f32_e32 v24, v24
	v_sub_f32_e32 v18, v18, v26
	v_exp_f32_e32 v18, v18
	v_mul_f32_e32 v28, v23, v22
	v_fma_f32 v22, v23, v22, 0
	v_mul_f32_e32 v23, v25, v24
	v_cndmask_b32_e64 v22, v22, 0, s[0:1]
	v_cndmask_b32_e64 v24, 0, v23, s[38:39]
	v_add_f32_e32 v22, v24, v22
	v_mul_f32_e32 v24, v19, v18
	v_cndmask_b32_e32 v18, 0, v24, vcc
	v_add_f32_e32 v22, v18, v22
	v_and_b32_e32 v18, 0xffff0000, v17
	v_and_b32_e32 v19, 0xffff0000, v13
	v_sub_f32_e32 v20, v20, v26
	v_fma_f32 v18, v28, v18, 0
	v_mul_f32_e32 v19, v23, v19
	v_exp_f32_e32 v20, v20
	v_cndmask_b32_e64 v18, v18, 0, s[0:1]
	v_cndmask_b32_e64 v19, 0, v19, s[38:39]
	v_add_f32_e32 v18, v19, v18
	v_and_b32_e32 v19, 0xffff0000, v9
	v_mul_f32_e32 v19, v24, v19
	v_cndmask_b32_e32 v19, 0, v19, vcc
	v_mul_f32_e32 v25, v21, v20
	v_add_f32_e32 v19, v19, v18
	v_and_b32_e32 v18, 0xffff0000, v5
	v_fmac_f32_e32 v22, v21, v20
	v_fmac_f32_e32 v19, v25, v18
	v_lshlrev_b32_e32 v18, 16, v16
	v_lshlrev_b32_e32 v20, 16, v12
	v_fma_f32 v18, v28, v18, 0
	v_mul_f32_e32 v20, v23, v20
	v_cndmask_b32_e64 v18, v18, 0, s[0:1]
	v_cndmask_b32_e64 v20, 0, v20, s[38:39]
	v_and_b32_e32 v16, 0xffff0000, v16
	v_and_b32_e32 v12, 0xffff0000, v12
	v_add_f32_e32 v18, v20, v18
	v_lshlrev_b32_e32 v20, 16, v8
	v_fma_f32 v16, v28, v16, 0
	v_mul_f32_e32 v12, v23, v12
	v_and_b32_e32 v8, 0xffff0000, v8
	v_mul_f32_e32 v20, v24, v20
	v_cndmask_b32_e64 v16, v16, 0, s[0:1]
	v_cndmask_b32_e64 v12, 0, v12, s[38:39]
	v_mul_f32_e32 v8, v24, v8
	v_cndmask_b32_e32 v20, 0, v20, vcc
	v_add_f32_e32 v12, v12, v16
	v_cndmask_b32_e32 v8, 0, v8, vcc
	v_add_f32_e32 v20, v20, v18
	v_lshlrev_b32_e32 v18, 16, v4
	v_add_f32_e32 v21, v8, v12
	v_and_b32_e32 v4, 0xffff0000, v4
	v_fmac_f32_e32 v21, v25, v4
	v_lshlrev_b32_e32 v4, 16, v17
	v_lshlrev_b32_e32 v8, 16, v13
	v_fma_f32 v4, v28, v4, 0
	v_mul_f32_e32 v8, v23, v8
	v_cndmask_b32_e64 v4, v4, 0, s[0:1]
	v_cndmask_b32_e64 v8, 0, v8, s[38:39]
	v_add_f32_e32 v4, v8, v4
	v_lshlrev_b32_e32 v8, 16, v9
	v_mul_f32_e32 v8, v24, v8
	v_cndmask_b32_e32 v8, 0, v8, vcc
	v_fmac_f32_e32 v20, v25, v18
	v_add_f32_e32 v18, v8, v4
	v_lshlrev_b32_e32 v4, 16, v5
	v_fmac_f32_e32 v18, v25, v4
	v_and_b32_e32 v4, 0xffff0000, v15
	v_and_b32_e32 v5, 0xffff0000, v11
	v_fma_f32 v4, v28, v4, 0
	v_mul_f32_e32 v5, v23, v5
	v_cndmask_b32_e64 v4, v4, 0, s[0:1]
	v_cndmask_b32_e64 v5, 0, v5, s[38:39]
	v_add_f32_e32 v4, v5, v4
	v_and_b32_e32 v5, 0xffff0000, v7
	v_mul_f32_e32 v5, v24, v5
	v_cndmask_b32_e32 v5, 0, v5, vcc
	v_add_f32_e32 v5, v5, v4
	v_and_b32_e32 v4, 0xffff0000, v3
	v_fmac_f32_e32 v5, v25, v4
	v_lshlrev_b32_e32 v4, 16, v14
	v_lshlrev_b32_e32 v8, 16, v10
	v_fma_f32 v4, v28, v4, 0
	v_mul_f32_e32 v8, v23, v8
	v_cndmask_b32_e64 v4, v4, 0, s[0:1]
	v_cndmask_b32_e64 v8, 0, v8, s[38:39]
	v_add_f32_e32 v4, v8, v4
	v_lshlrev_b32_e32 v8, 16, v6
	v_mul_f32_e32 v8, v24, v8
	v_cndmask_b32_e32 v8, 0, v8, vcc
	v_add_f32_e32 v8, v8, v4
	v_lshlrev_b32_e32 v4, 16, v2
	v_fmac_f32_e32 v8, v25, v4
	v_and_b32_e32 v4, 0xffff0000, v14
	v_and_b32_e32 v9, 0xffff0000, v10
	v_fma_f32 v4, v28, v4, 0
	v_mul_f32_e32 v9, v23, v9
	v_and_b32_e32 v6, 0xffff0000, v6
	v_cndmask_b32_e64 v4, v4, 0, s[0:1]
	v_cndmask_b32_e64 v9, 0, v9, s[38:39]
	v_mul_f32_e32 v6, v24, v6
	v_add_f32_e32 v4, v9, v4
	v_cndmask_b32_e32 v6, 0, v6, vcc
	v_add_f32_e32 v9, v6, v4
	v_and_b32_e32 v2, 0xffff0000, v2
	v_fmac_f32_e32 v9, v25, v2
	v_lshlrev_b32_e32 v2, 16, v15
	v_lshlrev_b32_e32 v4, 16, v11
	v_fma_f32 v2, v28, v2, 0
	v_mul_f32_e32 v4, v23, v4
	v_cndmask_b32_e64 v2, v2, 0, s[0:1]
	v_cndmask_b32_e64 v4, 0, v4, s[38:39]
	v_div_scale_f32 v6, s[0:1], v22, v22, 1.0
	v_add_f32_e32 v2, v4, v2
	v_lshlrev_b32_e32 v4, 16, v7
	v_rcp_f32_e32 v7, v6
	v_mul_f32_e32 v4, v24, v4
	v_cndmask_b32_e32 v4, 0, v4, vcc
	v_add_f32_e32 v4, v4, v2
	v_lshlrev_b32_e32 v2, 16, v3
	v_fmac_f32_e32 v4, v25, v2
	v_fma_f32 v2, -v6, v7, 1.0
	v_fmac_f32_e32 v7, v2, v7
	v_div_scale_f32 v2, vcc, 1.0, v22, 1.0
	v_mul_f32_e32 v3, v2, v7
	v_fma_f32 v10, -v6, v3, v2
	v_fmac_f32_e32 v3, v10, v7
	v_fma_f32 v2, -v6, v3, v2
	v_div_fmas_f32 v2, v2, v7, v3
	v_div_fixup_f32 v2, v2, v22, 1.0
	v_and_b32_e32 v27, 7, v47
	v_pk_mul_f32 v[6:7], v[2:3], v[8:9] op_sel_hi:[0,1]
	v_ashrrev_i32_e32 v47, 31, v46
	v_pk_mul_f32 v[4:5], v[2:3], v[4:5] op_sel_hi:[0,1]
	v_pk_mul_f32 v[8:9], v[2:3], v[18:19] op_sel_hi:[0,1]
	v_pk_mul_f32 v[10:11], v[2:3], v[20:21] op_sel_hi:[0,1]
	v_cvt_pk_bf16_f32 v2, v6, v7
	v_lshlrev_b64 v[6:7], 12, v[46:47]
	v_cvt_pk_bf16_f32 v3, v4, v5
	v_cvt_pk_bf16_f32 v4, v10, v11
	v_cvt_pk_bf16_f32 v5, v8, v9
	v_lshl_add_u64 v[6:7], s[92:93], 0, v[6:7]
	v_lshlrev_b32_e32 v8, 8, v27
	v_mov_b32_e32 v9, v1
	v_lshl_add_u64 v[6:7], v[6:7], 0, v[8:9]
	v_lshl_add_u64 v[6:7], v[6:7], 0, v[0:1]
	v_add_co_u32_e32 v6, vcc, 0x28d81000, v6
	s_nop 1
	v_addc_co_u32_e32 v7, vcc, 0, v7, vcc
	global_store_dwordx4 v[6:7], v[2:5], off offset:3072 sc0 sc1
	s_branch .LBB0_1421

.LBB0_1496:
	v_cmp_eq_u32_e32 vcc, 0, v132
	v_lshl_or_b32 v160, s58, 8, v186
	v_cmp_ne_u32_e64 s[40:41], 0, v132
	v_ashrrev_i32_e32 v161, 31, v160
	v_lshl_add_u32 v2, s57, 8, v184
	s_movk_i32 s63, 0x5000
	s_cbranch_vccnz .LBB0_1504
	v_mov_b64_e32 v[176:177], s[28:29]
	v_mad_i64_i32 v[132:133], s[2:3], v2, s63, v[176:177]
	v_lshlrev_b64 v[162:163], 1, v[160:161]
	v_lshl_add_u64 v[132:133], v[132:133], 0, v[162:163]
	s_mov_b64 s[30:31], 0x4000
	v_lshl_add_u64 v[134:135], v[132:133], 0, s[30:31]
	v_add_co_u32_e32 v132, vcc, 0x4000, v132
	v_or_b32_e32 v182, 16, v2
	s_nop 0
	v_addc_co_u32_e32 v133, vcc, 0, v133, vcc
	global_load_dwordx4 v[190:193], v[132:133], off
	global_load_dwordx4 v[156:159], v[134:135], off offset:256
	v_mad_i64_i32 v[132:133], s[2:3], v182, s63, v[176:177]
	v_lshl_add_u64 v[132:133], v[132:133], 0, v[162:163]
	v_lshl_add_u64 v[134:135], v[132:133], 0, s[30:31]
	v_add_co_u32_e32 v132, vcc, 0x4000, v132
	v_or_b32_e32 v180, 32, v2
	s_nop 0
	v_addc_co_u32_e32 v133, vcc, 0, v133, vcc
	global_load_dwordx4 v[152:155], v[132:133], off
	global_load_dwordx4 v[148:151], v[134:135], off offset:256
	v_mad_i64_i32 v[132:133], s[2:3], v180, s63, v[176:177]
	v_lshl_add_u64 v[132:133], v[132:133], 0, v[162:163]
	v_lshl_add_u64 v[134:135], v[132:133], 0, s[30:31]
	v_add_co_u32_e32 v132, vcc, 0x4000, v132
	v_or_b32_e32 v178, 48, v2
	s_nop 0
	v_addc_co_u32_e32 v133, vcc, 0, v133, vcc
	global_load_dwordx4 v[144:147], v[132:133], off
	global_load_dwordx4 v[136:139], v[134:135], off offset:256
	v_mad_i64_i32 v[132:133], s[2:3], v178, s63, v[176:177]
	v_lshl_add_u64 v[132:133], v[132:133], 0, v[162:163]
	v_lshl_add_u64 v[134:135], v[132:133], 0, s[30:31]
	v_add_co_u32_e32 v132, vcc, 0x4000, v132
	v_ashrrev_i32_e32 v3, 31, v2
	s_nop 0
	v_addc_co_u32_e32 v133, vcc, 0, v133, vcc
	global_load_dwordx4 v[140:143], v[132:133], off
	s_nop 0
	global_load_dwordx4 v[132:135], v[134:135], off offset:256
	v_lshlrev_b64 v[194:195], 12, v[2:3]
	v_lshl_add_u64 v[194:195], s[34:35], 0, v[194:195]
	v_lshl_add_u64 v[194:195], v[194:195], 0, v[162:163]
	v_ashrrev_i32_e32 v183, 31, v182
	v_ashrrev_i32_e32 v181, 31, v180
	v_ashrrev_i32_e32 v179, 31, v178
	s_movk_i32 s9, 0x4000
	s_waitcnt vmcnt(0)
	v_lshlrev_b32_e32 v196, 16, v190
	v_and_b32_e32 v197, 0xffff0000, v190
	v_lshlrev_b32_e32 v190, 16, v191
	v_and_b32_e32 v191, 0xffff0000, v191
	v_lshlrev_b32_e32 v198, 16, v192
	v_and_b32_e32 v199, 0xffff0000, v192
	v_lshlrev_b32_e32 v192, 16, v193
	v_and_b32_e32 v193, 0xffff0000, v193
	v_pk_mul_f32 v[200:201], v[130:131], v[190:191]
	v_pk_mul_f32 v[190:191], v[128:129], v[196:197]
	v_pk_mul_f32 v[196:197], v[126:127], v[192:193]
	v_pk_mul_f32 v[192:193], v[124:125], v[198:199]
	v_cvt_pk_bf16_f32 v190, v190, v191
	v_cvt_pk_bf16_f32 v191, v200, v201
	s_nop 0
	v_cvt_pk_bf16_f32 v192, v192, v193
	v_cvt_pk_bf16_f32 v193, v196, v197
	global_store_dwordx4 v[194:195], v[190:193], off sc0 sc1
	s_nop 1
	v_lshlrev_b32_e32 v190, 16, v156
	v_and_b32_e32 v191, 0xffff0000, v156
	v_lshlrev_b32_e32 v156, 16, v157
	v_and_b32_e32 v157, 0xffff0000, v157
	v_lshlrev_b32_e32 v192, 16, v158
	v_and_b32_e32 v193, 0xffff0000, v158
	v_lshlrev_b32_e32 v158, 16, v159
	v_and_b32_e32 v159, 0xffff0000, v159
	v_pk_mul_f32 v[196:197], v[98:99], v[156:157]
	v_pk_mul_f32 v[156:157], v[96:97], v[190:191]
	v_pk_mul_f32 v[190:191], v[94:95], v[158:159]
	v_pk_mul_f32 v[158:159], v[92:93], v[192:193]
	v_cvt_pk_bf16_f32 v156, v156, v157
	v_cvt_pk_bf16_f32 v157, v196, v197
	s_nop 0
	v_cvt_pk_bf16_f32 v158, v158, v159
	v_cvt_pk_bf16_f32 v159, v190, v191
	global_store_dwordx4 v[194:195], v[156:159], off offset:256 sc0 sc1
	v_add_u32_e32 v194, 0xa0, v2
	v_ashrrev_i32_e32 v195, 31, v194
	v_lshlrev_b64 v[156:157], 12, v[182:183]
	v_lshlrev_b32_e32 v158, 16, v152
	v_and_b32_e32 v159, 0xffff0000, v152
	v_lshlrev_b32_e32 v152, 16, v153
	v_and_b32_e32 v153, 0xffff0000, v153
	v_lshlrev_b32_e32 v182, 16, v154
	v_and_b32_e32 v183, 0xffff0000, v154
	v_lshlrev_b32_e32 v154, 16, v155
	v_and_b32_e32 v155, 0xffff0000, v155
	v_pk_mul_f32 v[190:191], v[122:123], v[152:153]
	v_pk_mul_f32 v[152:153], v[120:121], v[158:159]
	v_pk_mul_f32 v[158:159], v[118:119], v[154:155]
	v_pk_mul_f32 v[154:155], v[116:117], v[182:183]
	v_lshl_add_u64 v[156:157], s[34:35], 0, v[156:157]
	v_cvt_pk_bf16_f32 v152, v152, v153
	v_cvt_pk_bf16_f32 v153, v190, v191
	v_cvt_pk_bf16_f32 v154, v154, v155
	v_cvt_pk_bf16_f32 v155, v158, v159
	v_lshl_add_u64 v[156:157], v[156:157], 0, v[162:163]
	global_store_dwordx4 v[156:157], v[152:155], off sc0 sc1
	v_add_u32_e32 v182, 0x90, v2
	v_ashrrev_i32_e32 v183, 31, v182
	v_lshlrev_b32_e32 v152, 16, v148
	v_and_b32_e32 v153, 0xffff0000, v148
	v_lshlrev_b32_e32 v148, 16, v149
	v_and_b32_e32 v149, 0xffff0000, v149
	v_lshlrev_b32_e32 v154, 16, v150
	v_and_b32_e32 v155, 0xffff0000, v150
	v_lshlrev_b32_e32 v150, 16, v151
	v_and_b32_e32 v151, 0xffff0000, v151
	v_pk_mul_f32 v[158:159], v[90:91], v[148:149]
	v_pk_mul_f32 v[148:149], v[88:89], v[152:153]
	v_pk_mul_f32 v[152:153], v[86:87], v[150:151]
	v_pk_mul_f32 v[150:151], v[84:85], v[154:155]
	v_cvt_pk_bf16_f32 v148, v148, v149
	v_cvt_pk_bf16_f32 v149, v158, v159
	v_add_u32_e32 v158, 0x80, v2
	v_cvt_pk_bf16_f32 v150, v150, v151
	v_cvt_pk_bf16_f32 v151, v152, v153
	global_store_dwordx4 v[156:157], v[148:151], off offset:256 sc0 sc1
	v_lshlrev_b32_e32 v152, 16, v146
	v_and_b32_e32 v153, 0xffff0000, v146
	v_lshlrev_b64 v[148:149], 12, v[180:181]
	v_lshlrev_b32_e32 v150, 16, v144
	v_and_b32_e32 v151, 0xffff0000, v144
	v_lshlrev_b32_e32 v144, 16, v145
	v_and_b32_e32 v145, 0xffff0000, v145
	v_lshlrev_b32_e32 v146, 16, v147
	v_and_b32_e32 v147, 0xffff0000, v147
	v_pk_mul_f32 v[154:155], v[114:115], v[144:145]
	v_pk_mul_f32 v[144:145], v[112:113], v[150:151]
	v_pk_mul_f32 v[150:151], v[110:111], v[146:147]
	v_pk_mul_f32 v[146:147], v[108:109], v[152:153]
	v_lshl_add_u64 v[148:149], s[34:35], 0, v[148:149]
	v_cvt_pk_bf16_f32 v144, v144, v145
	v_cvt_pk_bf16_f32 v145, v154, v155
	v_cvt_pk_bf16_f32 v146, v146, v147
	v_cvt_pk_bf16_f32 v147, v150, v151
	v_lshl_add_u64 v[148:149], v[148:149], 0, v[162:163]
	global_store_dwordx4 v[148:149], v[144:147], off sc0 sc1
	v_ashrrev_i32_e32 v159, 31, v158
	s_nop 0
	v_lshlrev_b32_e32 v144, 16, v136
	v_and_b32_e32 v145, 0xffff0000, v136
	v_lshlrev_b32_e32 v136, 16, v137
	v_and_b32_e32 v137, 0xffff0000, v137
	v_lshlrev_b32_e32 v146, 16, v138
	v_and_b32_e32 v147, 0xffff0000, v138
	v_lshlrev_b32_e32 v138, 16, v139
	v_and_b32_e32 v139, 0xffff0000, v139
	v_pk_mul_f32 v[150:151], v[82:83], v[136:137]
	v_pk_mul_f32 v[136:137], v[80:81], v[144:145]
	v_pk_mul_f32 v[144:145], v[78:79], v[138:139]
	v_pk_mul_f32 v[138:139], v[76:77], v[146:147]
	v_cvt_pk_bf16_f32 v136, v136, v137
	v_cvt_pk_bf16_f32 v137, v150, v151
	s_nop 0
	v_cvt_pk_bf16_f32 v138, v138, v139
	v_cvt_pk_bf16_f32 v139, v144, v145
	global_store_dwordx4 v[148:149], v[136:139], off offset:256 sc0 sc1
	v_lshlrev_b64 v[144:145], 12, v[178:179]
	s_nop 0
	v_lshlrev_b32_e32 v136, 16, v140
	v_and_b32_e32 v137, 0xffff0000, v140
	v_lshlrev_b32_e32 v138, 16, v141
	v_and_b32_e32 v139, 0xffff0000, v141
	v_lshlrev_b32_e32 v140, 16, v142
	v_and_b32_e32 v141, 0xffff0000, v142
	v_pk_mul_f32 v[138:139], v[106:107], v[138:139]
	v_pk_mul_f32 v[136:137], v[104:105], v[136:137]
	v_pk_mul_f32 v[140:141], v[100:101], v[140:141]
	v_cvt_pk_bf16_f32 v136, v136, v137
	v_cvt_pk_bf16_f32 v137, v138, v139
	v_lshlrev_b32_e32 v142, 16, v143
	v_cvt_pk_bf16_f32 v138, v140, v141
	v_lshl_add_u64 v[140:141], s[34:35], 0, v[144:145]
	v_and_b32_e32 v143, 0xffff0000, v143
	v_lshl_add_u64 v[140:141], v[140:141], 0, v[162:163]
	v_pk_mul_f32 v[142:143], v[102:103], v[142:143]
	s_nop 0
	v_cvt_pk_bf16_f32 v139, v142, v143
	global_store_dwordx4 v[140:141], v[136:139], off sc0 sc1
	s_nop 1
	v_lshlrev_b32_e32 v136, 16, v132
	v_and_b32_e32 v137, 0xffff0000, v132
	v_lshlrev_b32_e32 v132, 16, v133
	v_and_b32_e32 v133, 0xffff0000, v133
	v_lshlrev_b32_e32 v138, 16, v134
	v_and_b32_e32 v139, 0xffff0000, v134
	v_lshlrev_b32_e32 v134, 16, v135
	v_and_b32_e32 v135, 0xffff0000, v135
	v_pk_mul_f32 v[142:143], v[74:75], v[132:133]
	v_pk_mul_f32 v[132:133], v[72:73], v[136:137]
	v_pk_mul_f32 v[136:137], v[70:71], v[134:135]
	v_pk_mul_f32 v[134:135], v[68:69], v[138:139]
	v_cvt_pk_bf16_f32 v132, v132, v133
	v_cvt_pk_bf16_f32 v133, v142, v143
	s_nop 0
	v_cvt_pk_bf16_f32 v134, v134, v135
	v_cvt_pk_bf16_f32 v135, v136, v137
	global_store_dwordx4 v[140:141], v[132:135], off offset:256 sc0 sc1
	v_add_u32_e32 v140, 0xb0, v2
	v_ashrrev_i32_e32 v141, 31, v140
	v_mad_i64_i32 v[132:133], s[2:3], v158, s63, v[176:177]
	v_lshl_add_u64 v[132:133], v[132:133], 0, v[162:163]
	v_lshl_add_u64 v[134:135], v[132:133], 0, s[30:31]
	v_add_co_u32_e32 v132, vcc, s9, v132
	v_lshlrev_b64 v[158:159], 12, v[158:159]
	s_nop 0
	v_addc_co_u32_e32 v133, vcc, 0, v133, vcc
	global_load_dwordx4 v[142:145], v[132:133], off
	global_load_dwordx4 v[146:149], v[134:135], off offset:256
	v_mad_i64_i32 v[132:133], s[2:3], v182, s63, v[176:177]
	v_lshl_add_u64 v[132:133], v[132:133], 0, v[162:163]
	v_lshl_add_u64 v[134:135], v[132:133], 0, s[30:31]
	v_add_co_u32_e32 v132, vcc, s9, v132
	v_lshl_add_u64 v[158:159], s[34:35], 0, v[158:159]
	s_nop 0
	v_addc_co_u32_e32 v133, vcc, 0, v133, vcc
	global_load_dwordx4 v[150:153], v[132:133], off
	global_load_dwordx4 v[154:157], v[134:135], off offset:256
	v_mad_i64_i32 v[132:133], s[2:3], v194, s63, v[176:177]
	v_lshl_add_u64 v[132:133], v[132:133], 0, v[162:163]
	v_lshl_add_u64 v[134:135], v[132:133], 0, s[30:31]
	v_add_co_u32_e32 v132, vcc, s9, v132
	v_lshl_add_u64 v[158:159], v[158:159], 0, v[162:163]
	s_nop 0
	v_addc_co_u32_e32 v133, vcc, 0, v133, vcc
	global_load_dwordx4 v[178:181], v[132:133], off
	global_load_dwordx4 v[190:193], v[134:135], off offset:256
	v_mad_i64_i32 v[132:133], s[2:3], v140, s63, v[176:177]
	v_lshl_add_u64 v[132:133], v[132:133], 0, v[162:163]
	v_lshl_add_u64 v[134:135], v[132:133], 0, s[30:31]
	v_add_co_u32_e32 v132, vcc, s9, v132
	v_lshlrev_b64 v[140:141], 12, v[140:141]
	s_nop 0
	v_addc_co_u32_e32 v133, vcc, 0, v133, vcc
	global_load_dwordx4 v[136:139], v[132:133], off
	s_nop 0
	global_load_dwordx4 v[132:135], v[134:135], off offset:256
	v_lshl_add_u64 v[140:141], s[34:35], 0, v[140:141]
	v_lshl_add_u64 v[140:141], v[140:141], 0, v[162:163]
	s_waitcnt vmcnt(7)
	v_lshlrev_b32_e32 v176, 16, v142
	v_and_b32_e32 v177, 0xffff0000, v142
	v_lshlrev_b32_e32 v142, 16, v143
	v_and_b32_e32 v143, 0xffff0000, v143
	v_lshlrev_b32_e32 v196, 16, v144
	v_and_b32_e32 v197, 0xffff0000, v144
	v_lshlrev_b32_e32 v144, 16, v145
	v_and_b32_e32 v145, 0xffff0000, v145
	v_pk_mul_f32 v[198:199], v[66:67], v[142:143]
	v_pk_mul_f32 v[142:143], v[64:65], v[176:177]
	v_pk_mul_f32 v[176:177], v[62:63], v[144:145]
	v_pk_mul_f32 v[144:145], v[60:61], v[196:197]
	v_cvt_pk_bf16_f32 v142, v142, v143
	v_cvt_pk_bf16_f32 v143, v198, v199
	s_nop 0
	v_cvt_pk_bf16_f32 v144, v144, v145
	v_cvt_pk_bf16_f32 v145, v176, v177
	global_store_dwordx4 v[158:159], v[142:145], off sc0 sc1
	s_waitcnt vmcnt(7)
	s_nop 0
	v_lshlrev_b32_e32 v142, 16, v146
	v_and_b32_e32 v143, 0xffff0000, v146
	v_lshlrev_b32_e32 v144, 16, v147
	v_and_b32_e32 v145, 0xffff0000, v147
	v_lshlrev_b32_e32 v146, 16, v148
	v_and_b32_e32 v147, 0xffff0000, v148
	v_lshlrev_b32_e32 v148, 16, v149
	v_and_b32_e32 v149, 0xffff0000, v149
	v_pk_mul_f32 v[144:145], v[34:35], v[144:145]
	v_pk_mul_f32 v[142:143], v[32:33], v[142:143]
	v_pk_mul_f32 v[148:149], v[30:31], v[148:149]
	v_pk_mul_f32 v[146:147], v[28:29], v[146:147]
	v_cvt_pk_bf16_f32 v142, v142, v143
	v_cvt_pk_bf16_f32 v143, v144, v145
	s_nop 0
	v_cvt_pk_bf16_f32 v144, v146, v147
	v_cvt_pk_bf16_f32 v145, v148, v149
	global_store_dwordx4 v[158:159], v[142:145], off offset:256 sc0 sc1
	v_lshlrev_b64 v[146:147], 12, v[182:183]
	s_waitcnt vmcnt(7)
	v_lshlrev_b32_e32 v148, 16, v152
	v_lshlrev_b32_e32 v142, 16, v150
	v_and_b32_e32 v143, 0xffff0000, v150
	v_lshlrev_b32_e32 v144, 16, v151
	v_and_b32_e32 v145, 0xffff0000, v151
	v_and_b32_e32 v149, 0xffff0000, v152
	v_lshlrev_b32_e32 v150, 16, v153
	v_and_b32_e32 v151, 0xffff0000, v153
	v_pk_mul_f32 v[144:145], v[58:59], v[144:145]
	v_pk_mul_f32 v[142:143], v[56:57], v[142:143]
	v_lshl_add_u64 v[146:147], s[34:35], 0, v[146:147]
	v_pk_mul_f32 v[150:151], v[54:55], v[150:151]
	v_pk_mul_f32 v[148:149], v[52:53], v[148:149]
	v_cvt_pk_bf16_f32 v142, v142, v143
	v_cvt_pk_bf16_f32 v143, v144, v145
	v_lshl_add_u64 v[146:147], v[146:147], 0, v[162:163]
	v_cvt_pk_bf16_f32 v144, v148, v149
	v_cvt_pk_bf16_f32 v145, v150, v151
	global_store_dwordx4 v[146:147], v[142:145], off sc0 sc1
	s_waitcnt vmcnt(7)
	v_lshlrev_b32_e32 v148, 16, v156
	v_and_b32_e32 v149, 0xffff0000, v156
	v_lshlrev_b32_e32 v142, 16, v154
	v_and_b32_e32 v143, 0xffff0000, v154
	v_lshlrev_b32_e32 v144, 16, v155
	v_and_b32_e32 v145, 0xffff0000, v155
	v_lshlrev_b32_e32 v150, 16, v157
	v_and_b32_e32 v151, 0xffff0000, v157
	v_pk_mul_f32 v[144:145], v[26:27], v[144:145]
	v_pk_mul_f32 v[142:143], v[24:25], v[142:143]
	v_pk_mul_f32 v[150:151], v[22:23], v[150:151]
	v_pk_mul_f32 v[148:149], v[20:21], v[148:149]
	v_cvt_pk_bf16_f32 v142, v142, v143
	v_cvt_pk_bf16_f32 v143, v144, v145
	s_nop 0
	v_cvt_pk_bf16_f32 v144, v148, v149
	v_cvt_pk_bf16_f32 v145, v150, v151
	global_store_dwordx4 v[146:147], v[142:145], off offset:256 sc0 sc1
	v_lshlrev_b64 v[146:147], 12, v[194:195]
	s_waitcnt vmcnt(7)
	v_lshlrev_b32_e32 v148, 16, v180
	v_lshlrev_b32_e32 v142, 16, v178
	v_and_b32_e32 v143, 0xffff0000, v178
	v_lshlrev_b32_e32 v144, 16, v179
	v_and_b32_e32 v145, 0xffff0000, v179
	v_and_b32_e32 v149, 0xffff0000, v180
	v_lshlrev_b32_e32 v150, 16, v181
	v_and_b32_e32 v151, 0xffff0000, v181
	v_pk_mul_f32 v[144:145], v[50:51], v[144:145]
	v_pk_mul_f32 v[142:143], v[48:49], v[142:143]
	v_lshl_add_u64 v[146:147], s[34:35], 0, v[146:147]
	v_pk_mul_f32 v[150:151], v[46:47], v[150:151]
	v_pk_mul_f32 v[148:149], v[44:45], v[148:149]
	v_cvt_pk_bf16_f32 v142, v142, v143
	v_cvt_pk_bf16_f32 v143, v144, v145
	v_lshl_add_u64 v[146:147], v[146:147], 0, v[162:163]
	v_cvt_pk_bf16_f32 v144, v148, v149
	v_cvt_pk_bf16_f32 v145, v150, v151
	global_store_dwordx4 v[146:147], v[142:145], off sc0 sc1
	s_waitcnt vmcnt(7)
	v_lshlrev_b32_e32 v148, 16, v192
	v_and_b32_e32 v149, 0xffff0000, v192
	v_lshlrev_b32_e32 v142, 16, v190
	v_and_b32_e32 v143, 0xffff0000, v190
	v_lshlrev_b32_e32 v144, 16, v191
	v_and_b32_e32 v145, 0xffff0000, v191
	v_lshlrev_b32_e32 v150, 16, v193
	v_and_b32_e32 v151, 0xffff0000, v193
	v_pk_mul_f32 v[144:145], v[18:19], v[144:145]
	v_pk_mul_f32 v[142:143], v[16:17], v[142:143]
	v_pk_mul_f32 v[150:151], v[14:15], v[150:151]
	v_pk_mul_f32 v[148:149], v[12:13], v[148:149]
	v_cvt_pk_bf16_f32 v142, v142, v143
	v_cvt_pk_bf16_f32 v143, v144, v145
	s_nop 0
	v_cvt_pk_bf16_f32 v144, v148, v149
	v_cvt_pk_bf16_f32 v145, v150, v151
	global_store_dwordx4 v[146:147], v[142:145], off offset:256 sc0 sc1
	s_waitcnt vmcnt(7)
	s_nop 0
	v_lshlrev_b32_e32 v142, 16, v136
	v_and_b32_e32 v143, 0xffff0000, v136
	v_lshlrev_b32_e32 v136, 16, v137
	v_and_b32_e32 v137, 0xffff0000, v137
	v_lshlrev_b32_e32 v144, 16, v138
	v_and_b32_e32 v145, 0xffff0000, v138
	v_lshlrev_b32_e32 v138, 16, v139
	v_and_b32_e32 v139, 0xffff0000, v139
	v_pk_mul_f32 v[146:147], v[42:43], v[136:137]
	v_pk_mul_f32 v[136:137], v[40:41], v[142:143]
	v_pk_mul_f32 v[142:143], v[38:39], v[138:139]
	v_pk_mul_f32 v[138:139], v[36:37], v[144:145]
	v_cvt_pk_bf16_f32 v136, v136, v137
	v_cvt_pk_bf16_f32 v137, v146, v147
	s_nop 0
	v_cvt_pk_bf16_f32 v138, v138, v139
	v_cvt_pk_bf16_f32 v139, v142, v143
	global_store_dwordx4 v[140:141], v[136:139], off sc0 sc1
	s_waitcnt vmcnt(7)
	s_nop 0
	v_lshlrev_b32_e32 v136, 16, v132
	v_and_b32_e32 v137, 0xffff0000, v132
	v_lshlrev_b32_e32 v132, 16, v133
	v_and_b32_e32 v133, 0xffff0000, v133
	v_lshlrev_b32_e32 v138, 16, v134
	v_and_b32_e32 v139, 0xffff0000, v134
	v_lshlrev_b32_e32 v134, 16, v135
	v_and_b32_e32 v135, 0xffff0000, v135
	v_pk_mul_f32 v[142:143], v[10:11], v[132:133]
	v_pk_mul_f32 v[132:133], v[8:9], v[136:137]
	v_pk_mul_f32 v[136:137], v[6:7], v[134:135]
	v_pk_mul_f32 v[134:135], v[4:5], v[138:139]
	v_cvt_pk_bf16_f32 v132, v132, v133
	v_cvt_pk_bf16_f32 v133, v142, v143
	s_nop 0
	v_cvt_pk_bf16_f32 v134, v134, v135
	v_cvt_pk_bf16_f32 v135, v136, v137
	global_store_dwordx4 v[140:141], v[132:135], off offset:256 sc0 sc1
	s_cbranch_execnz .LBB0_1499

.LBB0_1578:
	v_lshl_add_u32 v158, s62, 8, v164
	v_lshl_or_b32 v156, s24, 8, v166
	v_ashrrev_i32_e32 v157, 31, v156
	v_ashrrev_i32_e32 v159, 31, v158
	v_lshl_add_u64 v[160:161], v[156:157], 2, s[8:9]
	v_lshlrev_b64 v[130:131], 13, v[158:159]
	v_lshl_add_u64 v[130:131], v[160:161], 0, v[130:131]
	global_load_dwordx4 v[170:173], v[130:131], off
	global_load_dwordx4 v[174:177], v[130:131], off offset:16
	global_load_dwordx4 v[178:181], v[130:131], off offset:512
	global_load_dwordx4 v[182:185], v[130:131], off offset:528
	v_or_b32_e32 v162, 16, v158
	v_ashrrev_i32_e32 v163, 31, v162
	v_lshlrev_b64 v[130:131], 13, v[162:163]
	v_lshl_add_u64 v[134:135], v[160:161], 0, v[130:131]
	global_load_dwordx4 v[138:141], v[134:135], off offset:16
	global_load_dwordx4 v[142:145], v[134:135], off
	global_load_dwordx4 v[130:133], v[134:135], off offset:528
	s_nop 0
	global_load_dwordx4 v[134:137], v[134:135], off offset:512
	v_lshlrev_b64 v[186:187], 11, v[158:159]
	v_lshl_add_u64 v[186:187], v[186:187], 0, v[156:157]
	v_lshlrev_b64 v[188:189], 2, v[186:187]
	v_lshl_add_u64 v[190:191], s[20:21], 0, v[188:189]
	v_cmp_lt_i32_e32 vcc, v232, v227
	v_lshl_add_u64 v[186:187], v[186:187], 1, s[4:5]
	v_or_b32_e32 v188, 0x200, v188
	v_cndmask_b32_e32 v168, v226, v232, vcc
	v_lshlrev_b32_e32 v168, 2, v168
	v_cmp_lt_i32_e32 vcc, v233, v227
	v_lshl_add_u64 v[188:189], s[20:21], 0, v[188:189]
	s_lshl_b32 s48, s24, 2
	v_cndmask_b32_e32 v169, v226, v233, vcc
	s_ashr_i32 s49, s48, 31
	s_waitcnt vmcnt(0)
	v_pk_add_f32 v[128:129], v[128:129], v[172:173]
	v_pk_add_f32 v[126:127], v[126:127], v[170:171]
	v_pk_add_f32 v[124:125], v[124:125], v[176:177]
	v_pk_add_f32 v[122:123], v[122:123], v[174:175]
	v_pk_add_f32 v[120:121], v[120:121], v[180:181]
	v_pk_add_f32 v[118:119], v[118:119], v[178:179]
	v_pk_add_f32 v[172:173], v[116:117], v[184:185]
	v_pk_add_f32 v[170:171], v[114:115], v[182:183]
	global_store_dwordx4 v[190:191], v[126:129], off sc0 sc1
	global_store_dwordx4 v[190:191], v[122:125], off offset:16 sc0 sc1
	v_cvt_pk_bf16_f32 v114, v126, v127
	v_cvt_pk_bf16_f32 v115, v128, v129
	v_cvt_pk_bf16_f32 v116, v122, v123
	v_cvt_pk_bf16_f32 v117, v124, v125
	s_nop 0
	v_mul_f32_e32 v127, v127, v127
	v_mul_f32_e32 v128, v128, v128
	v_mul_f32_e32 v122, v122, v122
	v_mul_f32_e32 v124, v124, v124
	v_mul_f32_e32 v174, v119, v119
	v_mul_f32_e32 v175, v120, v120
	v_mul_f32_e32 v176, v170, v170
	v_mul_f32_e32 v177, v172, v172
	v_fmac_f32_e32 v127, v126, v126
	v_fmac_f32_e32 v128, v129, v129
	v_fmac_f32_e32 v122, v123, v123
	v_fmac_f32_e32 v124, v125, v125
	v_fmac_f32_e32 v174, v118, v118
	v_fmac_f32_e32 v175, v121, v121
	v_fmac_f32_e32 v176, v171, v171
	v_fmac_f32_e32 v177, v173, v173
	v_add_f32_e32 v123, v127, v128
	v_add_f32_e32 v122, v124, v122
	v_add_f32_e32 v124, v174, v175
	v_add_f32_e32 v125, v177, v176
	v_add_f32_e32 v122, v123, v122
	v_add_f32_e32 v123, v124, v125
	v_add_f32_e32 v123, v122, v123
	ds_bpermute_b32 v124, v168, v123
	global_store_dwordx4 v[186:187], v[114:117], off sc0 sc1
	global_store_dwordx4 v[188:189], v[118:121], off sc0 sc1
	global_store_dwordx4 v[188:189], v[170:173], off offset:16 sc0 sc1
	v_cvt_pk_bf16_f32 v122, v118, v119
	s_waitcnt lgkmcnt(0)
	v_add_f32_e32 v114, v123, v124
	v_lshlrev_b32_e32 v118, 2, v169
	ds_bpermute_b32 v115, v118, v114
	v_cvt_pk_bf16_f32 v123, v120, v121
	v_cvt_pk_bf16_f32 v124, v170, v171
	v_cvt_pk_bf16_f32 v125, v172, v173
	global_store_dwordx4 v[186:187], v[122:125], off offset:256 sc0 sc1
	s_and_saveexec_b64 s[50:51], s[38:39]
	s_mov_b32 s67, 0x800000
	s_movk_i32 s63, 0x5000
	s_cbranch_execz .LBB0_1580
	v_lshlrev_b64 v[116:117], 7, v[158:159]
	v_lshl_add_u64 v[116:117], s[6:7], 0, v[116:117]
	v_lshl_add_u64 v[116:117], s[48:49], 2, v[116:117]
	s_lshl_b32 s24, s58, 2
	v_lshl_add_u64 v[116:117], v[116:117], 0, s[24:25]
	s_waitcnt lgkmcnt(0)
	v_add_f32_e32 v114, v114, v115
	global_store_dword v[116:117], v114, off
.LBB0_1580:
	s_or_b64 exec, exec, s[50:51]
	s_waitcnt lgkmcnt(0)
	v_lshlrev_b64 v[114:115], 11, v[162:163]
	v_lshl_add_u64 v[120:121], v[114:115], 0, v[156:157]
	v_lshlrev_b64 v[122:123], 2, v[120:121]
	v_pk_add_f32 v[112:113], v[112:113], v[144:145]
	v_pk_add_f32 v[110:111], v[110:111], v[142:143]
	v_pk_add_f32 v[106:107], v[106:107], v[138:139]
	v_lshl_add_u64 v[114:115], s[20:21], 0, v[122:123]
	v_pk_add_f32 v[108:109], v[108:109], v[140:141]
	global_store_dwordx4 v[114:115], v[110:113], off sc0 sc1
	global_store_dwordx4 v[114:115], v[106:109], off offset:16 sc0 sc1
	v_cvt_pk_bf16_f32 v114, v110, v111
	v_cvt_pk_bf16_f32 v115, v112, v113
	v_cvt_pk_bf16_f32 v116, v106, v107
	v_pk_add_f32 v[104:105], v[104:105], v[136:137]
	v_mul_f32_e32 v111, v111, v111
	v_mul_f32_e32 v106, v106, v106
	v_fmac_f32_e32 v111, v110, v110
	v_mul_f32_e32 v110, v112, v112
	v_fmac_f32_e32 v106, v107, v107
	v_mul_f32_e32 v107, v108, v108
	v_fmac_f32_e32 v110, v113, v113
	v_fmac_f32_e32 v107, v109, v109
	v_add_f32_e32 v110, v111, v110
	v_add_f32_e32 v106, v107, v106
	v_pk_add_f32 v[102:103], v[102:103], v[134:135]
	v_add_f32_e32 v110, v110, v106
	v_pk_add_f32 v[106:107], v[98:99], v[130:131]
	v_mul_f32_e32 v98, v103, v103
	v_mul_f32_e32 v99, v104, v104
	v_cvt_pk_bf16_f32 v117, v108, v109
	v_pk_add_f32 v[108:109], v[100:101], v[132:133]
	v_fmac_f32_e32 v98, v102, v102
	v_fmac_f32_e32 v99, v105, v105
	v_add_f32_e32 v98, v98, v99
	v_mul_f32_e32 v99, v106, v106
	v_mul_f32_e32 v100, v108, v108
	v_fmac_f32_e32 v99, v107, v107
	v_fmac_f32_e32 v100, v109, v109
	v_add_f32_e32 v99, v100, v99
	v_add_f32_e32 v98, v98, v99
	v_add_f32_e32 v101, v110, v98
	ds_bpermute_b32 v110, v168, v101
	v_or_b32_e32 v122, 0x200, v122
	v_lshl_add_u64 v[120:121], v[120:121], 1, s[4:5]
	v_lshl_add_u64 v[98:99], s[20:21], 0, v[122:123]
	global_store_dwordx4 v[120:121], v[114:117], off sc0 sc1
	global_store_dwordx4 v[98:99], v[102:105], off sc0 sc1
	global_store_dwordx4 v[98:99], v[106:109], off offset:16 sc0 sc1
	s_waitcnt lgkmcnt(0)
	v_add_f32_e32 v98, v101, v110
	ds_bpermute_b32 v99, v118, v98
	v_cvt_pk_bf16_f32 v100, v102, v103
	v_cvt_pk_bf16_f32 v101, v104, v105
	v_cvt_pk_bf16_f32 v102, v106, v107
	v_cvt_pk_bf16_f32 v103, v108, v109
	global_store_dwordx4 v[120:121], v[100:103], off offset:256 sc0 sc1
	s_and_saveexec_b64 s[50:51], s[38:39]
	s_cbranch_execz .LBB0_1582
	v_lshlrev_b64 v[100:101], 7, v[162:163]
	v_lshl_add_u64 v[100:101], s[6:7], 0, v[100:101]
	v_lshl_add_u64 v[100:101], s[48:49], 2, v[100:101]
	s_lshl_b32 s24, s58, 2
	v_lshl_add_u64 v[100:101], v[100:101], 0, s[24:25]
	s_waitcnt lgkmcnt(0)
	v_add_f32_e32 v98, v98, v99
	global_store_dword v[100:101], v98, off
.LBB0_1582:
	s_or_b64 exec, exec, s[50:51]
	v_or_b32_e32 v116, 32, v158
	v_ashrrev_i32_e32 v117, 31, v116
	s_waitcnt lgkmcnt(0)
	v_lshlrev_b64 v[98:99], 13, v[116:117]
	v_lshl_add_u64 v[98:99], v[160:161], 0, v[98:99]
	global_load_dwordx4 v[120:123], v[98:99], off offset:16
	global_load_dwordx4 v[124:127], v[98:99], off
	global_load_dwordx4 v[128:131], v[98:99], off offset:528
	global_load_dwordx4 v[132:135], v[98:99], off offset:512
	v_or_b32_e32 v114, 48, v158
	v_ashrrev_i32_e32 v115, 31, v114
	v_lshlrev_b64 v[98:99], 13, v[114:115]
	v_lshl_add_u64 v[102:103], v[160:161], 0, v[98:99]
	global_load_dwordx4 v[106:109], v[102:103], off offset:16
	global_load_dwordx4 v[110:113], v[102:103], off
	global_load_dwordx4 v[98:101], v[102:103], off offset:528
	s_nop 0
	global_load_dwordx4 v[102:105], v[102:103], off offset:512
	v_lshlrev_b64 v[136:137], 11, v[116:117]
	v_lshl_add_u64 v[136:137], v[136:137], 0, v[156:157]
	s_waitcnt vmcnt(7)
	v_pk_add_f32 v[90:91], v[90:91], v[120:121]
	s_waitcnt vmcnt(6)
	v_pk_add_f32 v[94:95], v[94:95], v[124:125]
	v_lshlrev_b64 v[124:125], 2, v[136:137]
	v_pk_add_f32 v[96:97], v[96:97], v[126:127]
	v_lshl_add_u64 v[120:121], s[20:21], 0, v[124:125]
	v_pk_add_f32 v[92:93], v[92:93], v[122:123]
	global_store_dwordx4 v[120:121], v[94:97], off sc0 sc1
	global_store_dwordx4 v[120:121], v[90:93], off offset:16 sc0 sc1
	v_cvt_pk_bf16_f32 v120, v94, v95
	v_cvt_pk_bf16_f32 v121, v96, v97
	v_cvt_pk_bf16_f32 v122, v90, v91
	v_or_b32_e32 v124, 0x200, v124
	v_mul_f32_e32 v95, v95, v95
	v_mul_f32_e32 v90, v90, v90
	v_fmac_f32_e32 v95, v94, v94
	v_mul_f32_e32 v94, v96, v96
	v_fmac_f32_e32 v90, v91, v91
	v_mul_f32_e32 v91, v92, v92
	v_fmac_f32_e32 v94, v97, v97
	v_fmac_f32_e32 v91, v93, v93
	v_add_f32_e32 v94, v95, v94
	v_add_f32_e32 v90, v91, v90
	v_lshl_add_u64 v[126:127], v[136:137], 1, s[4:5]
	v_add_f32_e32 v94, v94, v90
	s_waitcnt vmcnt(6)
	v_pk_add_f32 v[88:89], v[88:89], v[134:135]
	v_pk_add_f32 v[86:87], v[86:87], v[132:133]
	v_pk_add_f32 v[82:83], v[82:83], v[128:129]
	v_lshl_add_u64 v[90:91], s[20:21], 0, v[124:125]
	v_cvt_pk_bf16_f32 v123, v92, v93
	global_store_dwordx4 v[126:127], v[120:123], off sc0 sc1
	v_pk_add_f32 v[84:85], v[84:85], v[130:131]
	global_store_dwordx4 v[90:91], v[86:89], off sc0 sc1
	global_store_dwordx4 v[90:91], v[82:85], off offset:16 sc0 sc1
	v_cvt_pk_bf16_f32 v90, v86, v87
	v_cvt_pk_bf16_f32 v91, v88, v89
	v_cvt_pk_bf16_f32 v92, v82, v83
	v_cvt_pk_bf16_f32 v93, v84, v85
	s_nop 0
	v_mul_f32_e32 v87, v87, v87
	v_mul_f32_e32 v82, v82, v82
	v_fmac_f32_e32 v87, v86, v86
	v_mul_f32_e32 v86, v88, v88
	v_fmac_f32_e32 v82, v83, v83
	v_mul_f32_e32 v83, v84, v84
	v_fmac_f32_e32 v86, v89, v89
	v_fmac_f32_e32 v83, v85, v85
	v_add_f32_e32 v86, v87, v86
	v_add_f32_e32 v82, v83, v82
	v_add_f32_e32 v82, v86, v82
	v_add_f32_e32 v82, v94, v82
	ds_bpermute_b32 v83, v168, v82
	global_store_dwordx4 v[126:127], v[90:93], off offset:256 sc0 sc1
	s_waitcnt lgkmcnt(0)
	v_add_f32_e32 v82, v82, v83
	ds_bpermute_b32 v83, v118, v82
	s_and_saveexec_b64 s[50:51], s[38:39]
	v_readlane_b32 s68, v251, 10
	v_readlane_b32 s69, v251, 11
	v_readlane_b32 s76, v251, 18
	v_readlane_b32 s77, v251, 19
	v_readlane_b32 s78, v251, 20
	v_readlane_b32 s79, v251, 21
	v_readlane_b32 s80, v251, 22
	v_readlane_b32 s81, v251, 23
	v_readlane_b32 s82, v251, 24
	v_readlane_b32 s83, v251, 25
	v_readlane_b32 s70, v251, 12
	v_readlane_b32 s71, v251, 13
	v_readlane_b32 s72, v251, 14
	v_readlane_b32 s73, v251, 15
	v_readlane_b32 s74, v251, 16
	v_readlane_b32 s75, v251, 17
	s_cbranch_execz .LBB0_1584
	v_lshlrev_b64 v[84:85], 7, v[116:117]
	v_lshl_add_u64 v[84:85], s[6:7], 0, v[84:85]
	v_lshl_add_u64 v[84:85], s[48:49], 2, v[84:85]
	s_lshl_b32 s24, s58, 2
	v_lshl_add_u64 v[84:85], v[84:85], 0, s[24:25]
	s_waitcnt lgkmcnt(0)
	v_add_f32_e32 v82, v82, v83
	global_store_dword v[84:85], v82, off
.LBB0_1584:
	s_or_b64 exec, exec, s[50:51]
	s_waitcnt lgkmcnt(0)
	v_lshlrev_b64 v[82:83], 11, v[114:115]
	v_lshl_add_u64 v[86:87], v[82:83], 0, v[156:157]
	v_lshlrev_b64 v[88:89], 2, v[86:87]
	s_waitcnt vmcnt(8)
	v_pk_add_f32 v[80:81], v[80:81], v[112:113]
	v_pk_add_f32 v[78:79], v[78:79], v[110:111]
	v_pk_add_f32 v[74:75], v[74:75], v[106:107]
	v_lshl_add_u64 v[82:83], s[20:21], 0, v[88:89]
	v_pk_add_f32 v[76:77], v[76:77], v[108:109]
	global_store_dwordx4 v[82:83], v[78:81], off sc0 sc1
	global_store_dwordx4 v[82:83], v[74:77], off offset:16 sc0 sc1
	v_cvt_pk_bf16_f32 v82, v78, v79
	v_cvt_pk_bf16_f32 v83, v80, v81
	v_cvt_pk_bf16_f32 v84, v74, v75
	s_waitcnt vmcnt(8)
	v_pk_add_f32 v[72:73], v[72:73], v[104:105]
	v_mul_f32_e32 v79, v79, v79
	v_mul_f32_e32 v74, v74, v74
	v_fmac_f32_e32 v79, v78, v78
	v_mul_f32_e32 v78, v80, v80
	v_fmac_f32_e32 v74, v75, v75
	v_mul_f32_e32 v75, v76, v76
	v_fmac_f32_e32 v78, v81, v81
	v_fmac_f32_e32 v75, v77, v77
	v_add_f32_e32 v78, v79, v78
	v_add_f32_e32 v74, v75, v74
	v_pk_add_f32 v[70:71], v[70:71], v[102:103]
	v_add_f32_e32 v78, v78, v74
	v_pk_add_f32 v[74:75], v[66:67], v[98:99]
	v_mul_f32_e32 v66, v71, v71
	v_mul_f32_e32 v67, v72, v72
	v_cvt_pk_bf16_f32 v85, v76, v77
	v_pk_add_f32 v[76:77], v[68:69], v[100:101]
	v_fmac_f32_e32 v66, v70, v70
	v_fmac_f32_e32 v67, v73, v73
	v_add_f32_e32 v66, v66, v67
	v_mul_f32_e32 v67, v74, v74
	v_mul_f32_e32 v68, v76, v76
	v_fmac_f32_e32 v67, v75, v75
	v_fmac_f32_e32 v68, v77, v77
	v_add_f32_e32 v67, v68, v67
	v_add_f32_e32 v66, v66, v67
	v_add_f32_e32 v69, v78, v66
	ds_bpermute_b32 v78, v168, v69
	v_or_b32_e32 v88, 0x200, v88
	v_lshl_add_u64 v[86:87], v[86:87], 1, s[4:5]
	v_lshl_add_u64 v[66:67], s[20:21], 0, v[88:89]
	global_store_dwordx4 v[86:87], v[82:85], off sc0 sc1
	global_store_dwordx4 v[66:67], v[70:73], off sc0 sc1
	global_store_dwordx4 v[66:67], v[74:77], off offset:16 sc0 sc1
	s_waitcnt lgkmcnt(0)
	v_add_f32_e32 v66, v69, v78
	ds_bpermute_b32 v67, v118, v66
	v_cvt_pk_bf16_f32 v68, v70, v71
	v_cvt_pk_bf16_f32 v69, v72, v73
	v_cvt_pk_bf16_f32 v70, v74, v75
	v_cvt_pk_bf16_f32 v71, v76, v77
	global_store_dwordx4 v[86:87], v[68:71], off offset:256 sc0 sc1
	s_and_saveexec_b64 s[50:51], s[38:39]
	s_cbranch_execz .LBB0_1586
	v_lshlrev_b64 v[68:69], 7, v[114:115]
	v_lshl_add_u64 v[68:69], s[6:7], 0, v[68:69]
	v_lshl_add_u64 v[68:69], s[48:49], 2, v[68:69]
	s_lshl_b32 s24, s58, 2
	v_lshl_add_u64 v[68:69], v[68:69], 0, s[24:25]
	s_waitcnt lgkmcnt(0)
	v_add_f32_e32 v66, v66, v67
	global_store_dword v[68:69], v66, off
.LBB0_1586:
	s_or_b64 exec, exec, s[50:51]
	v_add_u32_e32 v84, 0x80, v158
	v_ashrrev_i32_e32 v85, 31, v84
	s_waitcnt lgkmcnt(0)
	v_lshlrev_b64 v[66:67], 13, v[84:85]
	v_lshl_add_u64 v[66:67], v[160:161], 0, v[66:67]
	global_load_dwordx4 v[86:89], v[66:67], off offset:16
	global_load_dwordx4 v[90:93], v[66:67], off
	global_load_dwordx4 v[94:97], v[66:67], off offset:528
	global_load_dwordx4 v[98:101], v[66:67], off offset:512
	v_add_u32_e32 v82, 0x90, v158
	v_ashrrev_i32_e32 v83, 31, v82
	v_lshlrev_b64 v[66:67], 13, v[82:83]
	v_lshl_add_u64 v[70:71], v[160:161], 0, v[66:67]
	global_load_dwordx4 v[74:77], v[70:71], off offset:16
	global_load_dwordx4 v[78:81], v[70:71], off
	global_load_dwordx4 v[66:69], v[70:71], off offset:528
	s_nop 0
	global_load_dwordx4 v[70:73], v[70:71], off offset:512
	v_lshlrev_b64 v[102:103], 11, v[84:85]
	v_lshl_add_u64 v[102:103], v[102:103], 0, v[156:157]
	s_waitcnt vmcnt(7)
	v_pk_add_f32 v[58:59], v[58:59], v[86:87]
	s_waitcnt vmcnt(6)
	v_pk_add_f32 v[62:63], v[62:63], v[90:91]
	v_lshlrev_b64 v[90:91], 2, v[102:103]
	v_pk_add_f32 v[64:65], v[64:65], v[92:93]
	v_lshl_add_u64 v[86:87], s[20:21], 0, v[90:91]
	v_pk_add_f32 v[60:61], v[60:61], v[88:89]
	global_store_dwordx4 v[86:87], v[62:65], off sc0 sc1
	global_store_dwordx4 v[86:87], v[58:61], off offset:16 sc0 sc1
	v_cvt_pk_bf16_f32 v86, v62, v63
	v_cvt_pk_bf16_f32 v87, v64, v65
	v_cvt_pk_bf16_f32 v88, v58, v59
	v_or_b32_e32 v90, 0x200, v90
	v_mul_f32_e32 v63, v63, v63
	v_mul_f32_e32 v58, v58, v58
	v_fmac_f32_e32 v63, v62, v62
	v_mul_f32_e32 v62, v64, v64
	v_fmac_f32_e32 v58, v59, v59
	v_mul_f32_e32 v59, v60, v60
	v_fmac_f32_e32 v62, v65, v65
	v_fmac_f32_e32 v59, v61, v61
	v_add_f32_e32 v62, v63, v62
	v_add_f32_e32 v58, v59, v58
	v_lshl_add_u64 v[92:93], v[102:103], 1, s[4:5]
	v_add_f32_e32 v62, v62, v58
	s_waitcnt vmcnt(6)
	v_pk_add_f32 v[56:57], v[56:57], v[100:101]
	v_pk_add_f32 v[54:55], v[54:55], v[98:99]
	v_pk_add_f32 v[50:51], v[50:51], v[94:95]
	v_lshl_add_u64 v[58:59], s[20:21], 0, v[90:91]
	v_cvt_pk_bf16_f32 v89, v60, v61
	global_store_dwordx4 v[92:93], v[86:89], off sc0 sc1
	v_pk_add_f32 v[52:53], v[52:53], v[96:97]
	global_store_dwordx4 v[58:59], v[54:57], off sc0 sc1
	global_store_dwordx4 v[58:59], v[50:53], off offset:16 sc0 sc1
	v_cvt_pk_bf16_f32 v58, v54, v55
	v_cvt_pk_bf16_f32 v59, v56, v57
	v_cvt_pk_bf16_f32 v60, v50, v51
	v_cvt_pk_bf16_f32 v61, v52, v53
	s_nop 0
	v_mul_f32_e32 v55, v55, v55
	v_mul_f32_e32 v50, v50, v50
	v_fmac_f32_e32 v55, v54, v54
	v_mul_f32_e32 v54, v56, v56
	v_fmac_f32_e32 v50, v51, v51
	v_mul_f32_e32 v51, v52, v52
	v_fmac_f32_e32 v54, v57, v57
	v_fmac_f32_e32 v51, v53, v53
	v_add_f32_e32 v54, v55, v54
	v_add_f32_e32 v50, v51, v50
	v_add_f32_e32 v50, v54, v50
	v_add_f32_e32 v50, v62, v50
	ds_bpermute_b32 v51, v168, v50
	global_store_dwordx4 v[92:93], v[58:61], off offset:256 sc0 sc1
	s_waitcnt lgkmcnt(0)
	v_add_f32_e32 v50, v50, v51
	ds_bpermute_b32 v51, v118, v50
	s_and_saveexec_b64 s[50:51], s[38:39]
	s_cbranch_execz .LBB0_1588
	v_lshlrev_b64 v[52:53], 7, v[84:85]
	v_lshl_add_u64 v[52:53], s[6:7], 0, v[52:53]
	v_lshl_add_u64 v[52:53], s[48:49], 2, v[52:53]
	s_lshl_b32 s24, s58, 2
	v_lshl_add_u64 v[52:53], v[52:53], 0, s[24:25]
	s_waitcnt lgkmcnt(0)
	v_add_f32_e32 v50, v50, v51
	global_store_dword v[52:53], v50, off
.LBB0_1588:
	s_or_b64 exec, exec, s[50:51]
	s_waitcnt lgkmcnt(0)
	v_lshlrev_b64 v[50:51], 11, v[82:83]
	v_lshl_add_u64 v[54:55], v[50:51], 0, v[156:157]
	v_lshlrev_b64 v[56:57], 2, v[54:55]
	s_waitcnt vmcnt(8)
	v_pk_add_f32 v[48:49], v[48:49], v[80:81]
	v_pk_add_f32 v[46:47], v[46:47], v[78:79]
	v_pk_add_f32 v[42:43], v[42:43], v[74:75]
	v_lshl_add_u64 v[50:51], s[20:21], 0, v[56:57]
	v_pk_add_f32 v[44:45], v[44:45], v[76:77]
	global_store_dwordx4 v[50:51], v[46:49], off sc0 sc1
	global_store_dwordx4 v[50:51], v[42:45], off offset:16 sc0 sc1
	v_cvt_pk_bf16_f32 v50, v46, v47
	v_cvt_pk_bf16_f32 v51, v48, v49
	v_cvt_pk_bf16_f32 v52, v42, v43
	s_waitcnt vmcnt(8)
	v_pk_add_f32 v[40:41], v[40:41], v[72:73]
	v_mul_f32_e32 v47, v47, v47
	v_mul_f32_e32 v42, v42, v42
	v_fmac_f32_e32 v47, v46, v46
	v_mul_f32_e32 v46, v48, v48
	v_fmac_f32_e32 v42, v43, v43
	v_mul_f32_e32 v43, v44, v44
	v_fmac_f32_e32 v46, v49, v49
	v_fmac_f32_e32 v43, v45, v45
	v_add_f32_e32 v46, v47, v46
	v_add_f32_e32 v42, v43, v42
	v_pk_add_f32 v[38:39], v[38:39], v[70:71]
	v_add_f32_e32 v46, v46, v42
	v_pk_add_f32 v[42:43], v[34:35], v[66:67]
	v_mul_f32_e32 v34, v39, v39
	v_mul_f32_e32 v35, v40, v40
	v_cvt_pk_bf16_f32 v53, v44, v45
	v_pk_add_f32 v[44:45], v[36:37], v[68:69]
	v_fmac_f32_e32 v34, v38, v38
	v_fmac_f32_e32 v35, v41, v41
	v_add_f32_e32 v34, v34, v35
	v_mul_f32_e32 v35, v42, v42
	v_mul_f32_e32 v36, v44, v44
	v_fmac_f32_e32 v35, v43, v43
	v_fmac_f32_e32 v36, v45, v45
	v_add_f32_e32 v35, v36, v35
	v_add_f32_e32 v34, v34, v35
	v_add_f32_e32 v37, v46, v34
	ds_bpermute_b32 v46, v168, v37
	v_or_b32_e32 v56, 0x200, v56
	v_lshl_add_u64 v[54:55], v[54:55], 1, s[4:5]
	v_lshl_add_u64 v[34:35], s[20:21], 0, v[56:57]
	global_store_dwordx4 v[54:55], v[50:53], off sc0 sc1
	global_store_dwordx4 v[34:35], v[38:41], off sc0 sc1
	global_store_dwordx4 v[34:35], v[42:45], off offset:16 sc0 sc1
	s_waitcnt lgkmcnt(0)
	v_add_f32_e32 v34, v37, v46
	ds_bpermute_b32 v35, v118, v34
	v_cvt_pk_bf16_f32 v36, v38, v39
	v_cvt_pk_bf16_f32 v37, v40, v41
	v_cvt_pk_bf16_f32 v38, v42, v43
	v_cvt_pk_bf16_f32 v39, v44, v45
	global_store_dwordx4 v[54:55], v[36:39], off offset:256 sc0 sc1
	s_and_saveexec_b64 s[50:51], s[38:39]
	s_cbranch_execz .LBB0_1590
	v_lshlrev_b64 v[36:37], 7, v[82:83]
	v_lshl_add_u64 v[36:37], s[6:7], 0, v[36:37]
	v_lshl_add_u64 v[36:37], s[48:49], 2, v[36:37]
	s_lshl_b32 s24, s58, 2
	v_lshl_add_u64 v[36:37], v[36:37], 0, s[24:25]
	s_waitcnt lgkmcnt(0)
	v_add_f32_e32 v34, v34, v35
	global_store_dword v[36:37], v34, off
.LBB0_1590:
	s_or_b64 exec, exec, s[50:51]
	v_add_u32_e32 v52, 0xa0, v158
	v_ashrrev_i32_e32 v53, 31, v52
	s_waitcnt lgkmcnt(0)
	v_lshlrev_b64 v[34:35], 13, v[52:53]
	v_lshl_add_u64 v[34:35], v[160:161], 0, v[34:35]
	global_load_dwordx4 v[54:57], v[34:35], off offset:16
	global_load_dwordx4 v[58:61], v[34:35], off
	global_load_dwordx4 v[62:65], v[34:35], off offset:528
	global_load_dwordx4 v[66:69], v[34:35], off offset:512
	v_add_u32_e32 v50, 0xb0, v158
	v_ashrrev_i32_e32 v51, 31, v50
	v_lshlrev_b64 v[34:35], 13, v[50:51]
	v_lshl_add_u64 v[38:39], v[160:161], 0, v[34:35]
	global_load_dwordx4 v[42:45], v[38:39], off offset:16
	global_load_dwordx4 v[46:49], v[38:39], off
	global_load_dwordx4 v[34:37], v[38:39], off offset:528
	s_nop 0
	global_load_dwordx4 v[38:41], v[38:39], off offset:512
	v_lshlrev_b64 v[70:71], 11, v[52:53]
	v_lshl_add_u64 v[70:71], v[70:71], 0, v[156:157]
	s_waitcnt vmcnt(7)
	v_pk_add_f32 v[26:27], v[26:27], v[54:55]
	s_waitcnt vmcnt(6)
	v_pk_add_f32 v[30:31], v[30:31], v[58:59]
	v_lshlrev_b64 v[58:59], 2, v[70:71]
	v_pk_add_f32 v[32:33], v[32:33], v[60:61]
	v_lshl_add_u64 v[54:55], s[20:21], 0, v[58:59]
	v_pk_add_f32 v[28:29], v[28:29], v[56:57]
	global_store_dwordx4 v[54:55], v[30:33], off sc0 sc1
	global_store_dwordx4 v[54:55], v[26:29], off offset:16 sc0 sc1
	v_cvt_pk_bf16_f32 v54, v30, v31
	v_cvt_pk_bf16_f32 v55, v32, v33
	v_cvt_pk_bf16_f32 v56, v26, v27
	v_or_b32_e32 v58, 0x200, v58
	v_mul_f32_e32 v31, v31, v31
	v_mul_f32_e32 v26, v26, v26
	v_fmac_f32_e32 v31, v30, v30
	v_mul_f32_e32 v30, v32, v32
	v_fmac_f32_e32 v26, v27, v27
	v_mul_f32_e32 v27, v28, v28
	v_fmac_f32_e32 v30, v33, v33
	v_fmac_f32_e32 v27, v29, v29
	v_add_f32_e32 v30, v31, v30
	v_add_f32_e32 v26, v27, v26
	v_lshl_add_u64 v[60:61], v[70:71], 1, s[4:5]
	v_add_f32_e32 v30, v30, v26
	s_waitcnt vmcnt(6)
	v_pk_add_f32 v[24:25], v[24:25], v[68:69]
	v_pk_add_f32 v[22:23], v[22:23], v[66:67]
	v_pk_add_f32 v[18:19], v[18:19], v[62:63]
	v_lshl_add_u64 v[26:27], s[20:21], 0, v[58:59]
	v_cvt_pk_bf16_f32 v57, v28, v29
	global_store_dwordx4 v[60:61], v[54:57], off sc0 sc1
	v_pk_add_f32 v[20:21], v[20:21], v[64:65]
	global_store_dwordx4 v[26:27], v[22:25], off sc0 sc1
	global_store_dwordx4 v[26:27], v[18:21], off offset:16 sc0 sc1
	v_cvt_pk_bf16_f32 v26, v22, v23
	v_cvt_pk_bf16_f32 v27, v24, v25
	v_cvt_pk_bf16_f32 v28, v18, v19
	v_cvt_pk_bf16_f32 v29, v20, v21
	s_nop 0
	v_mul_f32_e32 v23, v23, v23
	v_mul_f32_e32 v18, v18, v18
	v_fmac_f32_e32 v23, v22, v22
	v_mul_f32_e32 v22, v24, v24
	v_fmac_f32_e32 v18, v19, v19
	v_mul_f32_e32 v19, v20, v20
	v_fmac_f32_e32 v22, v25, v25
	v_fmac_f32_e32 v19, v21, v21
	v_add_f32_e32 v22, v23, v22
	v_add_f32_e32 v18, v19, v18
	v_add_f32_e32 v18, v22, v18
	v_add_f32_e32 v18, v30, v18
	ds_bpermute_b32 v19, v168, v18
	global_store_dwordx4 v[60:61], v[26:29], off offset:256 sc0 sc1
	s_waitcnt lgkmcnt(0)
	v_add_f32_e32 v18, v18, v19
	ds_bpermute_b32 v19, v118, v18
	s_and_saveexec_b64 s[50:51], s[38:39]
	s_cbranch_execz .LBB0_1592
	v_lshlrev_b64 v[20:21], 7, v[52:53]
	v_lshl_add_u64 v[20:21], s[6:7], 0, v[20:21]
	v_lshl_add_u64 v[20:21], s[48:49], 2, v[20:21]
	s_lshl_b32 s24, s58, 2
	v_lshl_add_u64 v[20:21], v[20:21], 0, s[24:25]
	s_waitcnt lgkmcnt(0)
	v_add_f32_e32 v18, v18, v19
	global_store_dword v[20:21], v18, off
.LBB0_1592:
	s_or_b64 exec, exec, s[50:51]
	s_waitcnt lgkmcnt(0)
	v_lshlrev_b64 v[18:19], 11, v[50:51]
	v_lshl_add_u64 v[22:23], v[18:19], 0, v[156:157]
	v_lshlrev_b64 v[24:25], 2, v[22:23]
	s_waitcnt vmcnt(8)
	v_pk_add_f32 v[16:17], v[16:17], v[48:49]
	v_pk_add_f32 v[14:15], v[14:15], v[46:47]
	v_pk_add_f32 v[10:11], v[10:11], v[42:43]
	v_lshl_add_u64 v[18:19], s[20:21], 0, v[24:25]
	v_pk_add_f32 v[12:13], v[12:13], v[44:45]
	global_store_dwordx4 v[18:19], v[14:17], off sc0 sc1
	global_store_dwordx4 v[18:19], v[10:13], off offset:16 sc0 sc1
	v_cvt_pk_bf16_f32 v18, v14, v15
	v_cvt_pk_bf16_f32 v19, v16, v17
	v_cvt_pk_bf16_f32 v20, v10, v11
	s_waitcnt vmcnt(8)
	v_pk_add_f32 v[8:9], v[8:9], v[40:41]
	v_mul_f32_e32 v15, v15, v15
	v_mul_f32_e32 v10, v10, v10
	v_fmac_f32_e32 v15, v14, v14
	v_mul_f32_e32 v14, v16, v16
	v_fmac_f32_e32 v10, v11, v11
	v_mul_f32_e32 v11, v12, v12
	v_fmac_f32_e32 v14, v17, v17
	v_fmac_f32_e32 v11, v13, v13
	v_add_f32_e32 v14, v15, v14
	v_add_f32_e32 v10, v11, v10
	v_pk_add_f32 v[6:7], v[6:7], v[38:39]
	v_add_f32_e32 v14, v14, v10
	v_pk_add_f32 v[10:11], v[2:3], v[34:35]
	v_mul_f32_e32 v2, v7, v7
	v_mul_f32_e32 v3, v8, v8
	v_cvt_pk_bf16_f32 v21, v12, v13
	v_pk_add_f32 v[12:13], v[4:5], v[36:37]
	v_fmac_f32_e32 v2, v6, v6
	v_fmac_f32_e32 v3, v9, v9
	v_add_f32_e32 v2, v2, v3
	v_mul_f32_e32 v3, v10, v10
	v_mul_f32_e32 v4, v12, v12
	v_fmac_f32_e32 v3, v11, v11
	v_fmac_f32_e32 v4, v13, v13
	v_add_f32_e32 v3, v4, v3
	v_add_f32_e32 v2, v2, v3
	v_add_f32_e32 v5, v14, v2
	ds_bpermute_b32 v14, v168, v5
	v_or_b32_e32 v24, 0x200, v24
	v_lshl_add_u64 v[22:23], v[22:23], 1, s[4:5]
	v_lshl_add_u64 v[2:3], s[20:21], 0, v[24:25]
	global_store_dwordx4 v[22:23], v[18:21], off sc0 sc1
	global_store_dwordx4 v[2:3], v[6:9], off sc0 sc1
	global_store_dwordx4 v[2:3], v[10:13], off offset:16 sc0 sc1
	s_waitcnt lgkmcnt(0)
	v_add_f32_e32 v2, v5, v14
	ds_bpermute_b32 v3, v118, v2
	v_cvt_pk_bf16_f32 v4, v6, v7
	v_cvt_pk_bf16_f32 v5, v8, v9
	v_cvt_pk_bf16_f32 v6, v10, v11
	v_cvt_pk_bf16_f32 v7, v12, v13
	global_store_dwordx4 v[22:23], v[4:7], off offset:256 sc0 sc1
	s_and_saveexec_b64 s[50:51], s[38:39]
	s_cbranch_execz .LBB0_1594
	v_lshlrev_b64 v[4:5], 7, v[50:51]
	v_lshl_add_u64 v[4:5], s[6:7], 0, v[4:5]
	v_lshl_add_u64 v[4:5], s[48:49], 2, v[4:5]
	s_lshl_b32 s24, s58, 2
	v_lshl_add_u64 v[4:5], v[4:5], 0, s[24:25]
	s_waitcnt lgkmcnt(0)
	v_add_f32_e32 v2, v2, v3
	global_store_dword v[4:5], v2, off

.LBB0_1670:
	v_cmp_lt_i32_e32 vcc, v232, v227
	v_lshl_add_u32 v150, s57, 8, v153
	v_ashrrev_i32_e32 v151, 31, v150
	v_cndmask_b32_e32 v130, v226, v232, vcc
	v_cmp_lt_i32_e32 vcc, v233, v227
	v_lshlrev_b32_e32 v175, 2, v130
	s_mov_b32 s0, 0x358637bd
	v_cndmask_b32_e32 v130, v226, v233, vcc
	v_lshlrev_b32_e32 v171, 2, v130
	v_lshlrev_b64 v[130:131], 7, v[150:151]
	v_lshl_add_u64 v[134:135], v[144:145], 0, v[130:131]
	global_load_dwordx4 v[130:133], v[134:135], off
	s_nop 0
	global_load_dwordx4 v[134:137], v[134:135], off offset:16
	v_mov_b64_e32 v[164:165], s[0:1]
	s_mov_b32 s46, 0x3a000000
	s_movk_i32 s63, 0x5000
	s_waitcnt vmcnt(0)
	v_mov_b32_e32 v154, v130
	v_mov_b32_e32 v155, v134
	v_mov_b32_e32 v134, v131
	v_pk_add_f32 v[130:131], v[154:155], v[134:135]
	v_mov_b32_e32 v134, v132
	v_mov_b32_e32 v135, v136
	v_mov_b32_e32 v136, v133
	v_or_b32_e32 v154, 16, v150
	v_pk_add_f32 v[132:133], v[134:135], v[136:137]
	v_ashrrev_i32_e32 v155, 31, v154
	v_pk_add_f32 v[160:161], v[130:131], v[132:133]
	v_lshlrev_b64 v[130:131], 7, v[154:155]
	v_lshl_add_u64 v[134:135], v[144:145], 0, v[130:131]
	global_load_dwordx4 v[130:133], v[134:135], off
	s_nop 0
	global_load_dwordx4 v[134:137], v[134:135], off offset:16
	s_waitcnt vmcnt(1)
	v_mov_b32_e32 v162, v130
	s_waitcnt vmcnt(0)
	v_mov_b32_e32 v163, v134
	v_mov_b32_e32 v134, v131
	v_pk_add_f32 v[130:131], v[162:163], v[134:135]
	v_mov_b32_e32 v134, v132
	v_mov_b32_e32 v135, v136
	v_mov_b32_e32 v136, v133
	v_pk_add_f32 v[132:133], v[134:135], v[136:137]
	v_or_b32_e32 v162, 32, v150
	v_pk_add_f32 v[130:131], v[130:131], v[132:133]
	v_mov_b32_e32 v133, v160
	v_mov_b32_e32 v132, v130
	v_mov_b32_e32 v160, v131
	v_pk_add_f32 v[130:131], v[132:133], v[160:161]
	ds_bpermute_b32 v133, v175, v131
	ds_bpermute_b32 v132, v175, v130
	v_ashrrev_i32_e32 v163, 31, v162
	s_waitcnt lgkmcnt(0)
	v_pk_add_f32 v[130:131], v[130:131], v[132:133]
	ds_bpermute_b32 v133, v171, v131
	ds_bpermute_b32 v132, v171, v130
	s_waitcnt lgkmcnt(0)
	v_pk_add_f32 v[130:131], v[130:131], v[132:133]
	s_nop 0
	v_pk_fma_f32 v[130:131], v[130:131], s[46:47], v[164:165] op_sel_hi:[1,0,0]
	s_nop 0
	v_mul_f32_e32 v132, 0x4b800000, v131
	v_cmp_gt_f32_e64 s[0:1], s67, v131
	v_cmp_gt_f32_e32 vcc, s67, v130
	s_nop 0
	v_cndmask_b32_e64 v131, v131, v132, s[0:1]
	v_rsq_f32_e32 v131, v131
	s_nop 0
	v_mul_f32_e32 v132, 0x45800000, v131
	v_cndmask_b32_e64 v156, v131, v132, s[0:1]
	v_mul_f32_e32 v131, 0x4b800000, v130
	v_cndmask_b32_e32 v130, v130, v131, vcc
	v_rsq_f32_e32 v130, v130
	v_pk_mul_f32 v[122:123], v[122:123], v[156:157] op_sel_hi:[1,0]
	v_pk_mul_f32 v[126:127], v[126:127], v[156:157] op_sel_hi:[1,0]
	v_pk_mul_f32 v[124:125], v[124:125], v[156:157] op_sel_hi:[1,0]
	v_mul_f32_e32 v131, 0x45800000, v130
	v_cndmask_b32_e32 v152, v130, v131, vcc
	v_lshlrev_b64 v[130:131], 7, v[162:163]
	v_lshl_add_u64 v[134:135], v[144:145], 0, v[130:131]
	global_load_dwordx4 v[130:133], v[134:135], off
	s_nop 0
	global_load_dwordx4 v[134:137], v[134:135], off offset:16
	v_max_f32_e32 v122, 0, v122
	v_pk_mul_f32 v[128:129], v[128:129], v[156:157] op_sel_hi:[1,0]
	v_max_f32_e32 v123, 0, v123
	v_max_f32_e32 v124, 0, v124
	v_max_f32_e32 v126, 0, v126
	v_max_f32_e32 v125, 0, v125
	v_pk_mul_f32 v[116:117], v[116:117], v[156:157] op_sel_hi:[1,0]
	v_pk_mul_f32 v[114:115], v[114:115], v[156:157] op_sel_hi:[1,0]
	v_mul_f32_e32 v126, v126, v126
	v_mul_f32_e32 v125, v125, v125
	v_pk_mul_f32 v[120:121], v[120:121], v[156:157] op_sel_hi:[1,0]
	v_pk_mul_f32 v[118:119], v[118:119], v[156:157] op_sel_hi:[1,0]
	v_max_f32_e32 v114, 0, v114
	v_max_f32_e32 v115, 0, v115
	v_max_f32_e32 v116, 0, v116
	v_max_f32_e32 v118, 0, v118
	v_max_f32_e32 v117, 0, v117
	v_pk_mul_f32 v[106:107], v[106:107], v[152:153] op_sel_hi:[1,0]
	v_mul_f32_e32 v118, v118, v118
	v_mul_f32_e32 v117, v117, v117
	v_pk_mul_f32 v[110:111], v[110:111], v[152:153] op_sel_hi:[1,0]
	v_pk_mul_f32 v[108:109], v[108:109], v[152:153] op_sel_hi:[1,0]
	v_max_f32_e32 v106, 0, v106
	v_pk_mul_f32 v[112:113], v[112:113], v[152:153] op_sel_hi:[1,0]
	v_max_f32_e32 v107, 0, v107
	v_max_f32_e32 v108, 0, v108
	v_max_f32_e32 v110, 0, v110
	v_max_f32_e32 v109, 0, v109
	v_pk_mul_f32 v[100:101], v[100:101], v[152:153] op_sel_hi:[1,0]
	v_pk_mul_f32 v[98:99], v[98:99], v[152:153] op_sel_hi:[1,0]
	v_mul_f32_e32 v110, v110, v110
	v_mul_f32_e32 v109, v109, v109
	v_pk_mul_f32 v[104:105], v[104:105], v[152:153] op_sel_hi:[1,0]
	v_pk_mul_f32 v[102:103], v[102:103], v[152:153] op_sel_hi:[1,0]
	v_max_f32_e32 v98, 0, v98
	v_max_f32_e32 v99, 0, v99
	v_max_f32_e32 v100, 0, v100
	v_max_f32_e32 v102, 0, v102
	v_max_f32_e32 v101, 0, v101
	v_mul_f32_e32 v102, v102, v102
	v_mul_f32_e32 v101, v101, v101
	s_waitcnt vmcnt(1)
	v_mov_b32_e32 v160, v130
	s_waitcnt vmcnt(0)
	v_mov_b32_e32 v161, v134
	v_mov_b32_e32 v134, v131
	v_pk_add_f32 v[130:131], v[160:161], v[134:135]
	v_mov_b32_e32 v134, v132
	v_mov_b32_e32 v135, v136
	v_mov_b32_e32 v136, v133
	v_or_b32_e32 v160, 48, v150
	v_pk_add_f32 v[132:133], v[134:135], v[136:137]
	v_ashrrev_i32_e32 v161, 31, v160
	v_pk_add_f32 v[168:169], v[130:131], v[132:133]
	v_lshlrev_b64 v[130:131], 7, v[160:161]
	v_lshl_add_u64 v[134:135], v[144:145], 0, v[130:131]
	global_load_dwordx4 v[130:133], v[134:135], off
	s_nop 0
	global_load_dwordx4 v[134:137], v[134:135], off offset:16
	s_waitcnt vmcnt(1)
	v_mov_b32_e32 v172, v130
	s_waitcnt vmcnt(0)
	v_mov_b32_e32 v173, v134
	v_mov_b32_e32 v134, v131
	v_pk_add_f32 v[130:131], v[172:173], v[134:135]
	v_mov_b32_e32 v134, v132
	v_mov_b32_e32 v135, v136
	v_mov_b32_e32 v136, v133
	v_pk_add_f32 v[132:133], v[134:135], v[136:137]
	s_nop 0
	v_pk_add_f32 v[130:131], v[130:131], v[132:133]
	v_mov_b32_e32 v133, v168
	v_mov_b32_e32 v132, v130
	v_mov_b32_e32 v168, v131
	v_pk_add_f32 v[130:131], v[132:133], v[168:169]
	ds_bpermute_b32 v133, v175, v131
	ds_bpermute_b32 v132, v175, v130
	v_add_u32_e32 v168, 0x80, v150
	v_ashrrev_i32_e32 v169, 31, v168
	s_waitcnt lgkmcnt(0)
	v_pk_add_f32 v[130:131], v[130:131], v[132:133]
	ds_bpermute_b32 v133, v171, v131
	ds_bpermute_b32 v132, v171, v130
	s_waitcnt lgkmcnt(0)
	v_pk_add_f32 v[130:131], v[130:131], v[132:133]
	s_nop 0
	v_pk_fma_f32 v[130:131], v[130:131], s[46:47], v[164:165] op_sel_hi:[1,0,0]
	s_nop 0
	v_mul_f32_e32 v132, 0x4b800000, v131
	v_cmp_gt_f32_e64 s[0:1], s67, v131
	v_cmp_gt_f32_e32 vcc, s67, v130
	s_nop 0
	v_cndmask_b32_e64 v131, v131, v132, s[0:1]
	v_rsq_f32_e32 v131, v131
	s_nop 0
	v_mul_f32_e32 v132, 0x45800000, v131
	v_cndmask_b32_e64 v166, v131, v132, s[0:1]
	v_mul_f32_e32 v131, 0x4b800000, v130
	v_cndmask_b32_e32 v130, v130, v131, vcc
	v_rsq_f32_e32 v130, v130
	v_pk_mul_f32 v[90:91], v[90:91], v[166:167] op_sel_hi:[1,0]
	v_pk_mul_f32 v[94:95], v[94:95], v[166:167] op_sel_hi:[1,0]
	v_pk_mul_f32 v[92:93], v[92:93], v[166:167] op_sel_hi:[1,0]
	v_mul_f32_e32 v131, 0x45800000, v130
	v_cndmask_b32_e32 v158, v130, v131, vcc
	v_lshlrev_b64 v[130:131], 7, v[168:169]
	v_lshl_add_u64 v[134:135], v[144:145], 0, v[130:131]
	global_load_dwordx4 v[130:133], v[134:135], off
	s_nop 0
	global_load_dwordx4 v[134:137], v[134:135], off offset:16
	v_max_f32_e32 v90, 0, v90
	v_pk_mul_f32 v[96:97], v[96:97], v[166:167] op_sel_hi:[1,0]
	v_max_f32_e32 v91, 0, v91
	v_max_f32_e32 v92, 0, v92
	v_max_f32_e32 v94, 0, v94
	v_max_f32_e32 v93, 0, v93
	v_pk_mul_f32 v[84:85], v[84:85], v[166:167] op_sel_hi:[1,0]
	v_pk_mul_f32 v[82:83], v[82:83], v[166:167] op_sel_hi:[1,0]
	v_mul_f32_e32 v94, v94, v94
	v_mul_f32_e32 v93, v93, v93
	v_pk_mul_f32 v[88:89], v[88:89], v[166:167] op_sel_hi:[1,0]
	v_pk_mul_f32 v[86:87], v[86:87], v[166:167] op_sel_hi:[1,0]
	v_max_f32_e32 v82, 0, v82
	v_max_f32_e32 v83, 0, v83
	v_max_f32_e32 v84, 0, v84
	v_max_f32_e32 v86, 0, v86
	v_max_f32_e32 v85, 0, v85
	v_pk_mul_f32 v[74:75], v[74:75], v[158:159] op_sel_hi:[1,0]
	v_mul_f32_e32 v86, v86, v86
	v_mul_f32_e32 v85, v85, v85
	v_pk_mul_f32 v[78:79], v[78:79], v[158:159] op_sel_hi:[1,0]
	v_pk_mul_f32 v[76:77], v[76:77], v[158:159] op_sel_hi:[1,0]
	v_max_f32_e32 v74, 0, v74
	v_pk_mul_f32 v[80:81], v[80:81], v[158:159] op_sel_hi:[1,0]
	v_max_f32_e32 v75, 0, v75
	v_max_f32_e32 v76, 0, v76
	v_max_f32_e32 v78, 0, v78
	v_max_f32_e32 v77, 0, v77
	v_pk_mul_f32 v[68:69], v[68:69], v[158:159] op_sel_hi:[1,0]
	v_pk_mul_f32 v[66:67], v[66:67], v[158:159] op_sel_hi:[1,0]
	v_mul_f32_e32 v78, v78, v78
	v_mul_f32_e32 v77, v77, v77
	v_pk_mul_f32 v[72:73], v[72:73], v[158:159] op_sel_hi:[1,0]
	v_pk_mul_f32 v[70:71], v[70:71], v[158:159] op_sel_hi:[1,0]
	v_max_f32_e32 v66, 0, v66
	v_max_f32_e32 v67, 0, v67
	v_max_f32_e32 v68, 0, v68
	v_max_f32_e32 v70, 0, v70
	v_max_f32_e32 v69, 0, v69
	v_mul_f32_e32 v70, v70, v70
	v_mul_f32_e32 v69, v69, v69
	s_waitcnt vmcnt(1)
	v_mov_b32_e32 v172, v130
	s_waitcnt vmcnt(0)
	v_mov_b32_e32 v173, v134
	v_mov_b32_e32 v134, v131
	v_pk_add_f32 v[130:131], v[172:173], v[134:135]
	v_mov_b32_e32 v134, v132
	v_mov_b32_e32 v135, v136
	v_mov_b32_e32 v136, v133
	v_add_u32_e32 v172, 0x90, v150
	v_pk_add_f32 v[132:133], v[134:135], v[136:137]
	v_ashrrev_i32_e32 v173, 31, v172
	v_pk_add_f32 v[176:177], v[130:131], v[132:133]
	v_lshlrev_b64 v[130:131], 7, v[172:173]
	v_lshl_add_u64 v[134:135], v[144:145], 0, v[130:131]
	global_load_dwordx4 v[130:133], v[134:135], off
	s_nop 0
	global_load_dwordx4 v[134:137], v[134:135], off offset:16
	s_waitcnt vmcnt(1)
	v_mov_b32_e32 v178, v130
	s_waitcnt vmcnt(0)
	v_mov_b32_e32 v179, v134
	v_mov_b32_e32 v134, v131
	v_pk_add_f32 v[130:131], v[178:179], v[134:135]
	v_mov_b32_e32 v134, v132
	v_mov_b32_e32 v135, v136
	v_mov_b32_e32 v136, v133
	v_pk_add_f32 v[132:133], v[134:135], v[136:137]
	s_nop 0
	v_pk_add_f32 v[130:131], v[130:131], v[132:133]
	v_mov_b32_e32 v133, v176
	v_mov_b32_e32 v132, v130
	v_mov_b32_e32 v176, v131
	v_pk_add_f32 v[130:131], v[132:133], v[176:177]
	ds_bpermute_b32 v133, v175, v131
	ds_bpermute_b32 v132, v175, v130
	v_add_u32_e32 v176, 0xa0, v150
	v_ashrrev_i32_e32 v177, 31, v176
	s_waitcnt lgkmcnt(0)
	v_pk_add_f32 v[130:131], v[130:131], v[132:133]
	ds_bpermute_b32 v133, v171, v131
	ds_bpermute_b32 v132, v171, v130
	s_waitcnt lgkmcnt(0)
	v_pk_add_f32 v[130:131], v[130:131], v[132:133]
	s_nop 0
	v_pk_fma_f32 v[130:131], v[130:131], s[46:47], v[164:165] op_sel_hi:[1,0,0]
	s_nop 0
	v_mul_f32_e32 v132, 0x4b800000, v131
	v_cmp_gt_f32_e64 s[0:1], s67, v131
	v_cmp_gt_f32_e32 vcc, s67, v130
	s_nop 0
	v_cndmask_b32_e64 v131, v131, v132, s[0:1]
	v_rsq_f32_e32 v131, v131
	s_nop 0
	v_mul_f32_e32 v132, 0x45800000, v131
	v_cndmask_b32_e64 v174, v131, v132, s[0:1]
	v_mul_f32_e32 v131, 0x4b800000, v130
	v_cndmask_b32_e32 v130, v130, v131, vcc
	v_rsq_f32_e32 v130, v130
	v_pk_mul_f32 v[58:59], v[58:59], v[174:175] op_sel_hi:[1,0]
	v_pk_mul_f32 v[62:63], v[62:63], v[174:175] op_sel_hi:[1,0]
	v_pk_mul_f32 v[60:61], v[60:61], v[174:175] op_sel_hi:[1,0]
	v_mul_f32_e32 v131, 0x45800000, v130
	v_cndmask_b32_e32 v170, v130, v131, vcc
	v_lshlrev_b64 v[130:131], 7, v[176:177]
	v_lshl_add_u64 v[134:135], v[144:145], 0, v[130:131]
	global_load_dwordx4 v[130:133], v[134:135], off
	s_nop 0
	global_load_dwordx4 v[134:137], v[134:135], off offset:16
	v_max_f32_e32 v58, 0, v58
	v_pk_mul_f32 v[64:65], v[64:65], v[174:175] op_sel_hi:[1,0]
	v_max_f32_e32 v59, 0, v59
	v_max_f32_e32 v60, 0, v60
	v_max_f32_e32 v62, 0, v62
	v_max_f32_e32 v61, 0, v61
	v_pk_mul_f32 v[52:53], v[52:53], v[174:175] op_sel_hi:[1,0]
	v_pk_mul_f32 v[50:51], v[50:51], v[174:175] op_sel_hi:[1,0]
	v_mul_f32_e32 v62, v62, v62
	v_mul_f32_e32 v61, v61, v61
	v_pk_mul_f32 v[56:57], v[56:57], v[174:175] op_sel_hi:[1,0]
	v_pk_mul_f32 v[54:55], v[54:55], v[174:175] op_sel_hi:[1,0]
	v_max_f32_e32 v50, 0, v50
	v_max_f32_e32 v51, 0, v51
	v_max_f32_e32 v52, 0, v52
	v_max_f32_e32 v54, 0, v54
	v_max_f32_e32 v53, 0, v53
	v_pk_mul_f32 v[42:43], v[42:43], v[170:171] op_sel_hi:[1,0]
	v_mul_f32_e32 v54, v54, v54
	v_mul_f32_e32 v53, v53, v53
	v_pk_mul_f32 v[46:47], v[46:47], v[170:171] op_sel_hi:[1,0]
	v_pk_mul_f32 v[44:45], v[44:45], v[170:171] op_sel_hi:[1,0]
	v_max_f32_e32 v42, 0, v42
	v_pk_mul_f32 v[48:49], v[48:49], v[170:171] op_sel_hi:[1,0]
	v_max_f32_e32 v43, 0, v43
	v_max_f32_e32 v44, 0, v44
	v_max_f32_e32 v46, 0, v46
	v_max_f32_e32 v45, 0, v45
	v_pk_mul_f32 v[36:37], v[36:37], v[170:171] op_sel_hi:[1,0]
	v_pk_mul_f32 v[34:35], v[34:35], v[170:171] op_sel_hi:[1,0]
	v_mul_f32_e32 v46, v46, v46
	v_mul_f32_e32 v45, v45, v45
	v_pk_mul_f32 v[40:41], v[40:41], v[170:171] op_sel_hi:[1,0]
	v_pk_mul_f32 v[38:39], v[38:39], v[170:171] op_sel_hi:[1,0]
	v_max_f32_e32 v34, 0, v34
	v_max_f32_e32 v35, 0, v35
	v_max_f32_e32 v36, 0, v36
	v_max_f32_e32 v38, 0, v38
	v_max_f32_e32 v37, 0, v37
	v_mul_f32_e32 v38, v38, v38
	v_mul_f32_e32 v37, v37, v37
	s_waitcnt vmcnt(1)
	v_mov_b32_e32 v178, v130
	s_waitcnt vmcnt(0)
	v_mov_b32_e32 v179, v134
	v_mov_b32_e32 v134, v131
	v_pk_add_f32 v[130:131], v[178:179], v[134:135]
	v_mov_b32_e32 v134, v132
	v_mov_b32_e32 v135, v136
	v_mov_b32_e32 v136, v133
	v_add_u32_e32 v178, 0xb0, v150
	v_pk_add_f32 v[132:133], v[134:135], v[136:137]
	v_ashrrev_i32_e32 v179, 31, v178
	v_pk_add_f32 v[180:181], v[130:131], v[132:133]
	v_lshlrev_b64 v[130:131], 7, v[178:179]
	v_lshl_add_u64 v[130:131], v[144:145], 0, v[130:131]
	global_load_dwordx4 v[134:137], v[130:131], off
	s_nop 0
	global_load_dwordx4 v[130:133], v[130:131], off offset:16
	s_waitcnt vmcnt(1)
	v_mov_b32_e32 v182, v134
	s_waitcnt vmcnt(0)
	v_mov_b32_e32 v183, v130
	v_mov_b32_e32 v130, v135
	v_mov_b32_e32 v134, v136
	v_mov_b32_e32 v135, v132
	v_mov_b32_e32 v132, v137
	v_pk_add_f32 v[130:131], v[182:183], v[130:131]
	v_pk_add_f32 v[132:133], v[134:135], v[132:133]
	v_lshl_or_b32 v134, s56, 8, v159
	v_pk_add_f32 v[130:131], v[130:131], v[132:133]
	v_mov_b32_e32 v133, v180
	v_mov_b32_e32 v132, v130
	v_mov_b32_e32 v180, v131
	v_pk_add_f32 v[130:131], v[132:133], v[180:181]
	ds_bpermute_b32 v133, v175, v131
	ds_bpermute_b32 v132, v175, v130
	v_ashrrev_i32_e32 v135, 31, v134
	v_lshlrev_b64 v[136:137], 14, v[150:151]
	v_lshl_add_u64 v[136:137], s[28:29], 0, v[136:137]
	v_lshlrev_b64 v[134:135], 1, v[134:135]
	s_waitcnt lgkmcnt(0)
	v_pk_add_f32 v[130:131], v[130:131], v[132:133]
	ds_bpermute_b32 v133, v171, v131
	ds_bpermute_b32 v132, v171, v130
	v_lshl_add_u64 v[136:137], v[136:137], 0, v[134:135]
	s_waitcnt lgkmcnt(0)
	v_pk_add_f32 v[130:131], v[130:131], v[132:133]
	s_nop 0
	v_pk_fma_f32 v[130:131], v[130:131], s[46:47], v[164:165] op_sel_hi:[1,0,0]
	s_nop 0
	v_mul_f32_e32 v132, 0x4b800000, v131
	v_cmp_gt_f32_e64 s[0:1], s67, v131
	v_cmp_gt_f32_e32 vcc, s67, v130
	s_nop 0
	v_cndmask_b32_e64 v131, v131, v132, s[0:1]
	v_rsq_f32_e32 v131, v131
	s_nop 0
	v_mul_f32_e32 v132, 0x45800000, v131
	v_cndmask_b32_e64 v132, v131, v132, s[0:1]
	v_mul_f32_e32 v131, 0x4b800000, v130
	v_cndmask_b32_e32 v130, v130, v131, vcc
	v_rsq_f32_e32 v130, v130
	v_pk_mul_f32 v[26:27], v[26:27], v[132:133] op_sel_hi:[1,0]
	v_pk_mul_f32 v[30:31], v[30:31], v[132:133] op_sel_hi:[1,0]
	v_pk_mul_f32 v[28:29], v[28:29], v[132:133] op_sel_hi:[1,0]
	v_mul_f32_e32 v131, 0x45800000, v130
	v_cndmask_b32_e32 v130, v130, v131, vcc
	v_mul_f32_e32 v131, v122, v122
	v_max_f32_e32 v122, 0, v127
	v_mul_f32_e32 v122, v122, v122
	v_mul_f32_e32 v127, v123, v123
	v_max_f32_e32 v123, 0, v128
	v_mul_f32_e32 v128, v124, v124
	v_max_f32_e32 v124, 0, v129
	v_mul_f32_e32 v123, v123, v123
	v_mul_f32_e32 v124, v124, v124
	v_cvt_pk_bf16_f32 v122, v126, v122
	v_cvt_pk_bf16_f32 v123, v123, v124
	v_cvt_pk_bf16_f32 v124, v131, v127
	v_cvt_pk_bf16_f32 v125, v128, v125
	global_store_dwordx4 v[136:137], v[122:125], off sc0 sc1
	v_max_f32_e32 v26, 0, v26
	v_pk_mul_f32 v[32:33], v[32:33], v[132:133] op_sel_hi:[1,0]
	v_mul_f32_e32 v122, v114, v114
	v_max_f32_e32 v114, 0, v119
	v_mul_f32_e32 v119, v115, v115
	v_max_f32_e32 v115, 0, v120
	v_mul_f32_e32 v120, v116, v116
	v_max_f32_e32 v116, 0, v121
	v_mul_f32_e32 v114, v114, v114
	v_mul_f32_e32 v115, v115, v115
	v_mul_f32_e32 v116, v116, v116
	v_cvt_pk_bf16_f32 v114, v118, v114
	v_cvt_pk_bf16_f32 v115, v115, v116
	v_cvt_pk_bf16_f32 v116, v122, v119
	v_cvt_pk_bf16_f32 v117, v120, v117
	global_store_dwordx4 v[136:137], v[114:117], off offset:256 sc0 sc1
	v_max_f32_e32 v27, 0, v27
	v_max_f32_e32 v28, 0, v28
	v_lshlrev_b64 v[114:115], 14, v[154:155]
	v_mul_f32_e32 v116, v106, v106
	v_max_f32_e32 v106, 0, v111
	v_lshl_add_u64 v[114:115], s[28:29], 0, v[114:115]
	v_mul_f32_e32 v106, v106, v106
	v_mul_f32_e32 v111, v107, v107
	v_max_f32_e32 v107, 0, v112
	v_mul_f32_e32 v112, v108, v108
	v_max_f32_e32 v108, 0, v113
	v_lshl_add_u64 v[114:115], v[114:115], 0, v[134:135]
	v_mul_f32_e32 v107, v107, v107
	v_mul_f32_e32 v108, v108, v108
	v_cvt_pk_bf16_f32 v106, v110, v106
	v_cvt_pk_bf16_f32 v107, v107, v108
	v_cvt_pk_bf16_f32 v108, v116, v111
	v_cvt_pk_bf16_f32 v109, v112, v109
	global_store_dwordx4 v[114:115], v[106:109], off sc0 sc1
	v_max_f32_e32 v30, 0, v30
	v_max_f32_e32 v29, 0, v29
	v_mul_f32_e32 v106, v98, v98
	v_max_f32_e32 v98, 0, v103
	v_mul_f32_e32 v103, v99, v99
	v_max_f32_e32 v99, 0, v104
	v_mul_f32_e32 v104, v100, v100
	v_max_f32_e32 v100, 0, v105
	v_mul_f32_e32 v98, v98, v98
	v_mul_f32_e32 v99, v99, v99
	v_mul_f32_e32 v100, v100, v100
	v_cvt_pk_bf16_f32 v98, v102, v98
	v_cvt_pk_bf16_f32 v99, v99, v100
	v_cvt_pk_bf16_f32 v100, v106, v103
	v_cvt_pk_bf16_f32 v101, v104, v101
	global_store_dwordx4 v[114:115], v[98:101], off offset:256 sc0 sc1
	v_pk_mul_f32 v[20:21], v[20:21], v[132:133] op_sel_hi:[1,0]
	v_pk_mul_f32 v[18:19], v[18:19], v[132:133] op_sel_hi:[1,0]
	v_lshlrev_b64 v[98:99], 14, v[162:163]
	v_mul_f32_e32 v100, v90, v90
	v_max_f32_e32 v90, 0, v95
	v_lshl_add_u64 v[98:99], s[28:29], 0, v[98:99]
	v_mul_f32_e32 v90, v90, v90
	v_mul_f32_e32 v95, v91, v91
	v_max_f32_e32 v91, 0, v96
	v_mul_f32_e32 v96, v92, v92
	v_max_f32_e32 v92, 0, v97
	v_lshl_add_u64 v[98:99], v[98:99], 0, v[134:135]
	v_mul_f32_e32 v91, v91, v91
	v_mul_f32_e32 v92, v92, v92
	v_cvt_pk_bf16_f32 v90, v94, v90
	v_cvt_pk_bf16_f32 v91, v91, v92
	v_cvt_pk_bf16_f32 v92, v100, v95
	v_cvt_pk_bf16_f32 v93, v96, v93
	global_store_dwordx4 v[98:99], v[90:93], off sc0 sc1
	v_mul_f32_e32 v30, v30, v30
	v_mul_f32_e32 v29, v29, v29
	v_mul_f32_e32 v90, v82, v82
	v_max_f32_e32 v82, 0, v87
	v_mul_f32_e32 v87, v83, v83
	v_max_f32_e32 v83, 0, v88
	v_mul_f32_e32 v88, v84, v84
	v_max_f32_e32 v84, 0, v89
	v_mul_f32_e32 v82, v82, v82
	v_mul_f32_e32 v83, v83, v83
	v_mul_f32_e32 v84, v84, v84
	v_cvt_pk_bf16_f32 v82, v86, v82
	v_cvt_pk_bf16_f32 v83, v83, v84
	v_cvt_pk_bf16_f32 v84, v90, v87
	v_cvt_pk_bf16_f32 v85, v88, v85
	global_store_dwordx4 v[98:99], v[82:85], off offset:256 sc0 sc1
	v_pk_mul_f32 v[24:25], v[24:25], v[132:133] op_sel_hi:[1,0]
	v_pk_mul_f32 v[22:23], v[22:23], v[132:133] op_sel_hi:[1,0]
	v_lshlrev_b64 v[82:83], 14, v[160:161]
	v_mul_f32_e32 v84, v74, v74
	v_max_f32_e32 v74, 0, v79
	v_lshl_add_u64 v[82:83], s[28:29], 0, v[82:83]
	v_mul_f32_e32 v74, v74, v74
	v_mul_f32_e32 v79, v75, v75
	v_max_f32_e32 v75, 0, v80
	v_mul_f32_e32 v80, v76, v76
	v_max_f32_e32 v76, 0, v81
	v_lshl_add_u64 v[82:83], v[82:83], 0, v[134:135]
	v_mul_f32_e32 v75, v75, v75
	v_mul_f32_e32 v76, v76, v76
	v_cvt_pk_bf16_f32 v74, v78, v74
	v_cvt_pk_bf16_f32 v75, v75, v76
	v_cvt_pk_bf16_f32 v76, v84, v79
	v_cvt_pk_bf16_f32 v77, v80, v77
	global_store_dwordx4 v[82:83], v[74:77], off sc0 sc1
	v_max_f32_e32 v18, 0, v18
	v_max_f32_e32 v19, 0, v19
	v_mul_f32_e32 v74, v66, v66
	v_max_f32_e32 v66, 0, v71
	v_mul_f32_e32 v71, v67, v67
	v_max_f32_e32 v67, 0, v72
	v_mul_f32_e32 v72, v68, v68
	v_max_f32_e32 v68, 0, v73
	v_mul_f32_e32 v66, v66, v66
	v_mul_f32_e32 v67, v67, v67
	v_mul_f32_e32 v68, v68, v68
	v_cvt_pk_bf16_f32 v66, v70, v66
	v_cvt_pk_bf16_f32 v67, v67, v68
	v_cvt_pk_bf16_f32 v68, v74, v71
	v_cvt_pk_bf16_f32 v69, v72, v69
	global_store_dwordx4 v[82:83], v[66:69], off offset:256 sc0 sc1
	v_max_f32_e32 v20, 0, v20
	v_max_f32_e32 v22, 0, v22
	v_lshlrev_b64 v[66:67], 14, v[168:169]
	v_mul_f32_e32 v68, v58, v58
	v_max_f32_e32 v58, 0, v63
	v_lshl_add_u64 v[66:67], s[28:29], 0, v[66:67]
	v_mul_f32_e32 v58, v58, v58
	v_mul_f32_e32 v63, v59, v59
	v_max_f32_e32 v59, 0, v64
	v_mul_f32_e32 v64, v60, v60
	v_max_f32_e32 v60, 0, v65
	v_lshl_add_u64 v[66:67], v[66:67], 0, v[134:135]
	v_mul_f32_e32 v59, v59, v59
	v_mul_f32_e32 v60, v60, v60
	v_cvt_pk_bf16_f32 v58, v62, v58
	v_cvt_pk_bf16_f32 v59, v59, v60
	v_cvt_pk_bf16_f32 v60, v68, v63
	v_cvt_pk_bf16_f32 v61, v64, v61
	global_store_dwordx4 v[66:67], v[58:61], off sc0 sc1
	v_max_f32_e32 v21, 0, v21
	v_pk_mul_f32 v[10:11], v[10:11], v[130:131] op_sel_hi:[1,0]
	v_mul_f32_e32 v58, v50, v50
	v_max_f32_e32 v50, 0, v55
	v_mul_f32_e32 v55, v51, v51
	v_max_f32_e32 v51, 0, v56
	v_mul_f32_e32 v56, v52, v52
	v_max_f32_e32 v52, 0, v57
	v_mul_f32_e32 v50, v50, v50
	v_mul_f32_e32 v51, v51, v51
	v_mul_f32_e32 v52, v52, v52
	v_cvt_pk_bf16_f32 v50, v54, v50
	v_cvt_pk_bf16_f32 v51, v51, v52
	v_cvt_pk_bf16_f32 v52, v58, v55
	v_cvt_pk_bf16_f32 v53, v56, v53
	global_store_dwordx4 v[66:67], v[50:53], off offset:256 sc0 sc1
	v_mul_f32_e32 v22, v22, v22
	v_mul_f32_e32 v21, v21, v21
	v_lshlrev_b64 v[50:51], 14, v[172:173]
	v_mul_f32_e32 v52, v42, v42
	v_max_f32_e32 v42, 0, v47
	v_lshl_add_u64 v[50:51], s[28:29], 0, v[50:51]
	v_mul_f32_e32 v42, v42, v42
	v_mul_f32_e32 v47, v43, v43
	v_max_f32_e32 v43, 0, v48
	v_mul_f32_e32 v48, v44, v44
	v_max_f32_e32 v44, 0, v49
	v_lshl_add_u64 v[50:51], v[50:51], 0, v[134:135]
	v_mul_f32_e32 v43, v43, v43
	v_mul_f32_e32 v44, v44, v44
	v_cvt_pk_bf16_f32 v42, v46, v42
	v_cvt_pk_bf16_f32 v43, v43, v44
	v_cvt_pk_bf16_f32 v44, v52, v47
	v_cvt_pk_bf16_f32 v45, v48, v45
	global_store_dwordx4 v[50:51], v[42:45], off sc0 sc1
	v_pk_mul_f32 v[14:15], v[14:15], v[130:131] op_sel_hi:[1,0]
	v_pk_mul_f32 v[12:13], v[12:13], v[130:131] op_sel_hi:[1,0]
	v_mul_f32_e32 v42, v34, v34
	v_max_f32_e32 v34, 0, v39
	v_mul_f32_e32 v39, v35, v35
	v_max_f32_e32 v35, 0, v40
	v_mul_f32_e32 v40, v36, v36
	v_max_f32_e32 v36, 0, v41
	v_mul_f32_e32 v34, v34, v34
	v_mul_f32_e32 v35, v35, v35
	v_mul_f32_e32 v36, v36, v36
	v_cvt_pk_bf16_f32 v34, v38, v34
	v_cvt_pk_bf16_f32 v35, v35, v36
	v_cvt_pk_bf16_f32 v36, v42, v39
	v_cvt_pk_bf16_f32 v37, v40, v37
	global_store_dwordx4 v[50:51], v[34:37], off offset:256 sc0 sc1
	v_max_f32_e32 v10, 0, v10
	v_pk_mul_f32 v[16:17], v[16:17], v[130:131] op_sel_hi:[1,0]
	v_lshlrev_b64 v[34:35], 14, v[176:177]
	v_mul_f32_e32 v36, v26, v26
	v_max_f32_e32 v26, 0, v31
	v_lshl_add_u64 v[34:35], s[28:29], 0, v[34:35]
	v_mul_f32_e32 v26, v26, v26
	v_mul_f32_e32 v31, v27, v27
	v_max_f32_e32 v27, 0, v32
	v_mul_f32_e32 v32, v28, v28
	v_max_f32_e32 v28, 0, v33
	v_lshl_add_u64 v[34:35], v[34:35], 0, v[134:135]
	v_mul_f32_e32 v27, v27, v27
	v_mul_f32_e32 v28, v28, v28
	v_cvt_pk_bf16_f32 v26, v30, v26
	v_cvt_pk_bf16_f32 v27, v27, v28
	v_cvt_pk_bf16_f32 v28, v36, v31
	v_cvt_pk_bf16_f32 v29, v32, v29
	global_store_dwordx4 v[34:35], v[26:29], off sc0 sc1
	v_max_f32_e32 v11, 0, v11
	v_max_f32_e32 v12, 0, v12
	v_mul_f32_e32 v26, v18, v18
	v_max_f32_e32 v18, 0, v23
	v_mul_f32_e32 v23, v19, v19
	v_max_f32_e32 v19, 0, v24
	v_mul_f32_e32 v24, v20, v20
	v_max_f32_e32 v20, 0, v25
	v_mul_f32_e32 v18, v18, v18
	v_mul_f32_e32 v19, v19, v19
	v_mul_f32_e32 v20, v20, v20
	v_cvt_pk_bf16_f32 v18, v22, v18
	v_cvt_pk_bf16_f32 v19, v19, v20
	v_cvt_pk_bf16_f32 v20, v26, v23
	v_cvt_pk_bf16_f32 v21, v24, v21
	global_store_dwordx4 v[34:35], v[18:21], off offset:256 sc0 sc1
	v_max_f32_e32 v14, 0, v14
	v_max_f32_e32 v13, 0, v13
	v_lshlrev_b64 v[18:19], 14, v[178:179]
	v_mul_f32_e32 v20, v10, v10
	v_max_f32_e32 v10, 0, v15
	v_lshl_add_u64 v[18:19], s[28:29], 0, v[18:19]
	v_mul_f32_e32 v10, v10, v10
	v_mul_f32_e32 v15, v11, v11
	v_max_f32_e32 v11, 0, v16
	v_mul_f32_e32 v16, v12, v12
	v_max_f32_e32 v12, 0, v17
	v_pk_mul_f32 v[4:5], v[4:5], v[130:131] op_sel_hi:[1,0]
	v_pk_mul_f32 v[2:3], v[2:3], v[130:131] op_sel_hi:[1,0]
	v_lshl_add_u64 v[18:19], v[18:19], 0, v[134:135]
	v_mul_f32_e32 v14, v14, v14
	v_mul_f32_e32 v11, v11, v11
	v_mul_f32_e32 v12, v12, v12
	v_mul_f32_e32 v13, v13, v13
	v_cvt_pk_bf16_f32 v10, v14, v10
	v_pk_mul_f32 v[8:9], v[8:9], v[130:131] op_sel_hi:[1,0]
	v_pk_mul_f32 v[6:7], v[6:7], v[130:131] op_sel_hi:[1,0]
	v_max_f32_e32 v2, 0, v2
	v_max_f32_e32 v3, 0, v3
	v_max_f32_e32 v4, 0, v4
	v_cvt_pk_bf16_f32 v11, v11, v12
	v_cvt_pk_bf16_f32 v12, v20, v15
	v_cvt_pk_bf16_f32 v13, v16, v13
	global_store_dwordx4 v[18:19], v[10:13], off sc0 sc1
	v_max_f32_e32 v5, 0, v5
	v_max_f32_e32 v6, 0, v6
	v_mul_f32_e32 v10, v2, v2
	v_max_f32_e32 v2, 0, v7
	v_mul_f32_e32 v7, v3, v3
	v_max_f32_e32 v3, 0, v8
	v_mul_f32_e32 v8, v4, v4
	v_max_f32_e32 v4, 0, v9
	v_mul_f32_e32 v2, v2, v2
	v_mul_f32_e32 v3, v3, v3
	v_mul_f32_e32 v4, v4, v4
	v_mul_f32_e32 v5, v5, v5
	s_mov_b64 s[0:1], -1
	s_andn2_b64 vcc, exec, s[38:39]
	v_mul_f32_e32 v6, v6, v6
	v_cvt_pk_bf16_f32 v2, v6, v2
	v_cvt_pk_bf16_f32 v3, v3, v4
	v_cvt_pk_bf16_f32 v4, v10, v7
	v_cvt_pk_bf16_f32 v5, v8, v5
	global_store_dwordx4 v[18:19], v[2:5], off offset:256 sc0 sc1
	s_cbranch_vccnz .LBB0_1659
	s_andn2_b64 vcc, exec, s[2:3]
	s_cbranch_vccnz .LBB0_1658
	s_barrier
	s_branch .LBB0_1658

.LBB0_1690:
	v_lshl_add_u32 v142, s71, 8, v138
	v_lshl_or_b32 v136, s70, 8, v140
	v_ashrrev_i32_e32 v143, 31, v142
	v_ashrrev_i32_e32 v137, 31, v136
	v_lshlrev_b64 v[144:145], 12, v[142:143]
	v_lshl_add_u64 v[144:145], s[34:35], 0, v[144:145]
	v_lshlrev_b64 v[146:147], 1, v[136:137]
	v_lshl_add_u64 v[136:137], v[144:145], 0, v[146:147]
	v_cvt_pk_bf16_f32 v126, v126, v127
	v_cvt_pk_bf16_f32 v127, v128, v129
	v_cvt_pk_bf16_f32 v128, v122, v123
	v_cvt_pk_bf16_f32 v129, v124, v125
	global_store_dwordx4 v[136:137], v[126:129], off sc0 sc1
	v_cvt_pk_bf16_f32 v114, v114, v115
	v_cvt_pk_bf16_f32 v115, v116, v117
	v_cvt_pk_bf16_f32 v116, v106, v107
	v_or_b32_e32 v106, 16, v142
	v_ashrrev_i32_e32 v107, 31, v106
	v_lshlrev_b64 v[106:107], 12, v[106:107]
	v_lshl_add_u64 v[106:107], s[34:35], 0, v[106:107]
	v_cvt_pk_bf16_f32 v117, v108, v109
	global_store_dwordx4 v[136:137], v[114:117], off offset:256 sc0 sc1
	s_mov_b32 s31, 0x80000
	s_mov_b64 s[44:45], 0x80000
	v_lshl_add_u64 v[114:115], v[106:107], 0, v[146:147]
	v_cvt_pk_bf16_f32 v106, v118, v119
	v_cvt_pk_bf16_f32 v107, v120, v121
	v_cvt_pk_bf16_f32 v108, v110, v111
	v_cvt_pk_bf16_f32 v109, v112, v113
	global_store_dwordx4 v[114:115], v[106:109], off sc0 sc1
	v_cvt_pk_bf16_f32 v98, v98, v99
	v_cvt_pk_bf16_f32 v99, v100, v101
	v_cvt_pk_bf16_f32 v100, v90, v91
	v_or_b32_e32 v90, 32, v142
	v_ashrrev_i32_e32 v91, 31, v90
	v_lshlrev_b64 v[90:91], 12, v[90:91]
	v_lshl_add_u64 v[90:91], s[34:35], 0, v[90:91]
	v_cvt_pk_bf16_f32 v101, v92, v93
	global_store_dwordx4 v[114:115], v[98:101], off offset:256 sc0 sc1
	v_readlane_b32 s84, v254, 52
	v_readlane_b32 s85, v254, 53
	v_lshl_add_u64 v[98:99], v[90:91], 0, v[146:147]
	v_cvt_pk_bf16_f32 v90, v102, v103
	v_cvt_pk_bf16_f32 v91, v104, v105
	v_cvt_pk_bf16_f32 v92, v94, v95
	v_cvt_pk_bf16_f32 v93, v96, v97
	global_store_dwordx4 v[98:99], v[90:93], off sc0 sc1
	v_cvt_pk_bf16_f32 v82, v82, v83
	v_cvt_pk_bf16_f32 v83, v84, v85
	v_cvt_pk_bf16_f32 v84, v74, v75
	v_or_b32_e32 v74, 48, v142
	v_ashrrev_i32_e32 v75, 31, v74
	v_lshlrev_b64 v[74:75], 12, v[74:75]
	v_lshl_add_u64 v[74:75], s[34:35], 0, v[74:75]
	v_cvt_pk_bf16_f32 v85, v76, v77
	global_store_dwordx4 v[98:99], v[82:85], off offset:256 sc0 sc1
	s_mov_b32 s56, 0x19ca0000
	s_movk_i32 s57, 0x210
	v_lshl_add_u64 v[82:83], v[74:75], 0, v[146:147]
	v_cvt_pk_bf16_f32 v74, v86, v87
	v_cvt_pk_bf16_f32 v75, v88, v89
	v_cvt_pk_bf16_f32 v76, v78, v79
	v_cvt_pk_bf16_f32 v77, v80, v81
	global_store_dwordx4 v[82:83], v[74:77], off sc0 sc1
	v_cvt_pk_bf16_f32 v70, v70, v71
	v_cvt_pk_bf16_f32 v71, v72, v73
	v_cvt_pk_bf16_f32 v72, v66, v67
	v_cvt_pk_bf16_f32 v73, v68, v69
	global_store_dwordx4 v[82:83], v[70:73], off offset:256 sc0 sc1
	v_cvt_pk_bf16_f32 v62, v62, v63
	v_cvt_pk_bf16_f32 v63, v64, v65
	v_cvt_pk_bf16_f32 v64, v58, v59
	v_add_co_u32_e32 v58, vcc, s31, v136
	v_lshl_add_u64 v[66:67], v[136:137], 0, s[44:45]
	s_nop 0
	v_addc_co_u32_e32 v59, vcc, 0, v137, vcc
	s_mov_b32 s31, 0x90000
	v_cvt_pk_bf16_f32 v65, v60, v61
	global_store_dwordx4 v[58:59], v[62:65], off sc0 sc1
	v_cvt_pk_bf16_f32 v50, v50, v51
	v_cvt_pk_bf16_f32 v51, v52, v53
	v_cvt_pk_bf16_f32 v52, v42, v43
	v_cvt_pk_bf16_f32 v53, v44, v45
	global_store_dwordx4 v[66:67], v[50:53], off offset:256 sc0 sc1
	s_mov_b64 s[44:45], 0x90000
	v_cvt_pk_bf16_f32 v42, v54, v55
	v_cvt_pk_bf16_f32 v43, v56, v57
	v_cvt_pk_bf16_f32 v44, v46, v47
	v_add_co_u32_e32 v46, vcc, s31, v136
	v_lshl_add_u64 v[50:51], v[136:137], 0, s[44:45]
	s_nop 0
	v_addc_co_u32_e32 v47, vcc, 0, v137, vcc
	s_mov_b32 s31, 0xa0000
	v_cvt_pk_bf16_f32 v45, v48, v49
	global_store_dwordx4 v[46:47], v[42:45], off sc0 sc1
	v_cvt_pk_bf16_f32 v34, v34, v35
	v_cvt_pk_bf16_f32 v35, v36, v37
	v_cvt_pk_bf16_f32 v36, v26, v27
	v_cvt_pk_bf16_f32 v37, v28, v29
	global_store_dwordx4 v[50:51], v[34:37], off offset:256 sc0 sc1
	s_mov_b64 s[44:45], 0xa0000
	v_cvt_pk_bf16_f32 v26, v38, v39
	v_cvt_pk_bf16_f32 v27, v40, v41
	v_cvt_pk_bf16_f32 v28, v30, v31
	v_add_co_u32_e32 v30, vcc, s31, v136
	v_lshl_add_u64 v[34:35], v[136:137], 0, s[44:45]
	s_nop 0
	v_addc_co_u32_e32 v31, vcc, 0, v137, vcc
	s_mov_b32 s31, 0xb0000
	v_cvt_pk_bf16_f32 v29, v32, v33
	global_store_dwordx4 v[30:31], v[26:29], off sc0 sc1
	v_cvt_pk_bf16_f32 v18, v18, v19
	v_cvt_pk_bf16_f32 v19, v20, v21
	v_cvt_pk_bf16_f32 v20, v10, v11
	v_cvt_pk_bf16_f32 v21, v12, v13
	global_store_dwordx4 v[34:35], v[18:21], off offset:256 sc0 sc1
	v_cvt_pk_bf16_f32 v10, v22, v23
	v_cvt_pk_bf16_f32 v11, v24, v25
	v_cvt_pk_bf16_f32 v12, v14, v15
	v_add_co_u32_e32 v14, vcc, s31, v136
	s_mov_b64 s[44:45], 0xb0000
	s_nop 0
	v_addc_co_u32_e32 v15, vcc, 0, v137, vcc
	v_lshl_add_u64 v[18:19], v[136:137], 0, s[44:45]
	s_andn2_b64 vcc, exec, s[38:39]
	s_mov_b64 s[38:39], -1
	v_cvt_pk_bf16_f32 v13, v16, v17
	global_store_dwordx4 v[14:15], v[10:13], off sc0 sc1
	v_cvt_pk_bf16_f32 v6, v6, v7
	v_cvt_pk_bf16_f32 v7, v8, v9
	v_cvt_pk_bf16_f32 v8, v2, v3
	v_cvt_pk_bf16_f32 v9, v4, v5
	global_store_dwordx4 v[18:19], v[6:9], off offset:256 sc0 sc1
	s_cbranch_vccnz .LBB0_1679
	s_andn2_b64 vcc, exec, s[0:1]
	s_cbranch_vccnz .LBB0_1678
	s_barrier
	s_branch .LBB0_1678

.LBB0_1766:
	v_lshl_add_u32 v158, s60, 8, v166
	v_lshl_or_b32 v156, s24, 8, v168
	v_ashrrev_i32_e32 v157, 31, v156
	v_ashrrev_i32_e32 v159, 31, v158
	v_lshl_add_u64 v[160:161], v[156:157], 2, s[20:21]
	v_lshlrev_b64 v[130:131], 13, v[158:159]
	v_lshl_add_u64 v[188:189], v[160:161], 0, v[130:131]
	global_load_dwordx4 v[172:175], v[188:189], off
	global_load_dwordx4 v[176:179], v[188:189], off offset:16
	global_load_dwordx4 v[180:183], v[188:189], off offset:512
	global_load_dwordx4 v[184:187], v[188:189], off offset:528
	v_or_b32_e32 v162, 16, v158
	v_ashrrev_i32_e32 v163, 31, v162
	v_lshlrev_b64 v[130:131], 13, v[162:163]
	v_lshl_add_u64 v[164:165], v[160:161], 0, v[130:131]
	global_load_dwordx4 v[138:141], v[164:165], off offset:16
	global_load_dwordx4 v[142:145], v[164:165], off
	global_load_dwordx4 v[130:133], v[164:165], off offset:528
	global_load_dwordx4 v[134:137], v[164:165], off offset:512
	v_cmp_lt_i32_e32 vcc, v232, v227
	v_lshlrev_b64 v[190:191], 11, v[158:159]
	v_lshl_add_u64 v[190:191], v[190:191], 0, v[156:157]
	v_cndmask_b32_e32 v170, v226, v232, vcc
	v_lshlrev_b32_e32 v170, 2, v170
	v_cmp_lt_i32_e32 vcc, v233, v227
	s_lshl_b32 s46, s24, 2
	v_lshl_add_u64 v[192:193], v[190:191], 1, s[14:15]
	v_cndmask_b32_e32 v171, v226, v233, vcc
	v_lshlrev_b64 v[190:191], 2, v[190:191]
	s_ashr_i32 s47, s46, 31
	v_or_b32_e32 v190, 0x200, v190
	v_lshl_add_u64 v[190:191], s[20:21], 0, v[190:191]
	s_waitcnt vmcnt(0)
	v_pk_add_f32 v[128:129], v[128:129], v[174:175]
	v_pk_add_f32 v[126:127], v[126:127], v[172:173]
	v_pk_add_f32 v[124:125], v[124:125], v[178:179]
	v_pk_add_f32 v[122:123], v[122:123], v[176:177]
	v_pk_add_f32 v[174:175], v[120:121], v[182:183]
	v_pk_add_f32 v[172:173], v[118:119], v[180:181]
	v_pk_add_f32 v[118:119], v[116:117], v[186:187]
	v_pk_add_f32 v[116:117], v[114:115], v[184:185]
	global_store_dwordx4 v[188:189], v[126:129], off sc0 sc1
	global_store_dwordx4 v[188:189], v[122:125], off offset:16 sc0 sc1
	v_cvt_pk_bf16_f32 v176, v126, v127
	v_cvt_pk_bf16_f32 v177, v128, v129
	v_cvt_pk_bf16_f32 v178, v122, v123
	v_cvt_pk_bf16_f32 v179, v124, v125
	v_mul_f32_e32 v114, v127, v127
	v_mul_f32_e32 v115, v128, v128
	v_mul_f32_e32 v120, v122, v122
	v_mul_f32_e32 v121, v124, v124
	v_mul_f32_e32 v122, v173, v173
	v_mul_f32_e32 v124, v174, v174
	v_mul_f32_e32 v127, v116, v116
	v_mul_f32_e32 v128, v118, v118
	v_fmac_f32_e32 v114, v126, v126
	v_fmac_f32_e32 v115, v129, v129
	v_fmac_f32_e32 v120, v123, v123
	v_fmac_f32_e32 v121, v125, v125
	v_fmac_f32_e32 v122, v172, v172
	v_fmac_f32_e32 v124, v175, v175
	v_fmac_f32_e32 v127, v117, v117
	v_fmac_f32_e32 v128, v119, v119
	v_add_f32_e32 v114, v114, v115
	v_add_f32_e32 v115, v121, v120
	v_add_f32_e32 v120, v122, v124
	v_add_f32_e32 v121, v128, v127
	v_add_f32_e32 v114, v114, v115
	v_add_f32_e32 v115, v120, v121
	v_add_f32_e32 v114, v114, v115
	ds_bpermute_b32 v115, v170, v114
	v_lshlrev_b32_e32 v120, 2, v171
	global_store_dwordx4 v[192:193], v[176:179], off sc0 sc1
	global_store_dwordx4 v[190:191], v[172:175], off sc0 sc1
	global_store_dwordx4 v[190:191], v[116:119], off offset:16 sc0 sc1
	v_cvt_pk_bf16_f32 v122, v172, v173
	v_cvt_pk_bf16_f32 v123, v174, v175
	s_waitcnt lgkmcnt(0)
	v_add_f32_e32 v114, v114, v115
	ds_bpermute_b32 v115, v120, v114
	v_cvt_pk_bf16_f32 v124, v116, v117
	v_cvt_pk_bf16_f32 v125, v118, v119
	global_store_dwordx4 v[192:193], v[122:125], off offset:256 sc0 sc1
	s_and_saveexec_b64 s[48:49], s[38:39]
	s_movk_i32 s63, 0x5000
	s_cbranch_execz .LBB0_1768
	v_readlane_b32 s50, v251, 0
	v_lshlrev_b64 v[116:117], 7, v[158:159]
	v_readlane_b32 s51, v251, 1
	s_lshl_b32 s24, s56, 2
	s_waitcnt lgkmcnt(0)
	v_add_f32_e32 v114, v114, v115
	v_lshl_add_u64 v[116:117], s[50:51], 0, v[116:117]
	v_lshl_add_u64 v[116:117], s[46:47], 2, v[116:117]
	v_lshl_add_u64 v[116:117], v[116:117], 0, s[24:25]
	global_store_dword v[116:117], v114, off
.LBB0_1768:
	s_or_b64 exec, exec, s[48:49]
	s_waitcnt lgkmcnt(0)
	v_lshlrev_b64 v[114:115], 11, v[162:163]
	v_pk_add_f32 v[112:113], v[112:113], v[144:145]
	v_pk_add_f32 v[110:111], v[110:111], v[142:143]
	v_pk_add_f32 v[106:107], v[106:107], v[138:139]
	v_lshl_add_u64 v[118:119], v[114:115], 0, v[156:157]
	v_pk_add_f32 v[108:109], v[108:109], v[140:141]
	global_store_dwordx4 v[164:165], v[110:113], off sc0 sc1
	global_store_dwordx4 v[164:165], v[106:109], off offset:16 sc0 sc1
	v_cvt_pk_bf16_f32 v114, v110, v111
	v_cvt_pk_bf16_f32 v115, v112, v113
	v_cvt_pk_bf16_f32 v116, v106, v107
	v_pk_add_f32 v[104:105], v[104:105], v[136:137]
	v_mul_f32_e32 v111, v111, v111
	v_mul_f32_e32 v106, v106, v106
	v_fmac_f32_e32 v111, v110, v110
	v_mul_f32_e32 v110, v112, v112
	v_fmac_f32_e32 v106, v107, v107
	v_mul_f32_e32 v107, v108, v108
	v_fmac_f32_e32 v110, v113, v113
	v_fmac_f32_e32 v107, v109, v109
	v_add_f32_e32 v110, v111, v110
	v_add_f32_e32 v106, v107, v106
	v_pk_add_f32 v[102:103], v[102:103], v[134:135]
	v_add_f32_e32 v112, v110, v106
	v_pk_add_f32 v[106:107], v[98:99], v[130:131]
	v_mul_f32_e32 v98, v103, v103
	v_mul_f32_e32 v99, v104, v104
	v_cvt_pk_bf16_f32 v117, v108, v109
	v_pk_add_f32 v[108:109], v[100:101], v[132:133]
	v_fmac_f32_e32 v98, v102, v102
	v_fmac_f32_e32 v99, v105, v105
	v_add_f32_e32 v98, v98, v99
	v_mul_f32_e32 v99, v106, v106
	v_mul_f32_e32 v100, v108, v108
	v_fmac_f32_e32 v99, v107, v107
	v_fmac_f32_e32 v100, v109, v109
	v_add_f32_e32 v99, v100, v99
	v_add_f32_e32 v98, v98, v99
	v_add_f32_e32 v101, v112, v98
	ds_bpermute_b32 v112, v170, v101
	v_lshlrev_b64 v[110:111], 2, v[118:119]
	v_or_b32_e32 v110, 0x200, v110
	v_lshl_add_u64 v[122:123], v[118:119], 1, s[14:15]
	v_lshl_add_u64 v[98:99], s[20:21], 0, v[110:111]
	global_store_dwordx4 v[122:123], v[114:117], off sc0 sc1
	global_store_dwordx4 v[98:99], v[102:105], off sc0 sc1
	global_store_dwordx4 v[98:99], v[106:109], off offset:16 sc0 sc1
	s_waitcnt lgkmcnt(0)
	v_add_f32_e32 v98, v101, v112
	ds_bpermute_b32 v99, v120, v98
	v_cvt_pk_bf16_f32 v100, v102, v103
	v_cvt_pk_bf16_f32 v101, v104, v105
	v_cvt_pk_bf16_f32 v102, v106, v107
	v_cvt_pk_bf16_f32 v103, v108, v109
	global_store_dwordx4 v[122:123], v[100:103], off offset:256 sc0 sc1
	s_and_saveexec_b64 s[48:49], s[38:39]
	s_cbranch_execz .LBB0_1770
	v_readlane_b32 s50, v251, 0
	v_lshlrev_b64 v[100:101], 7, v[162:163]
	v_readlane_b32 s51, v251, 1
	s_lshl_b32 s24, s56, 2
	s_waitcnt lgkmcnt(0)
	v_add_f32_e32 v98, v98, v99
	v_lshl_add_u64 v[100:101], s[50:51], 0, v[100:101]
	v_lshl_add_u64 v[100:101], s[46:47], 2, v[100:101]
	v_lshl_add_u64 v[100:101], v[100:101], 0, s[24:25]
	global_store_dword v[100:101], v98, off
.LBB0_1770:
	s_or_b64 exec, exec, s[48:49]
	v_or_b32_e32 v118, 32, v158
	v_ashrrev_i32_e32 v119, 31, v118
	s_waitcnt lgkmcnt(0)
	v_lshlrev_b64 v[98:99], 13, v[118:119]
	v_lshl_add_u64 v[138:139], v[160:161], 0, v[98:99]
	global_load_dwordx4 v[122:125], v[138:139], off offset:16
	global_load_dwordx4 v[126:129], v[138:139], off
	global_load_dwordx4 v[130:133], v[138:139], off offset:528
	global_load_dwordx4 v[134:137], v[138:139], off offset:512
	v_or_b32_e32 v114, 48, v158
	v_ashrrev_i32_e32 v115, 31, v114
	v_lshlrev_b64 v[98:99], 13, v[114:115]
	v_lshl_add_u64 v[116:117], v[160:161], 0, v[98:99]
	global_load_dwordx4 v[106:109], v[116:117], off offset:16
	global_load_dwordx4 v[110:113], v[116:117], off
	global_load_dwordx4 v[98:101], v[116:117], off offset:528
	global_load_dwordx4 v[102:105], v[116:117], off offset:512
	v_lshlrev_b64 v[140:141], 11, v[118:119]
	v_lshl_add_u64 v[140:141], v[140:141], 0, v[156:157]
	s_waitcnt vmcnt(7)
	v_pk_add_f32 v[90:91], v[90:91], v[122:123]
	s_waitcnt vmcnt(6)
	v_pk_add_f32 v[96:97], v[96:97], v[128:129]
	v_pk_add_f32 v[94:95], v[94:95], v[126:127]
	v_pk_add_f32 v[92:93], v[92:93], v[124:125]
	global_store_dwordx4 v[138:139], v[94:97], off sc0 sc1
	global_store_dwordx4 v[138:139], v[90:93], off offset:16 sc0 sc1
	v_cvt_pk_bf16_f32 v122, v94, v95
	v_cvt_pk_bf16_f32 v123, v96, v97
	v_cvt_pk_bf16_f32 v124, v90, v91
	v_lshl_add_u64 v[126:127], v[140:141], 1, s[14:15]
	v_mul_f32_e32 v95, v95, v95
	v_mul_f32_e32 v90, v90, v90
	v_fmac_f32_e32 v95, v94, v94
	v_mul_f32_e32 v94, v96, v96
	v_fmac_f32_e32 v90, v91, v91
	v_mul_f32_e32 v91, v92, v92
	v_fmac_f32_e32 v94, v97, v97
	v_fmac_f32_e32 v91, v93, v93
	v_add_f32_e32 v94, v95, v94
	v_add_f32_e32 v90, v91, v90
	v_add_f32_e32 v94, v94, v90
	v_lshlrev_b64 v[90:91], 2, v[140:141]
	v_or_b32_e32 v90, 0x200, v90
	s_waitcnt vmcnt(6)
	v_pk_add_f32 v[88:89], v[88:89], v[136:137]
	v_pk_add_f32 v[86:87], v[86:87], v[134:135]
	v_pk_add_f32 v[82:83], v[82:83], v[130:131]
	v_lshl_add_u64 v[90:91], s[20:21], 0, v[90:91]
	v_cvt_pk_bf16_f32 v125, v92, v93
	global_store_dwordx4 v[126:127], v[122:125], off sc0 sc1
	v_pk_add_f32 v[84:85], v[84:85], v[132:133]
	global_store_dwordx4 v[90:91], v[86:89], off sc0 sc1
	global_store_dwordx4 v[90:91], v[82:85], off offset:16 sc0 sc1
	v_cvt_pk_bf16_f32 v90, v86, v87
	v_cvt_pk_bf16_f32 v91, v88, v89
	v_cvt_pk_bf16_f32 v92, v82, v83
	v_cvt_pk_bf16_f32 v93, v84, v85
	s_nop 0
	v_mul_f32_e32 v87, v87, v87
	v_mul_f32_e32 v82, v82, v82
	v_fmac_f32_e32 v87, v86, v86
	v_mul_f32_e32 v86, v88, v88
	v_fmac_f32_e32 v82, v83, v83
	v_mul_f32_e32 v83, v84, v84
	v_fmac_f32_e32 v86, v89, v89
	v_fmac_f32_e32 v83, v85, v85
	v_add_f32_e32 v86, v87, v86
	v_add_f32_e32 v82, v83, v82
	v_add_f32_e32 v82, v86, v82
	v_add_f32_e32 v82, v94, v82
	ds_bpermute_b32 v83, v170, v82
	global_store_dwordx4 v[126:127], v[90:93], off offset:256 sc0 sc1
	s_waitcnt lgkmcnt(0)
	v_add_f32_e32 v82, v82, v83
	ds_bpermute_b32 v83, v120, v82
	s_and_saveexec_b64 s[48:49], s[38:39]
	v_readlane_b32 s68, v251, 10
	v_readlane_b32 s69, v251, 11
	v_readlane_b32 s76, v251, 18
	v_readlane_b32 s77, v251, 19
	v_readlane_b32 s78, v251, 20
	v_readlane_b32 s79, v251, 21
	v_readlane_b32 s80, v251, 22
	v_readlane_b32 s81, v251, 23
	v_readlane_b32 s82, v251, 24
	v_readlane_b32 s83, v251, 25
	s_mov_b32 s67, 0x800000
	v_readlane_b32 s70, v251, 12
	v_readlane_b32 s71, v251, 13
	v_readlane_b32 s72, v251, 14
	v_readlane_b32 s73, v251, 15
	v_readlane_b32 s74, v251, 16
	v_readlane_b32 s75, v251, 17
	s_cbranch_execz .LBB0_1772
	v_readlane_b32 s50, v251, 0
	v_lshlrev_b64 v[84:85], 7, v[118:119]
	v_readlane_b32 s51, v251, 1
	s_lshl_b32 s24, s56, 2
	s_waitcnt lgkmcnt(0)
	v_add_f32_e32 v82, v82, v83
	v_lshl_add_u64 v[84:85], s[50:51], 0, v[84:85]
	v_lshl_add_u64 v[84:85], s[46:47], 2, v[84:85]
	v_lshl_add_u64 v[84:85], v[84:85], 0, s[24:25]
	global_store_dword v[84:85], v82, off
.LBB0_1772:
	s_or_b64 exec, exec, s[48:49]
	s_waitcnt lgkmcnt(0)
	v_lshlrev_b64 v[82:83], 11, v[114:115]
	s_waitcnt vmcnt(8)
	v_pk_add_f32 v[80:81], v[80:81], v[112:113]
	v_pk_add_f32 v[78:79], v[78:79], v[110:111]
	v_pk_add_f32 v[74:75], v[74:75], v[106:107]
	v_lshl_add_u64 v[86:87], v[82:83], 0, v[156:157]
	v_pk_add_f32 v[76:77], v[76:77], v[108:109]
	global_store_dwordx4 v[116:117], v[78:81], off sc0 sc1
	global_store_dwordx4 v[116:117], v[74:77], off offset:16 sc0 sc1
	v_cvt_pk_bf16_f32 v82, v78, v79
	v_cvt_pk_bf16_f32 v83, v80, v81
	v_cvt_pk_bf16_f32 v84, v74, v75
	s_waitcnt vmcnt(8)
	v_pk_add_f32 v[72:73], v[72:73], v[104:105]
	v_mul_f32_e32 v79, v79, v79
	v_mul_f32_e32 v74, v74, v74
	v_fmac_f32_e32 v79, v78, v78
	v_mul_f32_e32 v78, v80, v80
	v_fmac_f32_e32 v74, v75, v75
	v_mul_f32_e32 v75, v76, v76
	v_fmac_f32_e32 v78, v81, v81
	v_fmac_f32_e32 v75, v77, v77
	v_add_f32_e32 v78, v79, v78
	v_add_f32_e32 v74, v75, v74
	v_pk_add_f32 v[70:71], v[70:71], v[102:103]
	v_add_f32_e32 v80, v78, v74
	v_pk_add_f32 v[74:75], v[66:67], v[98:99]
	v_mul_f32_e32 v66, v71, v71
	v_mul_f32_e32 v67, v72, v72
	v_cvt_pk_bf16_f32 v85, v76, v77
	v_pk_add_f32 v[76:77], v[68:69], v[100:101]
	v_fmac_f32_e32 v66, v70, v70
	v_fmac_f32_e32 v67, v73, v73
	v_add_f32_e32 v66, v66, v67
	v_mul_f32_e32 v67, v74, v74
	v_mul_f32_e32 v68, v76, v76
	v_fmac_f32_e32 v67, v75, v75
	v_fmac_f32_e32 v68, v77, v77
	v_add_f32_e32 v67, v68, v67
	v_add_f32_e32 v66, v66, v67
	v_add_f32_e32 v69, v80, v66
	ds_bpermute_b32 v80, v170, v69
	v_lshlrev_b64 v[78:79], 2, v[86:87]
	v_or_b32_e32 v78, 0x200, v78
	v_lshl_add_u64 v[88:89], v[86:87], 1, s[14:15]
	v_lshl_add_u64 v[66:67], s[20:21], 0, v[78:79]
	global_store_dwordx4 v[88:89], v[82:85], off sc0 sc1
	global_store_dwordx4 v[66:67], v[70:73], off sc0 sc1
	global_store_dwordx4 v[66:67], v[74:77], off offset:16 sc0 sc1
	s_waitcnt lgkmcnt(0)
	v_add_f32_e32 v66, v69, v80
	ds_bpermute_b32 v67, v120, v66
	v_cvt_pk_bf16_f32 v68, v70, v71
	v_cvt_pk_bf16_f32 v69, v72, v73
	v_cvt_pk_bf16_f32 v70, v74, v75
	v_cvt_pk_bf16_f32 v71, v76, v77
	global_store_dwordx4 v[88:89], v[68:71], off offset:256 sc0 sc1
	s_and_saveexec_b64 s[48:49], s[38:39]
	s_cbranch_execz .LBB0_1774
	v_readlane_b32 s50, v251, 0
	v_lshlrev_b64 v[68:69], 7, v[114:115]
	v_readlane_b32 s51, v251, 1
	s_lshl_b32 s24, s56, 2
	s_waitcnt lgkmcnt(0)
	v_add_f32_e32 v66, v66, v67
	v_lshl_add_u64 v[68:69], s[50:51], 0, v[68:69]
	v_lshl_add_u64 v[68:69], s[46:47], 2, v[68:69]
	v_lshl_add_u64 v[68:69], v[68:69], 0, s[24:25]
	global_store_dword v[68:69], v66, off
.LBB0_1774:
	s_or_b64 exec, exec, s[48:49]
	v_add_u32_e32 v86, 0x80, v158
	v_ashrrev_i32_e32 v87, 31, v86
	s_waitcnt lgkmcnt(0)
	v_lshlrev_b64 v[66:67], 13, v[86:87]
	v_lshl_add_u64 v[104:105], v[160:161], 0, v[66:67]
	global_load_dwordx4 v[88:91], v[104:105], off offset:16
	global_load_dwordx4 v[92:95], v[104:105], off
	global_load_dwordx4 v[96:99], v[104:105], off offset:528
	global_load_dwordx4 v[100:103], v[104:105], off offset:512
	v_add_u32_e32 v82, 0x90, v158
	v_ashrrev_i32_e32 v83, 31, v82
	v_lshlrev_b64 v[66:67], 13, v[82:83]
	v_lshl_add_u64 v[84:85], v[160:161], 0, v[66:67]
	global_load_dwordx4 v[74:77], v[84:85], off offset:16
	global_load_dwordx4 v[78:81], v[84:85], off
	global_load_dwordx4 v[66:69], v[84:85], off offset:528
	global_load_dwordx4 v[70:73], v[84:85], off offset:512
	v_lshlrev_b64 v[106:107], 11, v[86:87]
	v_lshl_add_u64 v[106:107], v[106:107], 0, v[156:157]
	s_waitcnt vmcnt(7)
	v_pk_add_f32 v[58:59], v[58:59], v[88:89]
	s_waitcnt vmcnt(6)
	v_pk_add_f32 v[64:65], v[64:65], v[94:95]
	v_pk_add_f32 v[62:63], v[62:63], v[92:93]
	v_pk_add_f32 v[60:61], v[60:61], v[90:91]
	global_store_dwordx4 v[104:105], v[62:65], off sc0 sc1
	global_store_dwordx4 v[104:105], v[58:61], off offset:16 sc0 sc1
	v_cvt_pk_bf16_f32 v88, v62, v63
	v_cvt_pk_bf16_f32 v89, v64, v65
	v_cvt_pk_bf16_f32 v90, v58, v59
	v_lshl_add_u64 v[92:93], v[106:107], 1, s[14:15]
	v_mul_f32_e32 v63, v63, v63
	v_mul_f32_e32 v58, v58, v58
	v_fmac_f32_e32 v63, v62, v62
	v_mul_f32_e32 v62, v64, v64
	v_fmac_f32_e32 v58, v59, v59
	v_mul_f32_e32 v59, v60, v60
	v_fmac_f32_e32 v62, v65, v65
	v_fmac_f32_e32 v59, v61, v61
	v_add_f32_e32 v62, v63, v62
	v_add_f32_e32 v58, v59, v58
	v_add_f32_e32 v62, v62, v58
	v_lshlrev_b64 v[58:59], 2, v[106:107]
	v_or_b32_e32 v58, 0x200, v58
	s_waitcnt vmcnt(6)
	v_pk_add_f32 v[56:57], v[56:57], v[102:103]
	v_pk_add_f32 v[54:55], v[54:55], v[100:101]
	v_pk_add_f32 v[50:51], v[50:51], v[96:97]
	v_lshl_add_u64 v[58:59], s[20:21], 0, v[58:59]
	v_cvt_pk_bf16_f32 v91, v60, v61
	global_store_dwordx4 v[92:93], v[88:91], off sc0 sc1
	v_pk_add_f32 v[52:53], v[52:53], v[98:99]
	global_store_dwordx4 v[58:59], v[54:57], off sc0 sc1
	global_store_dwordx4 v[58:59], v[50:53], off offset:16 sc0 sc1
	v_cvt_pk_bf16_f32 v58, v54, v55
	v_cvt_pk_bf16_f32 v59, v56, v57
	v_cvt_pk_bf16_f32 v60, v50, v51
	v_cvt_pk_bf16_f32 v61, v52, v53
	s_nop 0
	v_mul_f32_e32 v55, v55, v55
	v_mul_f32_e32 v50, v50, v50
	v_fmac_f32_e32 v55, v54, v54
	v_mul_f32_e32 v54, v56, v56
	v_fmac_f32_e32 v50, v51, v51
	v_mul_f32_e32 v51, v52, v52
	v_fmac_f32_e32 v54, v57, v57
	v_fmac_f32_e32 v51, v53, v53
	v_add_f32_e32 v54, v55, v54
	v_add_f32_e32 v50, v51, v50
	v_add_f32_e32 v50, v54, v50
	v_add_f32_e32 v50, v62, v50
	ds_bpermute_b32 v51, v170, v50
	global_store_dwordx4 v[92:93], v[58:61], off offset:256 sc0 sc1
	s_waitcnt lgkmcnt(0)
	v_add_f32_e32 v50, v50, v51
	ds_bpermute_b32 v51, v120, v50
	s_and_saveexec_b64 s[48:49], s[38:39]
	s_cbranch_execz .LBB0_1776
	v_readlane_b32 s50, v251, 0
	v_lshlrev_b64 v[52:53], 7, v[86:87]
	v_readlane_b32 s51, v251, 1
	s_lshl_b32 s24, s56, 2
	s_waitcnt lgkmcnt(0)
	v_add_f32_e32 v50, v50, v51
	v_lshl_add_u64 v[52:53], s[50:51], 0, v[52:53]
	v_lshl_add_u64 v[52:53], s[46:47], 2, v[52:53]
	v_lshl_add_u64 v[52:53], v[52:53], 0, s[24:25]
	global_store_dword v[52:53], v50, off
.LBB0_1776:
	s_or_b64 exec, exec, s[48:49]
	s_waitcnt lgkmcnt(0)
	v_lshlrev_b64 v[50:51], 11, v[82:83]
	s_waitcnt vmcnt(8)
	v_pk_add_f32 v[48:49], v[48:49], v[80:81]
	v_pk_add_f32 v[46:47], v[46:47], v[78:79]
	v_pk_add_f32 v[42:43], v[42:43], v[74:75]
	v_lshl_add_u64 v[54:55], v[50:51], 0, v[156:157]
	v_pk_add_f32 v[44:45], v[44:45], v[76:77]
	global_store_dwordx4 v[84:85], v[46:49], off sc0 sc1
	global_store_dwordx4 v[84:85], v[42:45], off offset:16 sc0 sc1
	v_cvt_pk_bf16_f32 v50, v46, v47
	v_cvt_pk_bf16_f32 v51, v48, v49
	v_cvt_pk_bf16_f32 v52, v42, v43
	s_waitcnt vmcnt(8)
	v_pk_add_f32 v[40:41], v[40:41], v[72:73]
	v_mul_f32_e32 v47, v47, v47
	v_mul_f32_e32 v42, v42, v42
	v_fmac_f32_e32 v47, v46, v46
	v_mul_f32_e32 v46, v48, v48
	v_fmac_f32_e32 v42, v43, v43
	v_mul_f32_e32 v43, v44, v44
	v_fmac_f32_e32 v46, v49, v49
	v_fmac_f32_e32 v43, v45, v45
	v_add_f32_e32 v46, v47, v46
	v_add_f32_e32 v42, v43, v42
	v_pk_add_f32 v[38:39], v[38:39], v[70:71]
	v_add_f32_e32 v48, v46, v42
	v_pk_add_f32 v[42:43], v[34:35], v[66:67]
	v_mul_f32_e32 v34, v39, v39
	v_mul_f32_e32 v35, v40, v40
	v_cvt_pk_bf16_f32 v53, v44, v45
	v_pk_add_f32 v[44:45], v[36:37], v[68:69]
	v_fmac_f32_e32 v34, v38, v38
	v_fmac_f32_e32 v35, v41, v41
	v_add_f32_e32 v34, v34, v35
	v_mul_f32_e32 v35, v42, v42
	v_mul_f32_e32 v36, v44, v44
	v_fmac_f32_e32 v35, v43, v43
	v_fmac_f32_e32 v36, v45, v45
	v_add_f32_e32 v35, v36, v35
	v_add_f32_e32 v34, v34, v35
	v_add_f32_e32 v37, v48, v34
	ds_bpermute_b32 v48, v170, v37
	v_lshlrev_b64 v[46:47], 2, v[54:55]
	v_or_b32_e32 v46, 0x200, v46
	v_lshl_add_u64 v[56:57], v[54:55], 1, s[14:15]
	v_lshl_add_u64 v[34:35], s[20:21], 0, v[46:47]
	global_store_dwordx4 v[56:57], v[50:53], off sc0 sc1
	global_store_dwordx4 v[34:35], v[38:41], off sc0 sc1
	global_store_dwordx4 v[34:35], v[42:45], off offset:16 sc0 sc1
	s_waitcnt lgkmcnt(0)
	v_add_f32_e32 v34, v37, v48
	ds_bpermute_b32 v35, v120, v34
	v_cvt_pk_bf16_f32 v36, v38, v39
	v_cvt_pk_bf16_f32 v37, v40, v41
	v_cvt_pk_bf16_f32 v38, v42, v43
	v_cvt_pk_bf16_f32 v39, v44, v45
	global_store_dwordx4 v[56:57], v[36:39], off offset:256 sc0 sc1
	s_and_saveexec_b64 s[48:49], s[38:39]
	s_cbranch_execz .LBB0_1778
	v_readlane_b32 s50, v251, 0
	v_lshlrev_b64 v[36:37], 7, v[82:83]
	v_readlane_b32 s51, v251, 1
	s_lshl_b32 s24, s56, 2
	s_waitcnt lgkmcnt(0)
	v_add_f32_e32 v34, v34, v35
	v_lshl_add_u64 v[36:37], s[50:51], 0, v[36:37]
	v_lshl_add_u64 v[36:37], s[46:47], 2, v[36:37]
	v_lshl_add_u64 v[36:37], v[36:37], 0, s[24:25]
	global_store_dword v[36:37], v34, off
.LBB0_1778:
	s_or_b64 exec, exec, s[48:49]
	v_add_u32_e32 v54, 0xa0, v158
	v_ashrrev_i32_e32 v55, 31, v54
	s_waitcnt lgkmcnt(0)
	v_lshlrev_b64 v[34:35], 13, v[54:55]
	v_lshl_add_u64 v[72:73], v[160:161], 0, v[34:35]
	global_load_dwordx4 v[56:59], v[72:73], off offset:16
	global_load_dwordx4 v[60:63], v[72:73], off
	global_load_dwordx4 v[64:67], v[72:73], off offset:528
	global_load_dwordx4 v[68:71], v[72:73], off offset:512
	v_add_u32_e32 v50, 0xb0, v158
	v_ashrrev_i32_e32 v51, 31, v50
	v_lshlrev_b64 v[34:35], 13, v[50:51]
	v_lshl_add_u64 v[52:53], v[160:161], 0, v[34:35]
	global_load_dwordx4 v[42:45], v[52:53], off offset:16
	global_load_dwordx4 v[46:49], v[52:53], off
	global_load_dwordx4 v[34:37], v[52:53], off offset:528
	global_load_dwordx4 v[38:41], v[52:53], off offset:512
	v_lshlrev_b64 v[74:75], 11, v[54:55]
	v_lshl_add_u64 v[74:75], v[74:75], 0, v[156:157]
	s_waitcnt vmcnt(7)
	v_pk_add_f32 v[26:27], v[26:27], v[56:57]
	s_waitcnt vmcnt(6)
	v_pk_add_f32 v[32:33], v[32:33], v[62:63]
	v_pk_add_f32 v[30:31], v[30:31], v[60:61]
	v_pk_add_f32 v[28:29], v[28:29], v[58:59]
	global_store_dwordx4 v[72:73], v[30:33], off sc0 sc1
	global_store_dwordx4 v[72:73], v[26:29], off offset:16 sc0 sc1
	v_cvt_pk_bf16_f32 v56, v30, v31
	v_cvt_pk_bf16_f32 v57, v32, v33
	v_cvt_pk_bf16_f32 v58, v26, v27
	v_lshl_add_u64 v[60:61], v[74:75], 1, s[14:15]
	v_mul_f32_e32 v31, v31, v31
	v_mul_f32_e32 v26, v26, v26
	v_fmac_f32_e32 v31, v30, v30
	v_mul_f32_e32 v30, v32, v32
	v_fmac_f32_e32 v26, v27, v27
	v_mul_f32_e32 v27, v28, v28
	v_fmac_f32_e32 v30, v33, v33
	v_fmac_f32_e32 v27, v29, v29
	v_add_f32_e32 v30, v31, v30
	v_add_f32_e32 v26, v27, v26
	v_add_f32_e32 v30, v30, v26
	v_lshlrev_b64 v[26:27], 2, v[74:75]
	v_or_b32_e32 v26, 0x200, v26
	s_waitcnt vmcnt(6)
	v_pk_add_f32 v[24:25], v[24:25], v[70:71]
	v_pk_add_f32 v[22:23], v[22:23], v[68:69]
	v_pk_add_f32 v[18:19], v[18:19], v[64:65]
	v_lshl_add_u64 v[26:27], s[20:21], 0, v[26:27]
	v_cvt_pk_bf16_f32 v59, v28, v29
	global_store_dwordx4 v[60:61], v[56:59], off sc0 sc1
	v_pk_add_f32 v[20:21], v[20:21], v[66:67]
	global_store_dwordx4 v[26:27], v[22:25], off sc0 sc1
	global_store_dwordx4 v[26:27], v[18:21], off offset:16 sc0 sc1
	v_cvt_pk_bf16_f32 v26, v22, v23
	v_cvt_pk_bf16_f32 v27, v24, v25
	v_cvt_pk_bf16_f32 v28, v18, v19
	v_cvt_pk_bf16_f32 v29, v20, v21
	s_nop 0
	v_mul_f32_e32 v23, v23, v23
	v_mul_f32_e32 v18, v18, v18
	v_fmac_f32_e32 v23, v22, v22
	v_mul_f32_e32 v22, v24, v24
	v_fmac_f32_e32 v18, v19, v19
	v_mul_f32_e32 v19, v20, v20
	v_fmac_f32_e32 v22, v25, v25
	v_fmac_f32_e32 v19, v21, v21
	v_add_f32_e32 v22, v23, v22
	v_add_f32_e32 v18, v19, v18
	v_add_f32_e32 v18, v22, v18
	v_add_f32_e32 v18, v30, v18
	ds_bpermute_b32 v19, v170, v18
	global_store_dwordx4 v[60:61], v[26:29], off offset:256 sc0 sc1
	s_waitcnt lgkmcnt(0)
	v_add_f32_e32 v18, v18, v19
	ds_bpermute_b32 v19, v120, v18
	s_and_saveexec_b64 s[48:49], s[38:39]
	s_cbranch_execz .LBB0_1780
	v_readlane_b32 s50, v251, 0
	v_lshlrev_b64 v[20:21], 7, v[54:55]
	v_readlane_b32 s51, v251, 1
	s_lshl_b32 s24, s56, 2
	s_waitcnt lgkmcnt(0)
	v_add_f32_e32 v18, v18, v19
	v_lshl_add_u64 v[20:21], s[50:51], 0, v[20:21]
	v_lshl_add_u64 v[20:21], s[46:47], 2, v[20:21]
	v_lshl_add_u64 v[20:21], v[20:21], 0, s[24:25]
	global_store_dword v[20:21], v18, off
.LBB0_1780:
	s_or_b64 exec, exec, s[48:49]
	s_waitcnt lgkmcnt(0)
	v_lshlrev_b64 v[18:19], 11, v[50:51]
	s_waitcnt vmcnt(8)
	v_pk_add_f32 v[16:17], v[16:17], v[48:49]
	v_pk_add_f32 v[14:15], v[14:15], v[46:47]
	v_pk_add_f32 v[10:11], v[10:11], v[42:43]
	v_lshl_add_u64 v[22:23], v[18:19], 0, v[156:157]
	v_pk_add_f32 v[12:13], v[12:13], v[44:45]
	global_store_dwordx4 v[52:53], v[14:17], off sc0 sc1
	global_store_dwordx4 v[52:53], v[10:13], off offset:16 sc0 sc1
	v_cvt_pk_bf16_f32 v18, v14, v15
	v_cvt_pk_bf16_f32 v19, v16, v17
	v_cvt_pk_bf16_f32 v20, v10, v11
	s_waitcnt vmcnt(8)
	v_pk_add_f32 v[8:9], v[8:9], v[40:41]
	v_mul_f32_e32 v15, v15, v15
	v_mul_f32_e32 v10, v10, v10
	v_fmac_f32_e32 v15, v14, v14
	v_mul_f32_e32 v14, v16, v16
	v_fmac_f32_e32 v10, v11, v11
	v_mul_f32_e32 v11, v12, v12
	v_fmac_f32_e32 v14, v17, v17
	v_fmac_f32_e32 v11, v13, v13
	v_add_f32_e32 v14, v15, v14
	v_add_f32_e32 v10, v11, v10
	v_pk_add_f32 v[6:7], v[6:7], v[38:39]
	v_add_f32_e32 v16, v14, v10
	v_pk_add_f32 v[10:11], v[2:3], v[34:35]
	v_mul_f32_e32 v2, v7, v7
	v_mul_f32_e32 v3, v8, v8
	v_cvt_pk_bf16_f32 v21, v12, v13
	v_pk_add_f32 v[12:13], v[4:5], v[36:37]
	v_fmac_f32_e32 v2, v6, v6
	v_fmac_f32_e32 v3, v9, v9
	v_add_f32_e32 v2, v2, v3
	v_mul_f32_e32 v3, v10, v10
	v_mul_f32_e32 v4, v12, v12
	v_fmac_f32_e32 v3, v11, v11
	v_fmac_f32_e32 v4, v13, v13
	v_add_f32_e32 v3, v4, v3
	v_add_f32_e32 v2, v2, v3
	v_add_f32_e32 v5, v16, v2
	ds_bpermute_b32 v16, v170, v5
	v_lshlrev_b64 v[14:15], 2, v[22:23]
	v_or_b32_e32 v14, 0x200, v14
	v_lshl_add_u64 v[24:25], v[22:23], 1, s[14:15]
	v_lshl_add_u64 v[2:3], s[20:21], 0, v[14:15]
	global_store_dwordx4 v[24:25], v[18:21], off sc0 sc1
	global_store_dwordx4 v[2:3], v[6:9], off sc0 sc1
	global_store_dwordx4 v[2:3], v[10:13], off offset:16 sc0 sc1
	s_waitcnt lgkmcnt(0)
	v_add_f32_e32 v2, v5, v16
	ds_bpermute_b32 v3, v120, v2
	v_cvt_pk_bf16_f32 v4, v6, v7
	v_cvt_pk_bf16_f32 v5, v8, v9
	v_cvt_pk_bf16_f32 v6, v10, v11
	v_cvt_pk_bf16_f32 v7, v12, v13
	global_store_dwordx4 v[24:25], v[4:7], off offset:256 sc0 sc1
	s_and_saveexec_b64 s[48:49], s[38:39]
	s_cbranch_execz .LBB0_1782
	v_readlane_b32 s50, v251, 0
	v_lshlrev_b64 v[4:5], 7, v[50:51]
	v_readlane_b32 s51, v251, 1
	s_lshl_b32 s24, s56, 2
	s_waitcnt lgkmcnt(0)
	v_add_f32_e32 v2, v2, v3
	v_lshl_add_u64 v[4:5], s[50:51], 0, v[4:5]
	v_lshl_add_u64 v[4:5], s[46:47], 2, v[4:5]
	v_lshl_add_u64 v[4:5], v[4:5], 0, s[24:25]
	global_store_dword v[4:5], v2, off

.LBB0_1858:
	v_cmp_lt_i32_e32 vcc, v232, v227
	v_lshl_add_u32 v130, s54, 8, v240
	v_or_b32_e32 v208, 16, v130
	v_cndmask_b32_e32 v131, v226, v232, vcc
	v_cmp_lt_i32_e32 vcc, v233, v227
	v_lshlrev_b32_e32 v244, 2, v131
	v_ashrrev_i32_e32 v209, 31, v208
	v_cndmask_b32_e32 v131, v226, v233, vcc
	v_lshlrev_b32_e32 v245, 2, v131
	v_ashrrev_i32_e32 v131, 31, v130
	v_lshlrev_b64 v[206:207], 7, v[130:131]
	v_lshl_add_u64 v[136:137], v[160:161], 0, v[206:207]
	global_load_dwordx4 v[132:135], v[136:137], off
	s_nop 0
	global_load_dwordx4 v[136:139], v[136:137], off offset:16
	v_lshlrev_b64 v[198:199], 7, v[208:209]
	s_mov_b32 s2, 0x3a000000
	s_mov_b32 s67, 0x800000
	v_or_b32_e32 v200, 32, v130
	v_ashrrev_i32_e32 v201, 31, v200
	v_lshlrev_b64 v[194:195], 7, v[200:201]
	v_or_b32_e32 v196, 48, v130
	v_ashrrev_i32_e32 v197, 31, v196
	v_lshlrev_b64 v[186:187], 7, v[196:197]
	v_add_u32_e32 v188, 0x80, v130
	v_ashrrev_i32_e32 v189, 31, v188
	v_lshlrev_b64 v[182:183], 7, v[188:189]
	v_add_u32_e32 v184, 0x90, v130
	v_ashrrev_i32_e32 v185, 31, v184
	v_lshlrev_b64 v[174:175], 7, v[184:185]
	v_add_u32_e32 v176, 0xa0, v130
	v_ashrrev_i32_e32 v177, 31, v176
	v_lshlrev_b64 v[168:169], 7, v[176:177]
	v_add_u32_e32 v170, 0xb0, v130
	v_ashrrev_i32_e32 v171, 31, v170
	v_lshlrev_b64 v[166:167], 7, v[170:171]
	v_lshl_or_b32 v172, s24, 8, v242
	v_ashrrev_i32_e32 v173, 31, v172
	v_lshlrev_b64 v[130:131], 11, v[130:131]
	v_lshl_add_u64 v[220:221], v[130:131], 0, v[172:173]
	v_lshl_add_u64 v[222:223], v[220:221], 2, s[20:21]
	v_lshl_add_u64 v[130:131], v[220:221], 1, s[34:35]
	v_or_b32_e32 v150, 0x80, v220
	v_mov_b32_e32 v151, v221
	v_lshl_add_u64 v[218:219], v[150:151], 2, s[20:21]
	v_lshl_add_u64 v[150:151], v[150:151], 1, s[34:35]
	s_waitcnt vmcnt(0)
	v_mov_b32_e32 v140, v132
	v_mov_b32_e32 v141, v136
	v_mov_b32_e32 v136, v133
	v_pk_add_f32 v[132:133], v[140:141], v[136:137]
	v_mov_b32_e32 v136, v134
	v_mov_b32_e32 v137, v138
	v_mov_b32_e32 v138, v135
	v_pk_add_f32 v[134:135], v[136:137], v[138:139]
	v_lshl_add_u64 v[136:137], v[160:161], 0, v[198:199]
	v_pk_add_f32 v[140:141], v[132:133], v[134:135]
	global_load_dwordx4 v[132:135], v[136:137], off
	s_nop 0
	global_load_dwordx4 v[136:139], v[136:137], off offset:16
	s_waitcnt vmcnt(1)
	v_mov_b32_e32 v142, v132
	s_waitcnt vmcnt(0)
	v_mov_b32_e32 v143, v136
	v_mov_b32_e32 v136, v133
	v_pk_add_f32 v[132:133], v[142:143], v[136:137]
	v_mov_b32_e32 v136, v134
	v_mov_b32_e32 v137, v138
	v_mov_b32_e32 v138, v135
	v_pk_add_f32 v[134:135], v[136:137], v[138:139]
	v_lshl_add_u64 v[136:137], v[160:161], 0, v[194:195]
	v_pk_add_f32 v[132:133], v[132:133], v[134:135]
	v_mov_b32_e32 v135, v140
	v_mov_b32_e32 v134, v132
	v_mov_b32_e32 v140, v133
	v_pk_add_f32 v[132:133], v[134:135], v[140:141]
	ds_bpermute_b32 v135, v244, v133
	ds_bpermute_b32 v134, v244, v132
	s_waitcnt lgkmcnt(0)
	v_pk_add_f32 v[132:133], v[132:133], v[134:135]
	ds_bpermute_b32 v135, v245, v133
	ds_bpermute_b32 v134, v245, v132
	s_waitcnt lgkmcnt(0)
	v_pk_add_f32 v[132:133], v[132:133], v[134:135]
	s_nop 0
	v_pk_fma_f32 v[216:217], v[132:133], s[2:3], v[210:211] op_sel_hi:[1,0,0]
	s_nop 0
	v_mul_f32_e32 v132, 0x4b800000, v217
	v_cmp_gt_f32_e32 vcc, s67, v217
	v_cmp_gt_f32_e64 s[42:43], s67, v216
	s_nop 0
	v_cndmask_b32_e32 v132, v217, v132, vcc
	v_rsq_f32_e32 v132, v132
	s_nop 0
	v_mul_f32_e32 v133, 0x45800000, v132
	v_cndmask_b32_e32 v217, v132, v133, vcc
	global_load_dwordx4 v[132:135], v[136:137], off
	s_nop 0
	global_load_dwordx4 v[136:139], v[136:137], off offset:16
	v_mul_f32_e32 v122, v122, v217
	v_mul_f32_e32 v122, 0xbfb8aa3b, v122
	v_exp_f32_e32 v122, v122
	v_mul_f32_e32 v126, v126, v217
	v_mul_f32_e32 v126, 0xbfb8aa3b, v126
	v_exp_f32_e32 v126, v126
	v_add_f32_e32 v122, 1.0, v122
	v_rcp_f32_e32 v246, v122
	v_mul_f32_e32 v122, v127, v217
	v_mul_f32_e32 v122, 0xbfb8aa3b, v122
	v_exp_f32_e32 v122, v122
	v_add_f32_e32 v126, 1.0, v126
	v_rcp_f32_e32 v126, v126
	s_and_b64 vcc, exec, s[44:45]
	v_add_f32_e32 v122, 1.0, v122
	v_rcp_f32_e32 v127, v122
	v_mul_f32_e32 v122, v123, v217
	v_mul_f32_e32 v123, v124, v217
	v_mul_f32_e32 v122, 0xbfb8aa3b, v122
	v_mul_f32_e32 v123, 0xbfb8aa3b, v123
	v_exp_f32_e32 v122, v122
	v_exp_f32_e32 v123, v123
	v_mul_f32_e32 v124, v125, v217
	v_mul_f32_e32 v124, 0xbfb8aa3b, v124
	v_add_f32_e32 v122, 1.0, v122
	v_add_f32_e32 v123, 1.0, v123
	v_rcp_f32_e32 v247, v122
	v_mul_f32_e32 v122, v128, v217
	v_rcp_f32_e32 v128, v123
	v_mul_f32_e32 v123, v129, v217
	v_mul_f32_e32 v122, 0xbfb8aa3b, v122
	v_mul_f32_e32 v123, 0xbfb8aa3b, v123
	v_exp_f32_e32 v122, v122
	v_exp_f32_e32 v123, v123
	v_exp_f32_e32 v124, v124
	v_add_f32_e32 v122, 1.0, v122
	v_add_f32_e32 v123, 1.0, v123
	v_add_f32_e32 v124, 1.0, v124
	v_rcp_f32_e32 v122, v122
	v_rcp_f32_e32 v123, v123
	v_rcp_f32_e32 v129, v124
	s_waitcnt vmcnt(1)
	v_mov_b32_e32 v140, v132
	s_waitcnt vmcnt(0)
	v_mov_b32_e32 v141, v136
	v_mov_b32_e32 v136, v133
	v_pk_add_f32 v[132:133], v[140:141], v[136:137]
	v_mov_b32_e32 v136, v134
	v_mov_b32_e32 v137, v138
	v_mov_b32_e32 v138, v135
	v_pk_add_f32 v[134:135], v[136:137], v[138:139]
	v_lshl_add_u64 v[136:137], v[160:161], 0, v[186:187]
	v_pk_add_f32 v[140:141], v[132:133], v[134:135]
	global_load_dwordx4 v[132:135], v[136:137], off
	s_nop 0
	global_load_dwordx4 v[136:139], v[136:137], off offset:16
	s_waitcnt vmcnt(1)
	v_mov_b32_e32 v142, v132
	s_waitcnt vmcnt(0)
	v_mov_b32_e32 v143, v136
	v_mov_b32_e32 v136, v133
	v_pk_add_f32 v[132:133], v[142:143], v[136:137]
	v_mov_b32_e32 v136, v134
	v_mov_b32_e32 v137, v138
	v_mov_b32_e32 v138, v135
	v_pk_add_f32 v[134:135], v[136:137], v[138:139]
	v_lshl_add_u64 v[136:137], v[160:161], 0, v[182:183]
	v_pk_add_f32 v[132:133], v[132:133], v[134:135]
	v_mov_b32_e32 v135, v140
	v_mov_b32_e32 v134, v132
	v_mov_b32_e32 v140, v133
	v_pk_add_f32 v[132:133], v[134:135], v[140:141]
	ds_bpermute_b32 v135, v244, v133
	ds_bpermute_b32 v134, v244, v132
	s_waitcnt lgkmcnt(0)
	v_pk_add_f32 v[202:203], v[132:133], v[134:135]
	global_load_dwordx4 v[132:135], v[136:137], off
	s_nop 0
	global_load_dwordx4 v[136:139], v[136:137], off offset:16
	ds_bpermute_b32 v205, v245, v203
	ds_bpermute_b32 v204, v245, v202
	s_waitcnt vmcnt(1)
	v_mov_b32_e32 v140, v132
	s_waitcnt vmcnt(0)
	v_mov_b32_e32 v141, v136
	v_mov_b32_e32 v136, v133
	v_pk_add_f32 v[132:133], v[140:141], v[136:137]
	v_mov_b32_e32 v136, v134
	v_mov_b32_e32 v137, v138
	v_mov_b32_e32 v138, v135
	v_pk_add_f32 v[134:135], v[136:137], v[138:139]
	v_lshl_add_u64 v[136:137], v[160:161], 0, v[174:175]
	v_pk_add_f32 v[140:141], v[132:133], v[134:135]
	global_load_dwordx4 v[132:135], v[136:137], off
	s_nop 0
	global_load_dwordx4 v[136:139], v[136:137], off offset:16
	s_waitcnt vmcnt(1)
	v_mov_b32_e32 v142, v132
	s_waitcnt vmcnt(0)
	v_mov_b32_e32 v143, v136
	v_mov_b32_e32 v136, v133
	v_pk_add_f32 v[132:133], v[142:143], v[136:137]
	v_mov_b32_e32 v136, v134
	v_mov_b32_e32 v137, v138
	v_mov_b32_e32 v138, v135
	v_pk_add_f32 v[134:135], v[136:137], v[138:139]
	v_lshl_add_u64 v[136:137], v[160:161], 0, v[168:169]
	v_pk_add_f32 v[132:133], v[132:133], v[134:135]
	v_mov_b32_e32 v135, v140
	v_mov_b32_e32 v134, v132
	v_mov_b32_e32 v140, v133
	v_pk_add_f32 v[132:133], v[134:135], v[140:141]
	ds_bpermute_b32 v135, v244, v133
	ds_bpermute_b32 v134, v244, v132
	s_waitcnt lgkmcnt(0)
	v_pk_add_f32 v[190:191], v[132:133], v[134:135]
	global_load_dwordx4 v[132:135], v[136:137], off
	s_nop 0
	global_load_dwordx4 v[136:139], v[136:137], off offset:16
	ds_bpermute_b32 v193, v245, v191
	ds_bpermute_b32 v192, v245, v190
	s_waitcnt vmcnt(1)
	v_mov_b32_e32 v140, v132
	s_waitcnt vmcnt(0)
	v_mov_b32_e32 v141, v136
	v_mov_b32_e32 v136, v133
	v_pk_add_f32 v[132:133], v[140:141], v[136:137]
	v_mov_b32_e32 v136, v134
	v_mov_b32_e32 v137, v138
	v_mov_b32_e32 v138, v135
	v_pk_add_f32 v[134:135], v[136:137], v[138:139]
	v_lshl_add_u64 v[136:137], v[160:161], 0, v[166:167]
	v_pk_add_f32 v[140:141], v[132:133], v[134:135]
	global_load_dwordx4 v[132:135], v[136:137], off
	s_nop 0
	global_load_dwordx4 v[136:139], v[136:137], off offset:16
	s_waitcnt vmcnt(1)
	v_mov_b32_e32 v142, v132
	s_waitcnt vmcnt(0)
	v_mov_b32_e32 v143, v136
	v_mov_b32_e32 v136, v133
	v_pk_add_f32 v[132:133], v[142:143], v[136:137]
	v_mov_b32_e32 v136, v134
	v_mov_b32_e32 v137, v138
	v_mov_b32_e32 v138, v135
	v_pk_add_f32 v[134:135], v[136:137], v[138:139]
	s_nop 0
	v_pk_add_f32 v[132:133], v[132:133], v[134:135]
	v_mov_b32_e32 v135, v140
	v_mov_b32_e32 v134, v132
	v_mov_b32_e32 v140, v133
	v_pk_add_f32 v[132:133], v[134:135], v[140:141]
	ds_bpermute_b32 v135, v244, v133
	ds_bpermute_b32 v134, v244, v132
	s_waitcnt lgkmcnt(0)
	v_pk_add_f32 v[178:179], v[132:133], v[134:135]
	global_load_dwordx4 v[134:137], v[222:223], off offset:16
	global_load_dwordx4 v[142:145], v[222:223], off
	global_load_dwordx4 v[146:149], v[130:131], off
	s_nop 0
	global_load_dwordx4 v[130:133], v[218:219], off offset:16
	global_load_dwordx4 v[138:141], v[218:219], off
	ds_bpermute_b32 v181, v245, v179
	global_load_dwordx4 v[150:153], v[150:151], off
	ds_bpermute_b32 v180, v245, v178
	s_waitcnt vmcnt(3)
	v_lshlrev_b32_e32 v248, 16, v146
	v_and_b32_e32 v249, 0xffff0000, v146
	v_lshlrev_b32_e32 v228, 16, v148
	v_and_b32_e32 v229, 0xffff0000, v148
	v_lshlrev_b32_e32 v146, 16, v147
	v_and_b32_e32 v147, 0xffff0000, v147
	v_lshlrev_b32_e32 v148, 16, v149
	v_and_b32_e32 v149, 0xffff0000, v149
	v_pk_fma_f32 v[124:125], v[122:123], v[146:147], v[144:145]
	v_pk_fma_f32 v[122:123], v[126:127], v[248:249], v[142:143]
	v_pk_fma_f32 v[126:127], v[246:247], v[228:229], v[134:135]
	v_pk_fma_f32 v[128:129], v[128:129], v[148:149], v[136:137]
	v_lshl_add_u64 v[134:135], v[220:221], 1, s[4:5]
	global_store_dwordx4 v[222:223], v[122:125], off sc0 sc1
	global_store_dwordx4 v[222:223], v[126:129], off offset:16 sc0 sc1
	s_cbranch_vccz .LBB0_1860
	v_cvt_pk_bf16_f32 v142, v122, v123
	v_cvt_pk_bf16_f32 v143, v124, v125
	v_cvt_pk_bf16_f32 v144, v126, v127
	v_cvt_pk_bf16_f32 v145, v128, v129
	global_store_dwordx4 v[134:135], v[142:145], off sc0 sc1
.LBB0_1860:
	v_mul_f32_e32 v118, v118, v217
	v_mul_f32_e32 v114, v114, v217
	v_mul_f32_e32 v118, 0xbfb8aa3b, v118
	v_mul_f32_e32 v114, 0xbfb8aa3b, v114
	v_exp_f32_e32 v118, v118
	v_exp_f32_e32 v148, v114
	v_mul_f32_e32 v119, v119, v217
	v_mul_f32_e32 v115, v115, v217
	v_mul_f32_e32 v119, 0xbfb8aa3b, v119
	v_mul_f32_e32 v115, 0xbfb8aa3b, v115
	v_add_f32_e32 v114, 1.0, v118
	v_add_f32_e32 v118, 1.0, v148
	v_exp_f32_e32 v119, v119
	v_exp_f32_e32 v148, v115
	v_mul_f32_e32 v120, v120, v217
	v_mul_f32_e32 v116, v116, v217
	v_mul_f32_e32 v120, 0xbfb8aa3b, v120
	v_mul_f32_e32 v116, 0xbfb8aa3b, v116
	v_add_f32_e32 v115, 1.0, v119
	v_add_f32_e32 v119, 1.0, v148
	v_exp_f32_e32 v120, v120
	v_exp_f32_e32 v148, v116
	v_mul_f32_e32 v121, v121, v217
	v_mul_f32_e32 v117, v117, v217
	v_mul_f32_e32 v121, 0xbfb8aa3b, v121
	v_mul_f32_e32 v117, 0xbfb8aa3b, v117
	v_add_f32_e32 v116, 1.0, v120
	v_add_f32_e32 v120, 1.0, v148
	v_exp_f32_e32 v121, v121
	v_exp_f32_e32 v148, v117
	v_rcp_f32_e32 v114, v114
	v_rcp_f32_e32 v118, v118
	v_add_f32_e32 v117, 1.0, v121
	v_add_f32_e32 v121, 1.0, v148
	v_rcp_f32_e32 v115, v115
	v_rcp_f32_e32 v119, v119
	v_rcp_f32_e32 v116, v116
	v_rcp_f32_e32 v117, v117
	v_rcp_f32_e32 v120, v120
	v_rcp_f32_e32 v121, v121
	s_waitcnt vmcnt(2)
	v_lshlrev_b32_e32 v136, 16, v150
	v_and_b32_e32 v137, 0xffff0000, v150
	v_lshlrev_b32_e32 v142, 16, v151
	v_and_b32_e32 v143, 0xffff0000, v151
	v_lshlrev_b32_e32 v144, 16, v152
	v_and_b32_e32 v145, 0xffff0000, v152
	v_lshlrev_b32_e32 v146, 16, v153
	v_and_b32_e32 v147, 0xffff0000, v153
	v_readlane_b32 s68, v251, 10
	v_pk_fma_f32 v[116:117], v[116:117], v[142:143], v[140:141]
	v_pk_fma_f32 v[114:115], v[114:115], v[136:137], v[138:139]
	v_pk_fma_f32 v[118:119], v[118:119], v[144:145], v[130:131]
	v_pk_fma_f32 v[120:121], v[120:121], v[146:147], v[132:133]
	s_and_b64 vcc, exec, s[44:45]
	v_readlane_b32 s69, v251, 11
	v_readlane_b32 s76, v251, 18
	v_readlane_b32 s77, v251, 19
	v_readlane_b32 s78, v251, 20
	v_readlane_b32 s79, v251, 21
	v_readlane_b32 s80, v251, 22
	v_readlane_b32 s81, v251, 23
	v_readlane_b32 s82, v251, 24
	v_readlane_b32 s83, v251, 25
	global_store_dwordx4 v[218:219], v[114:117], off sc0 sc1
	global_store_dwordx4 v[218:219], v[118:121], off offset:16 sc0 sc1
	v_readlane_b32 s70, v251, 12
	v_readlane_b32 s71, v251, 13
	v_readlane_b32 s72, v251, 14
	v_readlane_b32 s73, v251, 15
	v_readlane_b32 s74, v251, 16
	v_readlane_b32 s75, v251, 17
	s_cbranch_vccz .LBB0_1862
	v_cvt_pk_bf16_f32 v130, v114, v115
	v_cvt_pk_bf16_f32 v131, v116, v117
	v_cvt_pk_bf16_f32 v132, v118, v119
	v_cvt_pk_bf16_f32 v133, v120, v121
	global_store_dwordx4 v[134:135], v[130:133], off offset:256 sc0 sc1

.LBB0_1864:
	s_or_b64 exec, exec, s[2:3]
	v_mul_f32_e32 v114, 0x4b800000, v216
	v_cndmask_b32_e64 v114, v216, v114, s[42:43]
	v_rsq_f32_e32 v114, v114
	s_and_b64 vcc, exec, s[44:45]
	s_waitcnt lgkmcnt(0)
	v_mul_f32_e32 v115, 0x45800000, v114
	v_cndmask_b32_e64 v130, v114, v115, s[42:43]
	v_lshlrev_b64 v[114:115], 11, v[208:209]
	v_lshl_add_u64 v[128:129], v[114:115], 0, v[172:173]
	v_lshl_add_u64 v[144:145], v[128:129], 2, s[20:21]
	v_lshl_add_u64 v[114:115], v[128:129], 1, s[34:35]
	global_load_dwordx4 v[132:135], v[144:145], off offset:16
	global_load_dwordx4 v[136:139], v[144:145], off
	global_load_dwordx4 v[140:143], v[114:115], off
	v_or_b32_e32 v122, 0x80, v128
	v_mov_b32_e32 v123, v129
	v_lshl_add_u64 v[126:127], v[122:123], 2, s[20:21]
	v_lshl_add_u64 v[122:123], v[122:123], 1, s[34:35]
	global_load_dwordx4 v[114:117], v[126:127], off offset:16
	global_load_dwordx4 v[118:121], v[126:127], off
	v_mul_f32_e32 v110, v110, v130
	global_load_dwordx4 v[122:125], v[122:123], off
	v_mul_f32_e32 v106, v106, v130
	v_mul_f32_e32 v111, v111, v130
	v_mul_f32_e32 v107, v107, v130
	v_mul_f32_e32 v112, v112, v130
	v_mul_f32_e32 v108, v108, v130
	v_mul_f32_e32 v113, v113, v130
	v_mul_f32_e32 v109, v109, v130
	v_mul_f32_e32 v110, 0xbfb8aa3b, v110
	v_mul_f32_e32 v106, 0xbfb8aa3b, v106
	v_mul_f32_e32 v111, 0xbfb8aa3b, v111
	v_mul_f32_e32 v107, 0xbfb8aa3b, v107
	v_mul_f32_e32 v112, 0xbfb8aa3b, v112
	v_mul_f32_e32 v108, 0xbfb8aa3b, v108
	v_mul_f32_e32 v113, 0xbfb8aa3b, v113
	v_mul_f32_e32 v109, 0xbfb8aa3b, v109
	v_exp_f32_e32 v110, v110
	v_exp_f32_e32 v106, v106
	v_exp_f32_e32 v111, v111
	v_exp_f32_e32 v107, v107
	v_exp_f32_e32 v112, v112
	v_exp_f32_e32 v108, v108
	v_exp_f32_e32 v113, v113
	v_exp_f32_e32 v109, v109
	v_add_f32_e32 v110, 1.0, v110
	v_add_f32_e32 v106, 1.0, v106
	v_add_f32_e32 v111, 1.0, v111
	v_add_f32_e32 v107, 1.0, v107
	v_add_f32_e32 v112, 1.0, v112
	v_add_f32_e32 v108, 1.0, v108
	v_add_f32_e32 v113, 1.0, v113
	v_add_f32_e32 v109, 1.0, v109
	v_rcp_f32_e32 v110, v110
	v_rcp_f32_e32 v106, v106
	v_rcp_f32_e32 v111, v111
	v_rcp_f32_e32 v107, v107
	v_rcp_f32_e32 v112, v112
	v_rcp_f32_e32 v108, v108
	v_rcp_f32_e32 v113, v113
	v_rcp_f32_e32 v109, v109
	v_lshl_add_u64 v[128:129], v[128:129], 1, s[4:5]
	s_waitcnt vmcnt(3)
	v_lshlrev_b32_e32 v146, 16, v140
	v_and_b32_e32 v147, 0xffff0000, v140
	v_lshlrev_b32_e32 v148, 16, v142
	v_and_b32_e32 v149, 0xffff0000, v142
	v_lshlrev_b32_e32 v140, 16, v141
	v_and_b32_e32 v141, 0xffff0000, v141
	v_lshlrev_b32_e32 v142, 16, v143
	v_and_b32_e32 v143, 0xffff0000, v143
	v_pk_fma_f32 v[112:113], v[112:113], v[140:141], v[138:139]
	v_pk_fma_f32 v[110:111], v[110:111], v[146:147], v[136:137]
	v_pk_fma_f32 v[106:107], v[106:107], v[148:149], v[132:133]
	v_pk_fma_f32 v[108:109], v[108:109], v[142:143], v[134:135]
	global_store_dwordx4 v[144:145], v[110:113], off sc0 sc1
	global_store_dwordx4 v[144:145], v[106:109], off offset:16 sc0 sc1
	s_cbranch_vccz .LBB0_1866
	v_cvt_pk_bf16_f32 v132, v110, v111
	v_cvt_pk_bf16_f32 v133, v112, v113
	v_cvt_pk_bf16_f32 v134, v106, v107
	v_cvt_pk_bf16_f32 v135, v108, v109
	global_store_dwordx4 v[128:129], v[132:135], off sc0 sc1
.LBB0_1866:
	v_mul_f32_e32 v102, v102, v130
	v_mul_f32_e32 v98, v98, v130
	v_mul_f32_e32 v102, 0xbfb8aa3b, v102
	v_mul_f32_e32 v98, 0xbfb8aa3b, v98
	v_exp_f32_e32 v102, v102
	v_exp_f32_e32 v131, v98
	v_mul_f32_e32 v103, v103, v130
	v_mul_f32_e32 v99, v99, v130
	v_mul_f32_e32 v103, 0xbfb8aa3b, v103
	v_mul_f32_e32 v99, 0xbfb8aa3b, v99
	v_add_f32_e32 v98, 1.0, v102
	v_add_f32_e32 v102, 1.0, v131
	v_exp_f32_e32 v103, v103
	v_exp_f32_e32 v131, v99
	v_mul_f32_e32 v104, v104, v130
	v_mul_f32_e32 v100, v100, v130
	v_mul_f32_e32 v105, v105, v130
	v_mul_f32_e32 v101, v101, v130
	v_mul_f32_e32 v104, 0xbfb8aa3b, v104
	v_mul_f32_e32 v100, 0xbfb8aa3b, v100
	v_mul_f32_e32 v105, 0xbfb8aa3b, v105
	v_mul_f32_e32 v101, 0xbfb8aa3b, v101
	v_add_f32_e32 v99, 1.0, v103
	v_add_f32_e32 v103, 1.0, v131
	v_exp_f32_e32 v104, v104
	v_exp_f32_e32 v131, v100
	v_exp_f32_e32 v105, v105
	v_exp_f32_e32 v130, v101
	v_add_f32_e32 v100, 1.0, v104
	v_add_f32_e32 v104, 1.0, v131
	v_add_f32_e32 v101, 1.0, v105
	v_add_f32_e32 v105, 1.0, v130
	v_rcp_f32_e32 v98, v98
	v_rcp_f32_e32 v102, v102
	v_rcp_f32_e32 v99, v99
	v_rcp_f32_e32 v103, v103
	v_rcp_f32_e32 v100, v100
	v_rcp_f32_e32 v101, v101
	v_rcp_f32_e32 v104, v104
	v_rcp_f32_e32 v105, v105
	s_waitcnt vmcnt(2)
	v_lshlrev_b32_e32 v132, 16, v122
	v_and_b32_e32 v133, 0xffff0000, v122
	v_lshlrev_b32_e32 v122, 16, v123
	v_and_b32_e32 v123, 0xffff0000, v123
	v_lshlrev_b32_e32 v134, 16, v124
	v_and_b32_e32 v135, 0xffff0000, v124
	v_lshlrev_b32_e32 v124, 16, v125
	v_and_b32_e32 v125, 0xffff0000, v125
	v_pk_fma_f32 v[100:101], v[100:101], v[122:123], v[120:121]
	v_pk_fma_f32 v[98:99], v[98:99], v[132:133], v[118:119]
	v_pk_fma_f32 v[102:103], v[102:103], v[134:135], v[114:115]
	v_pk_fma_f32 v[104:105], v[104:105], v[124:125], v[116:117]
	s_and_b64 vcc, exec, s[44:45]
	global_store_dwordx4 v[126:127], v[98:101], off sc0 sc1
	global_store_dwordx4 v[126:127], v[102:105], off offset:16 sc0 sc1
	s_cbranch_vccz .LBB0_1868
	v_cvt_pk_bf16_f32 v114, v98, v99
	v_cvt_pk_bf16_f32 v115, v100, v101
	v_cvt_pk_bf16_f32 v116, v102, v103
	v_cvt_pk_bf16_f32 v117, v104, v105
	global_store_dwordx4 v[128:129], v[114:117], off offset:256 sc0 sc1

.LBB0_1870:
	s_or_b64 exec, exec, s[2:3]
	s_waitcnt lgkmcnt(0)
	v_pk_add_f32 v[98:99], v[202:203], v[204:205]
	s_mov_b32 s2, 0x3a000000
	v_pk_fma_f32 v[110:111], v[98:99], s[2:3], v[210:211] op_sel_hi:[1,0,0]
	s_nop 0
	v_mul_f32_e32 v98, 0x4b800000, v111
	v_cmp_gt_f32_e32 vcc, s67, v111
	v_cmp_gt_f32_e64 s[42:43], s67, v110
	s_nop 0
	v_cndmask_b32_e32 v98, v111, v98, vcc
	v_rsq_f32_e32 v98, v98
	s_nop 0
	v_mul_f32_e32 v99, 0x45800000, v98
	v_cndmask_b32_e32 v111, v98, v99, vcc
	v_lshlrev_b64 v[98:99], 11, v[200:201]
	v_lshl_add_u64 v[114:115], v[98:99], 0, v[172:173]
	v_lshl_add_u64 v[128:129], v[114:115], 2, s[20:21]
	v_lshl_add_u64 v[98:99], v[114:115], 1, s[34:35]
	global_load_dwordx4 v[116:119], v[128:129], off offset:16
	global_load_dwordx4 v[120:123], v[128:129], off
	global_load_dwordx4 v[124:127], v[98:99], off
	v_or_b32_e32 v106, 0x80, v114
	v_mov_b32_e32 v107, v115
	v_lshl_add_u64 v[112:113], v[106:107], 2, s[20:21]
	v_lshl_add_u64 v[106:107], v[106:107], 1, s[34:35]
	global_load_dwordx4 v[98:101], v[112:113], off offset:16
	global_load_dwordx4 v[102:105], v[112:113], off
	v_mul_f32_e32 v94, v94, v111
	global_load_dwordx4 v[106:109], v[106:107], off
	v_mul_f32_e32 v90, v90, v111
	v_mul_f32_e32 v95, v95, v111
	v_mul_f32_e32 v91, v91, v111
	v_mul_f32_e32 v96, v96, v111
	v_mul_f32_e32 v92, v92, v111
	v_mul_f32_e32 v97, v97, v111
	v_mul_f32_e32 v93, v93, v111
	v_mul_f32_e32 v94, 0xbfb8aa3b, v94
	v_mul_f32_e32 v90, 0xbfb8aa3b, v90
	v_mul_f32_e32 v95, 0xbfb8aa3b, v95
	v_mul_f32_e32 v91, 0xbfb8aa3b, v91
	v_mul_f32_e32 v96, 0xbfb8aa3b, v96
	v_mul_f32_e32 v92, 0xbfb8aa3b, v92
	v_mul_f32_e32 v97, 0xbfb8aa3b, v97
	v_mul_f32_e32 v93, 0xbfb8aa3b, v93
	v_exp_f32_e32 v94, v94
	v_exp_f32_e32 v90, v90
	v_exp_f32_e32 v95, v95
	v_exp_f32_e32 v91, v91
	v_exp_f32_e32 v96, v96
	v_exp_f32_e32 v92, v92
	v_exp_f32_e32 v97, v97
	v_exp_f32_e32 v93, v93
	v_add_f32_e32 v94, 1.0, v94
	v_add_f32_e32 v90, 1.0, v90
	v_add_f32_e32 v95, 1.0, v95
	v_add_f32_e32 v91, 1.0, v91
	v_add_f32_e32 v96, 1.0, v96
	v_add_f32_e32 v92, 1.0, v92
	v_add_f32_e32 v97, 1.0, v97
	v_add_f32_e32 v93, 1.0, v93
	v_rcp_f32_e32 v94, v94
	v_rcp_f32_e32 v90, v90
	v_rcp_f32_e32 v95, v95
	v_rcp_f32_e32 v91, v91
	v_rcp_f32_e32 v96, v96
	v_rcp_f32_e32 v92, v92
	v_rcp_f32_e32 v97, v97
	v_rcp_f32_e32 v93, v93
	s_and_b64 vcc, exec, s[44:45]
	v_lshl_add_u64 v[114:115], v[114:115], 1, s[4:5]
	s_waitcnt vmcnt(3)
	v_lshlrev_b32_e32 v130, 16, v124
	v_and_b32_e32 v131, 0xffff0000, v124
	v_lshlrev_b32_e32 v132, 16, v126
	v_and_b32_e32 v133, 0xffff0000, v126
	v_lshlrev_b32_e32 v124, 16, v125
	v_and_b32_e32 v125, 0xffff0000, v125
	v_lshlrev_b32_e32 v126, 16, v127
	v_and_b32_e32 v127, 0xffff0000, v127
	v_pk_fma_f32 v[96:97], v[96:97], v[124:125], v[122:123]
	v_pk_fma_f32 v[94:95], v[94:95], v[130:131], v[120:121]
	v_pk_fma_f32 v[90:91], v[90:91], v[132:133], v[116:117]
	v_pk_fma_f32 v[92:93], v[92:93], v[126:127], v[118:119]
	global_store_dwordx4 v[128:129], v[94:97], off sc0 sc1
	global_store_dwordx4 v[128:129], v[90:93], off offset:16 sc0 sc1
	s_cbranch_vccz .LBB0_1872
	v_cvt_pk_bf16_f32 v116, v94, v95
	v_cvt_pk_bf16_f32 v117, v96, v97
	v_cvt_pk_bf16_f32 v118, v90, v91
	v_cvt_pk_bf16_f32 v119, v92, v93
	global_store_dwordx4 v[114:115], v[116:119], off sc0 sc1
.LBB0_1872:
	v_mul_f32_e32 v86, v86, v111
	v_mul_f32_e32 v82, v82, v111
	v_mul_f32_e32 v86, 0xbfb8aa3b, v86
	v_mul_f32_e32 v82, 0xbfb8aa3b, v82
	v_exp_f32_e32 v86, v86
	v_exp_f32_e32 v120, v82
	v_mul_f32_e32 v87, v87, v111
	v_mul_f32_e32 v83, v83, v111
	v_mul_f32_e32 v87, 0xbfb8aa3b, v87
	v_mul_f32_e32 v83, 0xbfb8aa3b, v83
	v_add_f32_e32 v82, 1.0, v86
	v_add_f32_e32 v86, 1.0, v120
	v_exp_f32_e32 v87, v87
	v_exp_f32_e32 v120, v83
	v_mul_f32_e32 v88, v88, v111
	v_mul_f32_e32 v84, v84, v111
	v_mul_f32_e32 v89, v89, v111
	v_mul_f32_e32 v85, v85, v111
	v_mul_f32_e32 v88, 0xbfb8aa3b, v88
	v_mul_f32_e32 v84, 0xbfb8aa3b, v84
	v_mul_f32_e32 v89, 0xbfb8aa3b, v89
	v_mul_f32_e32 v85, 0xbfb8aa3b, v85
	v_add_f32_e32 v83, 1.0, v87
	v_add_f32_e32 v87, 1.0, v120
	v_exp_f32_e32 v88, v88
	v_exp_f32_e32 v120, v84
	v_exp_f32_e32 v89, v89
	v_exp_f32_e32 v111, v85
	v_add_f32_e32 v84, 1.0, v88
	v_add_f32_e32 v88, 1.0, v120
	v_add_f32_e32 v85, 1.0, v89
	v_add_f32_e32 v89, 1.0, v111
	v_rcp_f32_e32 v82, v82
	v_rcp_f32_e32 v86, v86
	v_rcp_f32_e32 v83, v83
	v_rcp_f32_e32 v87, v87
	v_rcp_f32_e32 v84, v84
	v_rcp_f32_e32 v85, v85
	v_rcp_f32_e32 v88, v88
	v_rcp_f32_e32 v89, v89
	s_waitcnt vmcnt(2)
	v_lshlrev_b32_e32 v116, 16, v106
	v_and_b32_e32 v117, 0xffff0000, v106
	v_lshlrev_b32_e32 v106, 16, v107
	v_and_b32_e32 v107, 0xffff0000, v107
	v_lshlrev_b32_e32 v118, 16, v108
	v_and_b32_e32 v119, 0xffff0000, v108
	v_lshlrev_b32_e32 v108, 16, v109
	v_and_b32_e32 v109, 0xffff0000, v109
	v_pk_fma_f32 v[84:85], v[84:85], v[106:107], v[104:105]
	v_pk_fma_f32 v[82:83], v[82:83], v[116:117], v[102:103]
	v_pk_fma_f32 v[86:87], v[86:87], v[118:119], v[98:99]
	v_pk_fma_f32 v[88:89], v[88:89], v[108:109], v[100:101]
	s_and_b64 vcc, exec, s[44:45]
	global_store_dwordx4 v[112:113], v[82:85], off sc0 sc1
	global_store_dwordx4 v[112:113], v[86:89], off offset:16 sc0 sc1
	s_cbranch_vccz .LBB0_1874
	v_cvt_pk_bf16_f32 v98, v82, v83
	v_cvt_pk_bf16_f32 v99, v84, v85
	v_cvt_pk_bf16_f32 v100, v86, v87
	v_cvt_pk_bf16_f32 v101, v88, v89
	global_store_dwordx4 v[114:115], v[98:101], off offset:256 sc0 sc1

.LBB0_1876:
	s_or_b64 exec, exec, s[2:3]
	v_mul_f32_e32 v82, 0x4b800000, v110
	v_cndmask_b32_e64 v82, v110, v82, s[42:43]
	v_rsq_f32_e32 v82, v82
	s_and_b64 vcc, exec, s[44:45]
	s_waitcnt lgkmcnt(0)
	v_mul_f32_e32 v83, 0x45800000, v82
	v_cndmask_b32_e64 v98, v82, v83, s[42:43]
	v_lshlrev_b64 v[82:83], 11, v[196:197]
	v_lshl_add_u64 v[96:97], v[82:83], 0, v[172:173]
	v_lshl_add_u64 v[112:113], v[96:97], 2, s[20:21]
	v_lshl_add_u64 v[82:83], v[96:97], 1, s[34:35]
	global_load_dwordx4 v[100:103], v[112:113], off offset:16
	global_load_dwordx4 v[104:107], v[112:113], off
	global_load_dwordx4 v[108:111], v[82:83], off
	v_or_b32_e32 v90, 0x80, v96
	v_mov_b32_e32 v91, v97
	v_lshl_add_u64 v[94:95], v[90:91], 2, s[20:21]
	v_lshl_add_u64 v[90:91], v[90:91], 1, s[34:35]
	global_load_dwordx4 v[82:85], v[94:95], off offset:16
	global_load_dwordx4 v[86:89], v[94:95], off
	v_mul_f32_e32 v78, v78, v98
	global_load_dwordx4 v[90:93], v[90:91], off
	v_mul_f32_e32 v74, v74, v98
	v_mul_f32_e32 v79, v79, v98
	v_mul_f32_e32 v75, v75, v98
	v_mul_f32_e32 v80, v80, v98
	v_mul_f32_e32 v76, v76, v98
	v_mul_f32_e32 v81, v81, v98
	v_mul_f32_e32 v77, v77, v98
	v_mul_f32_e32 v78, 0xbfb8aa3b, v78
	v_mul_f32_e32 v74, 0xbfb8aa3b, v74
	v_mul_f32_e32 v79, 0xbfb8aa3b, v79
	v_mul_f32_e32 v75, 0xbfb8aa3b, v75
	v_mul_f32_e32 v80, 0xbfb8aa3b, v80
	v_mul_f32_e32 v76, 0xbfb8aa3b, v76
	v_mul_f32_e32 v81, 0xbfb8aa3b, v81
	v_mul_f32_e32 v77, 0xbfb8aa3b, v77
	v_exp_f32_e32 v78, v78
	v_exp_f32_e32 v74, v74
	v_exp_f32_e32 v79, v79
	v_exp_f32_e32 v75, v75
	v_exp_f32_e32 v80, v80
	v_exp_f32_e32 v76, v76
	v_exp_f32_e32 v81, v81
	v_exp_f32_e32 v77, v77
	v_add_f32_e32 v78, 1.0, v78
	v_add_f32_e32 v74, 1.0, v74
	v_add_f32_e32 v79, 1.0, v79
	v_add_f32_e32 v75, 1.0, v75
	v_add_f32_e32 v80, 1.0, v80
	v_add_f32_e32 v76, 1.0, v76
	v_add_f32_e32 v81, 1.0, v81
	v_add_f32_e32 v77, 1.0, v77
	v_rcp_f32_e32 v78, v78
	v_rcp_f32_e32 v74, v74
	v_rcp_f32_e32 v79, v79
	v_rcp_f32_e32 v75, v75
	v_rcp_f32_e32 v80, v80
	v_rcp_f32_e32 v76, v76
	v_rcp_f32_e32 v81, v81
	v_rcp_f32_e32 v77, v77
	v_lshl_add_u64 v[96:97], v[96:97], 1, s[4:5]
	s_waitcnt vmcnt(3)
	v_lshlrev_b32_e32 v114, 16, v108
	v_and_b32_e32 v115, 0xffff0000, v108
	v_lshlrev_b32_e32 v116, 16, v110
	v_and_b32_e32 v117, 0xffff0000, v110
	v_lshlrev_b32_e32 v108, 16, v109
	v_and_b32_e32 v109, 0xffff0000, v109
	v_lshlrev_b32_e32 v110, 16, v111
	v_and_b32_e32 v111, 0xffff0000, v111
	v_pk_fma_f32 v[80:81], v[80:81], v[108:109], v[106:107]
	v_pk_fma_f32 v[78:79], v[78:79], v[114:115], v[104:105]
	v_pk_fma_f32 v[74:75], v[74:75], v[116:117], v[100:101]
	v_pk_fma_f32 v[76:77], v[76:77], v[110:111], v[102:103]
	global_store_dwordx4 v[112:113], v[78:81], off sc0 sc1
	global_store_dwordx4 v[112:113], v[74:77], off offset:16 sc0 sc1
	s_cbranch_vccz .LBB0_1878
	v_cvt_pk_bf16_f32 v100, v78, v79
	v_cvt_pk_bf16_f32 v101, v80, v81
	v_cvt_pk_bf16_f32 v102, v74, v75
	v_cvt_pk_bf16_f32 v103, v76, v77
	global_store_dwordx4 v[96:97], v[100:103], off sc0 sc1
.LBB0_1878:
	v_mul_f32_e32 v70, v70, v98
	v_mul_f32_e32 v66, v66, v98
	v_mul_f32_e32 v70, 0xbfb8aa3b, v70
	v_mul_f32_e32 v66, 0xbfb8aa3b, v66
	v_exp_f32_e32 v70, v70
	v_exp_f32_e32 v99, v66
	v_mul_f32_e32 v71, v71, v98
	v_mul_f32_e32 v67, v67, v98
	v_mul_f32_e32 v71, 0xbfb8aa3b, v71
	v_mul_f32_e32 v67, 0xbfb8aa3b, v67
	v_add_f32_e32 v66, 1.0, v70
	v_add_f32_e32 v70, 1.0, v99
	v_exp_f32_e32 v71, v71
	v_exp_f32_e32 v99, v67
	v_mul_f32_e32 v72, v72, v98
	v_mul_f32_e32 v68, v68, v98
	v_mul_f32_e32 v73, v73, v98
	v_mul_f32_e32 v69, v69, v98
	v_mul_f32_e32 v72, 0xbfb8aa3b, v72
	v_mul_f32_e32 v68, 0xbfb8aa3b, v68
	v_mul_f32_e32 v73, 0xbfb8aa3b, v73
	v_mul_f32_e32 v69, 0xbfb8aa3b, v69
	v_add_f32_e32 v67, 1.0, v71
	v_add_f32_e32 v71, 1.0, v99
	v_exp_f32_e32 v72, v72
	v_exp_f32_e32 v99, v68
	v_exp_f32_e32 v73, v73
	v_exp_f32_e32 v98, v69
	v_add_f32_e32 v68, 1.0, v72
	v_add_f32_e32 v72, 1.0, v99
	v_add_f32_e32 v69, 1.0, v73
	v_add_f32_e32 v73, 1.0, v98
	v_rcp_f32_e32 v66, v66
	v_rcp_f32_e32 v70, v70
	v_rcp_f32_e32 v67, v67
	v_rcp_f32_e32 v71, v71
	v_rcp_f32_e32 v68, v68
	v_rcp_f32_e32 v69, v69
	v_rcp_f32_e32 v72, v72
	v_rcp_f32_e32 v73, v73
	s_waitcnt vmcnt(2)
	v_lshlrev_b32_e32 v100, 16, v90
	v_and_b32_e32 v101, 0xffff0000, v90
	v_lshlrev_b32_e32 v90, 16, v91
	v_and_b32_e32 v91, 0xffff0000, v91
	v_lshlrev_b32_e32 v102, 16, v92
	v_and_b32_e32 v103, 0xffff0000, v92
	v_lshlrev_b32_e32 v92, 16, v93
	v_and_b32_e32 v93, 0xffff0000, v93
	v_pk_fma_f32 v[68:69], v[68:69], v[90:91], v[88:89]
	v_pk_fma_f32 v[66:67], v[66:67], v[100:101], v[86:87]
	v_pk_fma_f32 v[70:71], v[70:71], v[102:103], v[82:83]
	v_pk_fma_f32 v[72:73], v[72:73], v[92:93], v[84:85]
	s_and_b64 vcc, exec, s[44:45]
	global_store_dwordx4 v[94:95], v[66:69], off sc0 sc1
	global_store_dwordx4 v[94:95], v[70:73], off offset:16 sc0 sc1
	s_cbranch_vccz .LBB0_1880
	v_cvt_pk_bf16_f32 v82, v66, v67
	v_cvt_pk_bf16_f32 v83, v68, v69
	v_cvt_pk_bf16_f32 v84, v70, v71
	v_cvt_pk_bf16_f32 v85, v72, v73
	global_store_dwordx4 v[96:97], v[82:85], off offset:256 sc0 sc1

.LBB0_1882:
	s_or_b64 exec, exec, s[2:3]
	s_waitcnt lgkmcnt(0)
	v_pk_add_f32 v[66:67], v[190:191], v[192:193]
	s_mov_b32 s2, 0x3a000000
	v_pk_fma_f32 v[78:79], v[66:67], s[2:3], v[210:211] op_sel_hi:[1,0,0]
	s_nop 0
	v_mul_f32_e32 v66, 0x4b800000, v79
	v_cmp_gt_f32_e32 vcc, s67, v79
	v_cmp_gt_f32_e64 s[42:43], s67, v78
	s_nop 0
	v_cndmask_b32_e32 v66, v79, v66, vcc
	v_rsq_f32_e32 v66, v66
	s_nop 0
	v_mul_f32_e32 v67, 0x45800000, v66
	v_cndmask_b32_e32 v79, v66, v67, vcc
	v_lshlrev_b64 v[66:67], 11, v[188:189]
	v_lshl_add_u64 v[82:83], v[66:67], 0, v[172:173]
	v_lshl_add_u64 v[96:97], v[82:83], 2, s[20:21]
	v_lshl_add_u64 v[66:67], v[82:83], 1, s[34:35]
	global_load_dwordx4 v[84:87], v[96:97], off offset:16
	global_load_dwordx4 v[88:91], v[96:97], off
	global_load_dwordx4 v[92:95], v[66:67], off
	v_or_b32_e32 v74, 0x80, v82
	v_mov_b32_e32 v75, v83
	v_lshl_add_u64 v[80:81], v[74:75], 2, s[20:21]
	v_lshl_add_u64 v[74:75], v[74:75], 1, s[34:35]
	global_load_dwordx4 v[66:69], v[80:81], off offset:16
	global_load_dwordx4 v[70:73], v[80:81], off
	v_mul_f32_e32 v62, v62, v79
	global_load_dwordx4 v[74:77], v[74:75], off
	v_mul_f32_e32 v58, v58, v79
	v_mul_f32_e32 v63, v63, v79
	v_mul_f32_e32 v59, v59, v79
	v_mul_f32_e32 v64, v64, v79
	v_mul_f32_e32 v60, v60, v79
	v_mul_f32_e32 v65, v65, v79
	v_mul_f32_e32 v61, v61, v79
	v_mul_f32_e32 v62, 0xbfb8aa3b, v62
	v_mul_f32_e32 v58, 0xbfb8aa3b, v58
	v_mul_f32_e32 v63, 0xbfb8aa3b, v63
	v_mul_f32_e32 v59, 0xbfb8aa3b, v59
	v_mul_f32_e32 v64, 0xbfb8aa3b, v64
	v_mul_f32_e32 v60, 0xbfb8aa3b, v60
	v_mul_f32_e32 v65, 0xbfb8aa3b, v65
	v_mul_f32_e32 v61, 0xbfb8aa3b, v61
	v_exp_f32_e32 v62, v62
	v_exp_f32_e32 v58, v58
	v_exp_f32_e32 v63, v63
	v_exp_f32_e32 v59, v59
	v_exp_f32_e32 v64, v64
	v_exp_f32_e32 v60, v60
	v_exp_f32_e32 v65, v65
	v_exp_f32_e32 v61, v61
	v_add_f32_e32 v62, 1.0, v62
	v_add_f32_e32 v58, 1.0, v58
	v_add_f32_e32 v63, 1.0, v63
	v_add_f32_e32 v59, 1.0, v59
	v_add_f32_e32 v64, 1.0, v64
	v_add_f32_e32 v60, 1.0, v60
	v_add_f32_e32 v65, 1.0, v65
	v_add_f32_e32 v61, 1.0, v61
	v_rcp_f32_e32 v62, v62
	v_rcp_f32_e32 v58, v58
	v_rcp_f32_e32 v63, v63
	v_rcp_f32_e32 v59, v59
	v_rcp_f32_e32 v64, v64
	v_rcp_f32_e32 v60, v60
	v_rcp_f32_e32 v65, v65
	v_rcp_f32_e32 v61, v61
	s_and_b64 vcc, exec, s[44:45]
	v_lshl_add_u64 v[82:83], v[82:83], 1, s[4:5]
	s_waitcnt vmcnt(3)
	v_lshlrev_b32_e32 v98, 16, v92
	v_and_b32_e32 v99, 0xffff0000, v92
	v_lshlrev_b32_e32 v100, 16, v94
	v_and_b32_e32 v101, 0xffff0000, v94
	v_lshlrev_b32_e32 v92, 16, v93
	v_and_b32_e32 v93, 0xffff0000, v93
	v_lshlrev_b32_e32 v94, 16, v95
	v_and_b32_e32 v95, 0xffff0000, v95
	v_pk_fma_f32 v[64:65], v[64:65], v[92:93], v[90:91]
	v_pk_fma_f32 v[62:63], v[62:63], v[98:99], v[88:89]
	v_pk_fma_f32 v[58:59], v[58:59], v[100:101], v[84:85]
	v_pk_fma_f32 v[60:61], v[60:61], v[94:95], v[86:87]
	global_store_dwordx4 v[96:97], v[62:65], off sc0 sc1
	global_store_dwordx4 v[96:97], v[58:61], off offset:16 sc0 sc1
	s_cbranch_vccz .LBB0_1884
	v_cvt_pk_bf16_f32 v84, v62, v63
	v_cvt_pk_bf16_f32 v85, v64, v65
	v_cvt_pk_bf16_f32 v86, v58, v59
	v_cvt_pk_bf16_f32 v87, v60, v61
	global_store_dwordx4 v[82:83], v[84:87], off sc0 sc1
.LBB0_1884:
	v_mul_f32_e32 v54, v54, v79
	v_mul_f32_e32 v50, v50, v79
	v_mul_f32_e32 v54, 0xbfb8aa3b, v54
	v_mul_f32_e32 v50, 0xbfb8aa3b, v50
	v_exp_f32_e32 v54, v54
	v_exp_f32_e32 v88, v50
	v_mul_f32_e32 v55, v55, v79
	v_mul_f32_e32 v51, v51, v79
	v_mul_f32_e32 v55, 0xbfb8aa3b, v55
	v_mul_f32_e32 v51, 0xbfb8aa3b, v51
	v_add_f32_e32 v50, 1.0, v54
	v_add_f32_e32 v54, 1.0, v88
	v_exp_f32_e32 v55, v55
	v_exp_f32_e32 v88, v51
	v_mul_f32_e32 v56, v56, v79
	v_mul_f32_e32 v52, v52, v79
	v_mul_f32_e32 v57, v57, v79
	v_mul_f32_e32 v53, v53, v79
	v_mul_f32_e32 v56, 0xbfb8aa3b, v56
	v_mul_f32_e32 v52, 0xbfb8aa3b, v52
	v_mul_f32_e32 v57, 0xbfb8aa3b, v57
	v_mul_f32_e32 v53, 0xbfb8aa3b, v53
	v_add_f32_e32 v51, 1.0, v55
	v_add_f32_e32 v55, 1.0, v88
	v_exp_f32_e32 v56, v56
	v_exp_f32_e32 v88, v52
	v_exp_f32_e32 v57, v57
	v_exp_f32_e32 v79, v53
	v_add_f32_e32 v52, 1.0, v56
	v_add_f32_e32 v56, 1.0, v88
	v_add_f32_e32 v53, 1.0, v57
	v_add_f32_e32 v57, 1.0, v79
	v_rcp_f32_e32 v50, v50
	v_rcp_f32_e32 v54, v54
	v_rcp_f32_e32 v51, v51
	v_rcp_f32_e32 v55, v55
	v_rcp_f32_e32 v52, v52
	v_rcp_f32_e32 v53, v53
	v_rcp_f32_e32 v56, v56
	v_rcp_f32_e32 v57, v57
	s_waitcnt vmcnt(2)
	v_lshlrev_b32_e32 v84, 16, v74
	v_and_b32_e32 v85, 0xffff0000, v74
	v_lshlrev_b32_e32 v74, 16, v75
	v_and_b32_e32 v75, 0xffff0000, v75
	v_lshlrev_b32_e32 v86, 16, v76
	v_and_b32_e32 v87, 0xffff0000, v76
	v_lshlrev_b32_e32 v76, 16, v77
	v_and_b32_e32 v77, 0xffff0000, v77
	v_pk_fma_f32 v[52:53], v[52:53], v[74:75], v[72:73]
	v_pk_fma_f32 v[50:51], v[50:51], v[84:85], v[70:71]
	v_pk_fma_f32 v[54:55], v[54:55], v[86:87], v[66:67]
	v_pk_fma_f32 v[56:57], v[56:57], v[76:77], v[68:69]
	s_and_b64 vcc, exec, s[44:45]
	global_store_dwordx4 v[80:81], v[50:53], off sc0 sc1
	global_store_dwordx4 v[80:81], v[54:57], off offset:16 sc0 sc1
	s_cbranch_vccz .LBB0_1886
	v_cvt_pk_bf16_f32 v66, v50, v51
	v_cvt_pk_bf16_f32 v67, v52, v53
	v_cvt_pk_bf16_f32 v68, v54, v55
	v_cvt_pk_bf16_f32 v69, v56, v57
	global_store_dwordx4 v[82:83], v[66:69], off offset:256 sc0 sc1

.LBB0_1888:
	s_or_b64 exec, exec, s[2:3]
	v_mul_f32_e32 v50, 0x4b800000, v78
	v_cndmask_b32_e64 v50, v78, v50, s[42:43]
	v_rsq_f32_e32 v50, v50
	s_and_b64 vcc, exec, s[44:45]
	s_waitcnt lgkmcnt(0)
	v_mul_f32_e32 v51, 0x45800000, v50
	v_cndmask_b32_e64 v66, v50, v51, s[42:43]
	v_lshlrev_b64 v[50:51], 11, v[184:185]
	v_lshl_add_u64 v[64:65], v[50:51], 0, v[172:173]
	v_lshl_add_u64 v[80:81], v[64:65], 2, s[20:21]
	v_lshl_add_u64 v[50:51], v[64:65], 1, s[34:35]
	global_load_dwordx4 v[68:71], v[80:81], off offset:16
	global_load_dwordx4 v[72:75], v[80:81], off
	global_load_dwordx4 v[76:79], v[50:51], off
	v_or_b32_e32 v58, 0x80, v64
	v_mov_b32_e32 v59, v65
	v_lshl_add_u64 v[62:63], v[58:59], 2, s[20:21]
	v_lshl_add_u64 v[58:59], v[58:59], 1, s[34:35]
	global_load_dwordx4 v[50:53], v[62:63], off offset:16
	global_load_dwordx4 v[54:57], v[62:63], off
	v_mul_f32_e32 v46, v46, v66
	global_load_dwordx4 v[58:61], v[58:59], off
	v_mul_f32_e32 v42, v42, v66
	v_mul_f32_e32 v47, v47, v66
	v_mul_f32_e32 v43, v43, v66
	v_mul_f32_e32 v48, v48, v66
	v_mul_f32_e32 v44, v44, v66
	v_mul_f32_e32 v49, v49, v66
	v_mul_f32_e32 v45, v45, v66
	v_mul_f32_e32 v46, 0xbfb8aa3b, v46
	v_mul_f32_e32 v42, 0xbfb8aa3b, v42
	v_mul_f32_e32 v47, 0xbfb8aa3b, v47
	v_mul_f32_e32 v43, 0xbfb8aa3b, v43
	v_mul_f32_e32 v48, 0xbfb8aa3b, v48
	v_mul_f32_e32 v44, 0xbfb8aa3b, v44
	v_mul_f32_e32 v49, 0xbfb8aa3b, v49
	v_mul_f32_e32 v45, 0xbfb8aa3b, v45
	v_exp_f32_e32 v46, v46
	v_exp_f32_e32 v42, v42
	v_exp_f32_e32 v47, v47
	v_exp_f32_e32 v43, v43
	v_exp_f32_e32 v48, v48
	v_exp_f32_e32 v44, v44
	v_exp_f32_e32 v49, v49
	v_exp_f32_e32 v45, v45
	v_add_f32_e32 v46, 1.0, v46
	v_add_f32_e32 v42, 1.0, v42
	v_add_f32_e32 v47, 1.0, v47
	v_add_f32_e32 v43, 1.0, v43
	v_add_f32_e32 v48, 1.0, v48
	v_add_f32_e32 v44, 1.0, v44
	v_add_f32_e32 v49, 1.0, v49
	v_add_f32_e32 v45, 1.0, v45
	v_rcp_f32_e32 v46, v46
	v_rcp_f32_e32 v42, v42
	v_rcp_f32_e32 v47, v47
	v_rcp_f32_e32 v43, v43
	v_rcp_f32_e32 v48, v48
	v_rcp_f32_e32 v44, v44
	v_rcp_f32_e32 v49, v49
	v_rcp_f32_e32 v45, v45
	v_lshl_add_u64 v[64:65], v[64:65], 1, s[4:5]
	s_waitcnt vmcnt(3)
	v_lshlrev_b32_e32 v82, 16, v76
	v_and_b32_e32 v83, 0xffff0000, v76
	v_lshlrev_b32_e32 v84, 16, v78
	v_and_b32_e32 v85, 0xffff0000, v78
	v_lshlrev_b32_e32 v76, 16, v77
	v_and_b32_e32 v77, 0xffff0000, v77
	v_lshlrev_b32_e32 v78, 16, v79
	v_and_b32_e32 v79, 0xffff0000, v79
	v_pk_fma_f32 v[48:49], v[48:49], v[76:77], v[74:75]
	v_pk_fma_f32 v[46:47], v[46:47], v[82:83], v[72:73]
	v_pk_fma_f32 v[42:43], v[42:43], v[84:85], v[68:69]
	v_pk_fma_f32 v[44:45], v[44:45], v[78:79], v[70:71]
	global_store_dwordx4 v[80:81], v[46:49], off sc0 sc1
	global_store_dwordx4 v[80:81], v[42:45], off offset:16 sc0 sc1
	s_cbranch_vccz .LBB0_1890
	v_cvt_pk_bf16_f32 v68, v46, v47
	v_cvt_pk_bf16_f32 v69, v48, v49
	v_cvt_pk_bf16_f32 v70, v42, v43
	v_cvt_pk_bf16_f32 v71, v44, v45
	global_store_dwordx4 v[64:65], v[68:71], off sc0 sc1
.LBB0_1890:
	v_mul_f32_e32 v38, v38, v66
	v_mul_f32_e32 v34, v34, v66
	v_mul_f32_e32 v38, 0xbfb8aa3b, v38
	v_mul_f32_e32 v34, 0xbfb8aa3b, v34
	v_exp_f32_e32 v38, v38
	v_exp_f32_e32 v67, v34
	v_mul_f32_e32 v39, v39, v66
	v_mul_f32_e32 v35, v35, v66
	v_mul_f32_e32 v39, 0xbfb8aa3b, v39
	v_mul_f32_e32 v35, 0xbfb8aa3b, v35
	v_add_f32_e32 v34, 1.0, v38
	v_add_f32_e32 v38, 1.0, v67
	v_exp_f32_e32 v39, v39
	v_exp_f32_e32 v67, v35
	v_mul_f32_e32 v40, v40, v66
	v_mul_f32_e32 v36, v36, v66
	v_mul_f32_e32 v41, v41, v66
	v_mul_f32_e32 v37, v37, v66
	v_mul_f32_e32 v40, 0xbfb8aa3b, v40
	v_mul_f32_e32 v36, 0xbfb8aa3b, v36
	v_mul_f32_e32 v41, 0xbfb8aa3b, v41
	v_mul_f32_e32 v37, 0xbfb8aa3b, v37
	v_add_f32_e32 v35, 1.0, v39
	v_add_f32_e32 v39, 1.0, v67
	v_exp_f32_e32 v40, v40
	v_exp_f32_e32 v67, v36
	v_exp_f32_e32 v41, v41
	v_exp_f32_e32 v66, v37
	v_add_f32_e32 v36, 1.0, v40
	v_add_f32_e32 v40, 1.0, v67
	v_add_f32_e32 v37, 1.0, v41
	v_add_f32_e32 v41, 1.0, v66
	v_rcp_f32_e32 v34, v34
	v_rcp_f32_e32 v38, v38
	v_rcp_f32_e32 v35, v35
	v_rcp_f32_e32 v39, v39
	v_rcp_f32_e32 v36, v36
	v_rcp_f32_e32 v37, v37
	v_rcp_f32_e32 v40, v40
	v_rcp_f32_e32 v41, v41
	s_waitcnt vmcnt(2)
	v_lshlrev_b32_e32 v68, 16, v58
	v_and_b32_e32 v69, 0xffff0000, v58
	v_lshlrev_b32_e32 v58, 16, v59
	v_and_b32_e32 v59, 0xffff0000, v59
	v_lshlrev_b32_e32 v70, 16, v60
	v_and_b32_e32 v71, 0xffff0000, v60
	v_lshlrev_b32_e32 v60, 16, v61
	v_and_b32_e32 v61, 0xffff0000, v61
	v_pk_fma_f32 v[36:37], v[36:37], v[58:59], v[56:57]
	v_pk_fma_f32 v[34:35], v[34:35], v[68:69], v[54:55]
	v_pk_fma_f32 v[38:39], v[38:39], v[70:71], v[50:51]
	v_pk_fma_f32 v[40:41], v[40:41], v[60:61], v[52:53]
	s_and_b64 vcc, exec, s[44:45]
	global_store_dwordx4 v[62:63], v[34:37], off sc0 sc1
	global_store_dwordx4 v[62:63], v[38:41], off offset:16 sc0 sc1
	s_cbranch_vccz .LBB0_1892
	v_cvt_pk_bf16_f32 v50, v34, v35
	v_cvt_pk_bf16_f32 v51, v36, v37
	v_cvt_pk_bf16_f32 v52, v38, v39
	v_cvt_pk_bf16_f32 v53, v40, v41
	global_store_dwordx4 v[64:65], v[50:53], off offset:256 sc0 sc1

.LBB0_1894:
	s_or_b64 exec, exec, s[2:3]
	s_waitcnt lgkmcnt(0)
	v_pk_add_f32 v[34:35], v[178:179], v[180:181]
	s_mov_b32 s2, 0x3a000000
	v_pk_fma_f32 v[46:47], v[34:35], s[2:3], v[210:211] op_sel_hi:[1,0,0]
	s_nop 0
	v_mul_f32_e32 v34, 0x4b800000, v47
	v_cmp_gt_f32_e32 vcc, s67, v47
	v_cmp_gt_f32_e64 s[42:43], s67, v46
	s_nop 0
	v_cndmask_b32_e32 v34, v47, v34, vcc
	v_rsq_f32_e32 v34, v34
	s_nop 0
	v_mul_f32_e32 v35, 0x45800000, v34
	v_cndmask_b32_e32 v47, v34, v35, vcc
	v_lshlrev_b64 v[34:35], 11, v[176:177]
	v_lshl_add_u64 v[50:51], v[34:35], 0, v[172:173]
	v_lshl_add_u64 v[64:65], v[50:51], 2, s[20:21]
	v_lshl_add_u64 v[34:35], v[50:51], 1, s[34:35]
	global_load_dwordx4 v[52:55], v[64:65], off offset:16
	global_load_dwordx4 v[56:59], v[64:65], off
	global_load_dwordx4 v[60:63], v[34:35], off
	v_or_b32_e32 v42, 0x80, v50
	v_mov_b32_e32 v43, v51
	v_lshl_add_u64 v[48:49], v[42:43], 2, s[20:21]
	v_lshl_add_u64 v[42:43], v[42:43], 1, s[34:35]
	global_load_dwordx4 v[34:37], v[48:49], off offset:16
	global_load_dwordx4 v[38:41], v[48:49], off
	v_mul_f32_e32 v30, v30, v47
	global_load_dwordx4 v[42:45], v[42:43], off
	v_mul_f32_e32 v26, v26, v47
	v_mul_f32_e32 v31, v31, v47
	v_mul_f32_e32 v27, v27, v47
	v_mul_f32_e32 v32, v32, v47
	v_mul_f32_e32 v28, v28, v47
	v_mul_f32_e32 v33, v33, v47
	v_mul_f32_e32 v29, v29, v47
	v_mul_f32_e32 v30, 0xbfb8aa3b, v30
	v_mul_f32_e32 v26, 0xbfb8aa3b, v26
	v_mul_f32_e32 v31, 0xbfb8aa3b, v31
	v_mul_f32_e32 v27, 0xbfb8aa3b, v27
	v_mul_f32_e32 v32, 0xbfb8aa3b, v32
	v_mul_f32_e32 v28, 0xbfb8aa3b, v28
	v_mul_f32_e32 v33, 0xbfb8aa3b, v33
	v_mul_f32_e32 v29, 0xbfb8aa3b, v29
	v_exp_f32_e32 v30, v30
	v_exp_f32_e32 v26, v26
	v_exp_f32_e32 v31, v31
	v_exp_f32_e32 v27, v27
	v_exp_f32_e32 v32, v32
	v_exp_f32_e32 v28, v28
	v_exp_f32_e32 v33, v33
	v_exp_f32_e32 v29, v29
	v_add_f32_e32 v30, 1.0, v30
	v_add_f32_e32 v26, 1.0, v26
	v_add_f32_e32 v31, 1.0, v31
	v_add_f32_e32 v27, 1.0, v27
	v_add_f32_e32 v32, 1.0, v32
	v_add_f32_e32 v28, 1.0, v28
	v_add_f32_e32 v33, 1.0, v33
	v_add_f32_e32 v29, 1.0, v29
	v_rcp_f32_e32 v30, v30
	v_rcp_f32_e32 v26, v26
	v_rcp_f32_e32 v31, v31
	v_rcp_f32_e32 v27, v27
	v_rcp_f32_e32 v32, v32
	v_rcp_f32_e32 v28, v28
	v_rcp_f32_e32 v33, v33
	v_rcp_f32_e32 v29, v29
	s_and_b64 vcc, exec, s[44:45]
	v_lshl_add_u64 v[50:51], v[50:51], 1, s[4:5]
	s_waitcnt vmcnt(3)
	v_lshlrev_b32_e32 v66, 16, v60
	v_and_b32_e32 v67, 0xffff0000, v60
	v_lshlrev_b32_e32 v68, 16, v62
	v_and_b32_e32 v69, 0xffff0000, v62
	v_lshlrev_b32_e32 v60, 16, v61
	v_and_b32_e32 v61, 0xffff0000, v61
	v_lshlrev_b32_e32 v62, 16, v63
	v_and_b32_e32 v63, 0xffff0000, v63
	v_pk_fma_f32 v[32:33], v[32:33], v[60:61], v[58:59]
	v_pk_fma_f32 v[30:31], v[30:31], v[66:67], v[56:57]
	v_pk_fma_f32 v[26:27], v[26:27], v[68:69], v[52:53]
	v_pk_fma_f32 v[28:29], v[28:29], v[62:63], v[54:55]
	global_store_dwordx4 v[64:65], v[30:33], off sc0 sc1
	global_store_dwordx4 v[64:65], v[26:29], off offset:16 sc0 sc1
	s_cbranch_vccz .LBB0_1896
	v_cvt_pk_bf16_f32 v52, v30, v31
	v_cvt_pk_bf16_f32 v53, v32, v33
	v_cvt_pk_bf16_f32 v54, v26, v27
	v_cvt_pk_bf16_f32 v55, v28, v29
	global_store_dwordx4 v[50:51], v[52:55], off sc0 sc1
.LBB0_1896:
	v_mul_f32_e32 v22, v22, v47
	v_mul_f32_e32 v18, v18, v47
	v_mul_f32_e32 v22, 0xbfb8aa3b, v22
	v_mul_f32_e32 v18, 0xbfb8aa3b, v18
	v_exp_f32_e32 v22, v22
	v_exp_f32_e32 v56, v18
	v_mul_f32_e32 v23, v23, v47
	v_mul_f32_e32 v19, v19, v47
	v_mul_f32_e32 v23, 0xbfb8aa3b, v23
	v_mul_f32_e32 v19, 0xbfb8aa3b, v19
	v_add_f32_e32 v18, 1.0, v22
	v_add_f32_e32 v22, 1.0, v56
	v_exp_f32_e32 v23, v23
	v_exp_f32_e32 v56, v19
	v_mul_f32_e32 v24, v24, v47
	v_mul_f32_e32 v20, v20, v47
	v_mul_f32_e32 v25, v25, v47
	v_mul_f32_e32 v21, v21, v47
	v_mul_f32_e32 v24, 0xbfb8aa3b, v24
	v_mul_f32_e32 v20, 0xbfb8aa3b, v20
	v_mul_f32_e32 v25, 0xbfb8aa3b, v25
	v_mul_f32_e32 v21, 0xbfb8aa3b, v21
	v_add_f32_e32 v19, 1.0, v23
	v_add_f32_e32 v23, 1.0, v56
	v_exp_f32_e32 v24, v24
	v_exp_f32_e32 v56, v20
	v_exp_f32_e32 v25, v25
	v_exp_f32_e32 v47, v21
	v_add_f32_e32 v20, 1.0, v24
	v_add_f32_e32 v24, 1.0, v56
	v_add_f32_e32 v21, 1.0, v25
	v_add_f32_e32 v25, 1.0, v47
	v_rcp_f32_e32 v18, v18
	v_rcp_f32_e32 v22, v22
	v_rcp_f32_e32 v19, v19
	v_rcp_f32_e32 v23, v23
	v_rcp_f32_e32 v20, v20
	v_rcp_f32_e32 v21, v21
	v_rcp_f32_e32 v24, v24
	v_rcp_f32_e32 v25, v25
	s_waitcnt vmcnt(2)
	v_lshlrev_b32_e32 v52, 16, v42
	v_and_b32_e32 v53, 0xffff0000, v42
	v_lshlrev_b32_e32 v42, 16, v43
	v_and_b32_e32 v43, 0xffff0000, v43
	v_lshlrev_b32_e32 v54, 16, v44
	v_and_b32_e32 v55, 0xffff0000, v44
	v_lshlrev_b32_e32 v44, 16, v45
	v_and_b32_e32 v45, 0xffff0000, v45
	v_pk_fma_f32 v[20:21], v[20:21], v[42:43], v[40:41]
	v_pk_fma_f32 v[18:19], v[18:19], v[52:53], v[38:39]
	v_pk_fma_f32 v[22:23], v[22:23], v[54:55], v[34:35]
	v_pk_fma_f32 v[24:25], v[24:25], v[44:45], v[36:37]
	s_and_b64 vcc, exec, s[44:45]
	global_store_dwordx4 v[48:49], v[18:21], off sc0 sc1
	global_store_dwordx4 v[48:49], v[22:25], off offset:16 sc0 sc1
	s_cbranch_vccz .LBB0_1898
	v_cvt_pk_bf16_f32 v34, v18, v19
	v_cvt_pk_bf16_f32 v35, v20, v21
	v_cvt_pk_bf16_f32 v36, v22, v23
	v_cvt_pk_bf16_f32 v37, v24, v25
	global_store_dwordx4 v[50:51], v[34:37], off offset:256 sc0 sc1

.LBB0_1900:
	s_or_b64 exec, exec, s[2:3]
	v_mul_f32_e32 v18, 0x4b800000, v46
	v_cndmask_b32_e64 v18, v46, v18, s[42:43]
	v_rsq_f32_e32 v18, v18
	s_and_b64 vcc, exec, s[44:45]
	s_waitcnt lgkmcnt(0)
	v_mul_f32_e32 v19, 0x45800000, v18
	v_cndmask_b32_e64 v34, v18, v19, s[42:43]
	v_lshlrev_b64 v[18:19], 11, v[170:171]
	v_lshl_add_u64 v[32:33], v[18:19], 0, v[172:173]
	v_lshl_add_u64 v[48:49], v[32:33], 2, s[20:21]
	v_lshl_add_u64 v[18:19], v[32:33], 1, s[34:35]
	global_load_dwordx4 v[36:39], v[48:49], off offset:16
	global_load_dwordx4 v[40:43], v[48:49], off
	global_load_dwordx4 v[44:47], v[18:19], off
	v_or_b32_e32 v26, 0x80, v32
	v_mov_b32_e32 v27, v33
	v_lshl_add_u64 v[30:31], v[26:27], 2, s[20:21]
	v_lshl_add_u64 v[26:27], v[26:27], 1, s[34:35]
	global_load_dwordx4 v[18:21], v[30:31], off offset:16
	global_load_dwordx4 v[22:25], v[30:31], off
	v_mul_f32_e32 v14, v14, v34
	global_load_dwordx4 v[26:29], v[26:27], off
	v_mul_f32_e32 v10, v10, v34
	v_mul_f32_e32 v15, v15, v34
	v_mul_f32_e32 v11, v11, v34
	v_mul_f32_e32 v16, v16, v34
	v_mul_f32_e32 v12, v12, v34
	v_mul_f32_e32 v17, v17, v34
	v_mul_f32_e32 v13, v13, v34
	v_mul_f32_e32 v14, 0xbfb8aa3b, v14
	v_mul_f32_e32 v10, 0xbfb8aa3b, v10
	v_mul_f32_e32 v15, 0xbfb8aa3b, v15
	v_mul_f32_e32 v11, 0xbfb8aa3b, v11
	v_mul_f32_e32 v16, 0xbfb8aa3b, v16
	v_mul_f32_e32 v12, 0xbfb8aa3b, v12
	v_mul_f32_e32 v17, 0xbfb8aa3b, v17
	v_mul_f32_e32 v13, 0xbfb8aa3b, v13
	v_exp_f32_e32 v14, v14
	v_exp_f32_e32 v10, v10
	v_exp_f32_e32 v15, v15
	v_exp_f32_e32 v11, v11
	v_exp_f32_e32 v16, v16
	v_exp_f32_e32 v12, v12
	v_exp_f32_e32 v17, v17
	v_exp_f32_e32 v13, v13
	v_add_f32_e32 v14, 1.0, v14
	v_add_f32_e32 v10, 1.0, v10
	v_add_f32_e32 v15, 1.0, v15
	v_add_f32_e32 v11, 1.0, v11
	v_add_f32_e32 v16, 1.0, v16
	v_add_f32_e32 v12, 1.0, v12
	v_add_f32_e32 v17, 1.0, v17
	v_add_f32_e32 v13, 1.0, v13
	v_rcp_f32_e32 v14, v14
	v_rcp_f32_e32 v10, v10
	v_rcp_f32_e32 v15, v15
	v_rcp_f32_e32 v11, v11
	v_rcp_f32_e32 v16, v16
	v_rcp_f32_e32 v12, v12
	v_rcp_f32_e32 v17, v17
	v_rcp_f32_e32 v13, v13
	v_lshl_add_u64 v[32:33], v[32:33], 1, s[4:5]
	s_waitcnt vmcnt(3)
	v_lshlrev_b32_e32 v50, 16, v44
	v_and_b32_e32 v51, 0xffff0000, v44
	v_lshlrev_b32_e32 v52, 16, v46
	v_and_b32_e32 v53, 0xffff0000, v46
	v_lshlrev_b32_e32 v44, 16, v45
	v_and_b32_e32 v45, 0xffff0000, v45
	v_lshlrev_b32_e32 v46, 16, v47
	v_and_b32_e32 v47, 0xffff0000, v47
	v_pk_fma_f32 v[16:17], v[16:17], v[44:45], v[42:43]
	v_pk_fma_f32 v[14:15], v[14:15], v[50:51], v[40:41]
	v_pk_fma_f32 v[10:11], v[10:11], v[52:53], v[36:37]
	v_pk_fma_f32 v[12:13], v[12:13], v[46:47], v[38:39]
	global_store_dwordx4 v[48:49], v[14:17], off sc0 sc1
	global_store_dwordx4 v[48:49], v[10:13], off offset:16 sc0 sc1
	s_cbranch_vccz .LBB0_1902
	v_cvt_pk_bf16_f32 v36, v14, v15
	v_cvt_pk_bf16_f32 v37, v16, v17
	v_cvt_pk_bf16_f32 v38, v10, v11
	v_cvt_pk_bf16_f32 v39, v12, v13
	global_store_dwordx4 v[32:33], v[36:39], off sc0 sc1
.LBB0_1902:
	v_mul_f32_e32 v6, v6, v34
	v_mul_f32_e32 v2, v2, v34
	v_mul_f32_e32 v6, 0xbfb8aa3b, v6
	v_mul_f32_e32 v2, 0xbfb8aa3b, v2
	v_exp_f32_e32 v6, v6
	v_exp_f32_e32 v35, v2
	v_mul_f32_e32 v7, v7, v34
	v_mul_f32_e32 v3, v3, v34
	v_mul_f32_e32 v7, 0xbfb8aa3b, v7
	v_mul_f32_e32 v3, 0xbfb8aa3b, v3
	v_add_f32_e32 v2, 1.0, v6
	v_add_f32_e32 v6, 1.0, v35
	v_exp_f32_e32 v7, v7
	v_exp_f32_e32 v35, v3
	v_mul_f32_e32 v8, v8, v34
	v_mul_f32_e32 v4, v4, v34
	v_mul_f32_e32 v9, v9, v34
	v_mul_f32_e32 v5, v5, v34
	v_mul_f32_e32 v8, 0xbfb8aa3b, v8
	v_mul_f32_e32 v4, 0xbfb8aa3b, v4
	v_mul_f32_e32 v9, 0xbfb8aa3b, v9
	v_mul_f32_e32 v5, 0xbfb8aa3b, v5
	v_add_f32_e32 v3, 1.0, v7
	v_add_f32_e32 v7, 1.0, v35
	v_exp_f32_e32 v8, v8
	v_exp_f32_e32 v35, v4
	v_exp_f32_e32 v9, v9
	v_exp_f32_e32 v34, v5
	v_add_f32_e32 v4, 1.0, v8
	v_add_f32_e32 v8, 1.0, v35
	v_add_f32_e32 v5, 1.0, v9
	v_add_f32_e32 v9, 1.0, v34
	v_rcp_f32_e32 v2, v2
	v_rcp_f32_e32 v6, v6
	v_rcp_f32_e32 v3, v3
	v_rcp_f32_e32 v7, v7
	v_rcp_f32_e32 v4, v4
	v_rcp_f32_e32 v5, v5
	v_rcp_f32_e32 v8, v8
	v_rcp_f32_e32 v9, v9
	s_waitcnt vmcnt(2)
	v_lshlrev_b32_e32 v36, 16, v26
	v_and_b32_e32 v37, 0xffff0000, v26
	v_lshlrev_b32_e32 v26, 16, v27
	v_and_b32_e32 v27, 0xffff0000, v27
	v_lshlrev_b32_e32 v38, 16, v28
	v_and_b32_e32 v39, 0xffff0000, v28
	v_lshlrev_b32_e32 v28, 16, v29
	v_and_b32_e32 v29, 0xffff0000, v29
	v_pk_fma_f32 v[4:5], v[4:5], v[26:27], v[24:25]
	v_pk_fma_f32 v[2:3], v[2:3], v[36:37], v[22:23]
	v_pk_fma_f32 v[6:7], v[6:7], v[38:39], v[18:19]
	v_pk_fma_f32 v[8:9], v[8:9], v[28:29], v[20:21]
	s_and_b64 vcc, exec, s[44:45]
	global_store_dwordx4 v[30:31], v[2:5], off sc0 sc1
	global_store_dwordx4 v[30:31], v[6:9], off offset:16 sc0 sc1
	s_cbranch_vccz .LBB0_1904
	v_cvt_pk_bf16_f32 v18, v2, v3
	v_cvt_pk_bf16_f32 v19, v4, v5
	v_cvt_pk_bf16_f32 v20, v6, v7
	v_cvt_pk_bf16_f32 v21, v8, v9
	global_store_dwordx4 v[32:33], v[18:21], off offset:256 sc0 sc1
